# early1 plus: drop the redundant lgkmcnt(0) between the burst-start barrier and the first MFMA
# speedup vs baseline: 1.0478x; 1.0478x over previous
; #define PG8_STAGE(bufoff, gbase, voff) do { _Pragma("unroll") for (int _i = 0; _i < 2; ++_i) \
;         __builtin_amdgcn_global_load_lds((const unsigned*)((const char*)(gbase) + (voff)[_i]), (PG8_LAS unsigned*)(lds + (bufoff) + ldsw + _i * 8192), 16, 0, 0); } while (0)
; #define PG8_LDA(dst, b, h) do { _Pragma("unroll") for (int m = 0; m < 4; ++m) _Pragma("unroll") for (int k = 0; k < 2; ++k) dst[m][k] = *(const PG8_LAS bf16x8*)(lds + PG8_SA(b, h) + aoff + m * 2048 + k * 1024); } while (0)
; #define PG8_LDB(dst, b, h) do { _Pragma("unroll") for (int n = 0; n < 2; ++n) _Pragma("unroll") for (int k = 0; k < 2; ++k) dst[n][k] = *(const PG8_LAS bf16x8*)(lds + PG8_SB(b, h) + boff + n * 2048 + k * 1024); } while (0)
; #define PG8_MMA(ai, bj, At, Bt) do { __builtin_amdgcn_s_setprio(1); _Pragma("unroll") for (int m = 0; m < 4; ++m) _Pragma("unroll") for (int n = 0; n < 2; ++n) _Pragma("unroll") for (int k = 0; k < 2; ++k) \
;         acc[ai][bj][m][n] = __builtin_amdgcn_mfma_f32_16x16x32_bf16(Bt[n][k], At[m][k], acc[ai][bj][m][n], 0, 0, 0); __builtin_amdgcn_s_setprio(0); } while (0)
; #define PG8_WAIT_V(n) asm volatile("s_waitcnt vmcnt(" #n ")" ::: "memory")
; #define PG8_WAIT_L(n) asm volatile("s_waitcnt lgkmcnt(" #n ")" ::: "memory")
; #define PG8_BAR __builtin_amdgcn_s_barrier()
; #define PG8_SCHED __builtin_amdgcn_sched_barrier(0)
; template <class Epi, class Sched, bool ALIGN_EPI = false, bool SP2 = false>
; __device__ __forceinline__ void gemm_phase(PG8_LAS unsigned char* lds, const Gemm g, const Sched& S, const Epi& E) {
;     ...
;             const char* a1 = cA + (size_t)(t + 1) * kstep;
;             const char* a2 = last ? nA : cA + (size_t)(t + 2) * kstep; const char* b2 = last ? nB : cB + (size_t)(t + 2) * kstep;
;             const char* a3 = a2 + kstep; const char* b3 = b2 + kstep;
;             if constexpr (SP2) {
;             PG8_LDB(B0, 0, 0); PG8_LDB(B1, 0, 1); PG8_SCHED; PG8_LDA(At, 0, 0); PG8_STAGE(PG8_SA(1, 1), a1 + hstep, voffA);
;             PG8_WAIT_V(8); PG8_WAIT_L(0); PG8_BAR; PG8_MMA(0, 0, At, B0); PG8_MMA(0, 1, At, B1); PG8_BAR; PG8_SCHED;
;             PG8_LDA(At, 0, 1); PG8_STAGE(PG8_SB(0, 0), b2, voffB); PG8_STAGE(PG8_SB(0, 1), b2 + hstep, voffB); PG8_STAGE(PG8_SA(0, 0), a2, voffA);
;             PG8_WAIT_V(8); PG8_WAIT_L(0); PG8_BAR; PG8_MMA(1, 0, At, B0); PG8_MMA(1, 1, At, B1); PG8_BAR; PG8_SCHED;
.LBB0_200:
	ds_read_b128 v[148:151], v164
	ds_read_b128 v[152:155], v164 offset:1024
	ds_read_b128 v[156:159], v164 offset:2048
	ds_read_b128 v[168:171], v164 offset:3072
	ds_read_b128 v[172:175], v165
	ds_read_b128 v[176:179], v165 offset:1024
	ds_read_b128 v[180:183], v165 offset:2048
	ds_read_b128 v[184:187], v165 offset:3072
	s_add_u32 s52, s70, 0xfff80080
	s_addc_u32 s53, s71, -1
	s_cmp_eq_u32 s93, 28
	s_cselect_b32 s75, s39, s53
	s_cselect_b32 s74, s69, s52
	s_cselect_b32 s73, s35, s92
	s_cselect_b32 s72, s90, s91
	v_lshl_add_u64 v[220:221], s[70:71], 0, v[138:139]
	s_add_i32 m0, s33, 0xc000
	ds_read_b128 v[188:191], v166
	ds_read_b128 v[192:195], v166 offset:1024
	ds_read_b128 v[196:199], v166 offset:2048
	ds_read_b128 v[200:203], v166 offset:3072
	ds_read_b128 v[204:207], v166 offset:4096
	ds_read_b128 v[208:211], v166 offset:5120
	ds_read_b128 v[212:215], v166 offset:6144
	ds_read_b128 v[216:219], v166 offset:7168
	global_load_lds_dwordx4 v[220:221], off
	v_lshl_add_u64 v[220:221], s[70:71], 0, v[140:141]
	s_add_i32 m0, s33, 0xe000
	s_nop 0
	global_load_lds_dwordx4 v[220:221], off
	s_waitcnt vmcnt(8)
	s_waitcnt lgkmcnt(0)
	s_barrier
	s_setprio 1
	v_mfma_f32_16x16x32_bf16 v[124:127], v[148:151], v[188:191], v[124:127]
	v_mfma_f32_16x16x32_bf16 v[120:123], v[156:159], v[188:191], v[120:123]
	v_mfma_f32_16x16x32_bf16 v[116:119], v[148:151], v[196:199], v[116:119]
	v_mfma_f32_16x16x32_bf16 v[108:111], v[156:159], v[196:199], v[108:111]
	v_mfma_f32_16x16x32_bf16 v[100:103], v[148:151], v[204:207], v[100:103]
	v_mfma_f32_16x16x32_bf16 v[92:95], v[156:159], v[204:207], v[92:95]
	v_mfma_f32_16x16x32_bf16 v[84:87], v[148:151], v[212:215], v[84:87]
	v_mfma_f32_16x16x32_bf16 v[76:79], v[156:159], v[212:215], v[76:79]
	v_mfma_f32_16x16x32_bf16 v[124:127], v[152:155], v[192:195], v[124:127]
	v_mfma_f32_16x16x32_bf16 v[120:123], v[168:171], v[192:195], v[120:123]
	v_mfma_f32_16x16x32_bf16 v[116:119], v[152:155], v[200:203], v[116:119]
	v_mfma_f32_16x16x32_bf16 v[108:111], v[168:171], v[200:203], v[108:111]
	v_mfma_f32_16x16x32_bf16 v[100:103], v[152:155], v[208:211], v[100:103]
	v_mfma_f32_16x16x32_bf16 v[92:95], v[168:171], v[208:211], v[92:95]
	v_mfma_f32_16x16x32_bf16 v[84:87], v[152:155], v[216:219], v[84:87]
	v_mfma_f32_16x16x32_bf16 v[76:79], v[168:171], v[216:219], v[76:79]
	s_setprio 0
	s_setprio 1
	v_mfma_f32_16x16x32_bf16 v[112:115], v[172:175], v[188:191], v[112:115]
	v_mfma_f32_16x16x32_bf16 v[104:107], v[180:183], v[188:191], v[104:107]
	v_mfma_f32_16x16x32_bf16 v[96:99], v[172:175], v[196:199], v[96:99]
	v_mfma_f32_16x16x32_bf16 v[88:91], v[180:183], v[196:199], v[88:91]
	v_mfma_f32_16x16x32_bf16 v[80:83], v[172:175], v[204:207], v[80:83]
	v_mfma_f32_16x16x32_bf16 v[72:75], v[180:183], v[204:207], v[72:75]
	v_mfma_f32_16x16x32_bf16 v[68:71], v[172:175], v[212:215], v[68:71]
	v_mfma_f32_16x16x32_bf16 v[64:67], v[180:183], v[212:215], v[64:67]
	v_mfma_f32_16x16x32_bf16 v[112:115], v[176:179], v[192:195], v[112:115]
	v_mfma_f32_16x16x32_bf16 v[104:107], v[184:187], v[192:195], v[104:107]
	v_mfma_f32_16x16x32_bf16 v[96:99], v[176:179], v[200:203], v[96:99]
	v_mfma_f32_16x16x32_bf16 v[88:91], v[184:187], v[200:203], v[88:91]
	v_mfma_f32_16x16x32_bf16 v[80:83], v[176:179], v[208:211], v[80:83]
	v_mfma_f32_16x16x32_bf16 v[72:75], v[184:187], v[208:211], v[72:75]
	v_mfma_f32_16x16x32_bf16 v[68:71], v[176:179], v[216:219], v[68:71]
	s_barrier
	v_mfma_f32_16x16x32_bf16 v[64:67], v[184:187], v[216:219], v[64:67]
	s_setprio 0
	s_add_i32 s52, s84, s3
	v_lshl_add_u64 v[220:221], s[72:73], 0, v[132:133]
	s_mov_b32 m0, s52
	ds_read_b128 v[188:191], v166 offset:16384
	ds_read_b128 v[192:195], v166 offset:17408
	ds_read_b128 v[196:199], v166 offset:18432
	ds_read_b128 v[200:203], v166 offset:19456
	ds_read_b128 v[204:207], v166 offset:20480
	ds_read_b128 v[208:211], v166 offset:21504
	ds_read_b128 v[212:215], v166 offset:22528
	ds_read_b128 v[216:219], v166 offset:23552
	global_load_lds_dwordx4 v[220:221], off
	s_add_i32 m0, s52, 0x2000
	s_add_u32 s96, s72, 0x80000
	v_lshl_add_u64 v[222:223], s[72:73], 0, v[128:129]
	s_addc_u32 s97, s73, 0
	s_add_i32 s52, s85, s3
	global_load_lds_dwordx4 v[222:223], off
	v_lshl_add_u64 v[224:225], s[96:97], 0, v[132:133]
	s_mov_b32 m0, s52
	v_lshl_add_u64 v[226:227], s[74:75], 0, v[130:131]
	global_load_lds_dwordx4 v[224:225], off
	v_lshl_add_u64 v[224:225], s[96:97], 0, v[128:129]
	s_add_i32 m0, s52, 0x2000
	s_nop 0
	global_load_lds_dwordx4 v[224:225], off
	v_lshl_add_u64 v[224:225], s[74:75], 0, v[134:135]
	s_mov_b32 m0, s33
	s_nop 0
	global_load_lds_dwordx4 v[224:225], off
	s_mov_b32 m0, s76
	s_nop 0
	global_load_lds_dwordx4 v[226:227], off
	s_waitcnt vmcnt(8)
	s_waitcnt lgkmcnt(0)
	s_barrier
; #define PG8_STAGE(bufoff, gbase, voff) do { _Pragma("unroll") for (int _i = 0; _i < 2; ++_i) \
;         __builtin_amdgcn_global_load_lds((const unsigned*)((const char*)(gbase) + (voff)[_i]), (PG8_LAS unsigned*)(lds + (bufoff) + ldsw + _i * 8192), 16, 0, 0); } while (0)
; #define PG8_LDA(dst, b, h) do { _Pragma("unroll") for (int m = 0; m < 4; ++m) _Pragma("unroll") for (int k = 0; k < 2; ++k) dst[m][k] = *(const PG8_LAS bf16x8*)(lds + PG8_SA(b, h) + aoff + m * 2048 + k * 1024); } while (0)
; #define PG8_LDB(dst, b, h) do { _Pragma("unroll") for (int n = 0; n < 2; ++n) _Pragma("unroll") for (int k = 0; k < 2; ++k) dst[n][k] = *(const PG8_LAS bf16x8*)(lds + PG8_SB(b, h) + boff + n * 2048 + k * 1024); } while (0)
; #define PG8_MMA(ai, bj, At, Bt) do { __builtin_amdgcn_s_setprio(1); _Pragma("unroll") for (int m = 0; m < 4; ++m) _Pragma("unroll") for (int n = 0; n < 2; ++n) _Pragma("unroll") for (int k = 0; k < 2; ++k) \
;         acc[ai][bj][m][n] = __builtin_amdgcn_mfma_f32_16x16x32_bf16(Bt[n][k], At[m][k], acc[ai][bj][m][n], 0, 0, 0); __builtin_amdgcn_s_setprio(0); } while (0)
; #define PG8_WAIT_V(n) asm volatile("s_waitcnt vmcnt(" #n ")" ::: "memory")
; #define PG8_WAIT_L(n) asm volatile("s_waitcnt lgkmcnt(" #n ")" ::: "memory")
; #define PG8_BAR __builtin_amdgcn_s_barrier()
; #define PG8_SCHED __builtin_amdgcn_sched_barrier(0)
; template <class Epi, class Sched, bool ALIGN_EPI = false, bool SP2 = false>
; __device__ __forceinline__ void gemm_phase(PG8_LAS unsigned char* lds, const Gemm g, const Sched& S, const Epi& E) {
;     ...
;             PG8_WAIT_V(8); PG8_WAIT_L(0); PG8_BAR; PG8_MMA(1, 0, At, B0); PG8_MMA(1, 1, At, B1); PG8_BAR; PG8_SCHED;
;             PG8_LDB(B0, 1, 0); PG8_LDB(B1, 1, 1); PG8_SCHED; PG8_LDA(At, 1, 0); PG8_STAGE(PG8_SA(0, 1), a2 + hstep, voffA);
;             PG8_WAIT_V(8); PG8_WAIT_L(0); PG8_BAR; PG8_MMA(0, 0, At, B0); PG8_MMA(0, 1, At, B1); PG8_BAR; PG8_SCHED;
	s_setprio 1
	v_mfma_f32_16x16x32_bf16 v[60:63], v[148:151], v[188:191], v[60:63]
	v_mfma_f32_16x16x32_bf16 v[56:59], v[156:159], v[188:191], v[56:59]
	v_mfma_f32_16x16x32_bf16 v[52:55], v[148:151], v[196:199], v[52:55]
	v_mfma_f32_16x16x32_bf16 v[44:47], v[156:159], v[196:199], v[44:47]
	v_mfma_f32_16x16x32_bf16 v[36:39], v[148:151], v[204:207], v[36:39]
	v_mfma_f32_16x16x32_bf16 v[28:31], v[156:159], v[204:207], v[28:31]
	v_mfma_f32_16x16x32_bf16 v[20:23], v[148:151], v[212:215], v[20:23]
	v_mfma_f32_16x16x32_bf16 v[12:15], v[156:159], v[212:215], v[12:15]
	v_mfma_f32_16x16x32_bf16 v[60:63], v[152:155], v[192:195], v[60:63]
	v_mfma_f32_16x16x32_bf16 v[56:59], v[168:171], v[192:195], v[56:59]
	v_mfma_f32_16x16x32_bf16 v[52:55], v[152:155], v[200:203], v[52:55]
	v_mfma_f32_16x16x32_bf16 v[44:47], v[168:171], v[200:203], v[44:47]
	v_mfma_f32_16x16x32_bf16 v[36:39], v[152:155], v[208:211], v[36:39]
	v_mfma_f32_16x16x32_bf16 v[28:31], v[168:171], v[208:211], v[28:31]
	v_mfma_f32_16x16x32_bf16 v[20:23], v[152:155], v[216:219], v[20:23]
	v_mfma_f32_16x16x32_bf16 v[12:15], v[168:171], v[216:219], v[12:15]
	s_setprio 0
	s_setprio 1
	v_mfma_f32_16x16x32_bf16 v[48:51], v[172:175], v[188:191], v[48:51]
	v_mfma_f32_16x16x32_bf16 v[40:43], v[180:183], v[188:191], v[40:43]
	v_mfma_f32_16x16x32_bf16 v[32:35], v[172:175], v[196:199], v[32:35]
	v_mfma_f32_16x16x32_bf16 v[24:27], v[180:183], v[196:199], v[24:27]
	v_mfma_f32_16x16x32_bf16 v[16:19], v[172:175], v[204:207], v[16:19]
	v_mfma_f32_16x16x32_bf16 v[8:11], v[180:183], v[204:207], v[8:11]
	v_mfma_f32_16x16x32_bf16 v[4:7], v[172:175], v[212:215], v[4:7]
	v_mfma_f32_16x16x32_bf16 v[0:3], v[180:183], v[212:215], v[0:3]
	v_mfma_f32_16x16x32_bf16 v[48:51], v[176:179], v[192:195], v[48:51]
	v_mfma_f32_16x16x32_bf16 v[40:43], v[184:187], v[192:195], v[40:43]
	v_mfma_f32_16x16x32_bf16 v[32:35], v[176:179], v[200:203], v[32:35]
	v_mfma_f32_16x16x32_bf16 v[24:27], v[184:187], v[200:203], v[24:27]
	v_mfma_f32_16x16x32_bf16 v[16:19], v[176:179], v[208:211], v[16:19]
	v_mfma_f32_16x16x32_bf16 v[8:11], v[184:187], v[208:211], v[8:11]
	v_mfma_f32_16x16x32_bf16 v[4:7], v[176:179], v[216:219], v[4:7]
	s_barrier
	v_mfma_f32_16x16x32_bf16 v[0:3], v[184:187], v[216:219], v[0:3]
	s_setprio 0
	s_add_i32 s52, 0, 0x18000
	v_add_u32_e32 v136, s52, v161
	s_add_i32 s53, 0, 0x1c000
	ds_read_b128 v[148:151], v136
	ds_read_b128 v[152:155], v136 offset:1024
	ds_read_b128 v[156:159], v136 offset:2048
	ds_read_b128 v[168:171], v136 offset:3072
	v_add_u32_e32 v136, s53, v161
	ds_read_b128 v[172:175], v136
	ds_read_b128 v[176:179], v136 offset:1024
	ds_read_b128 v[180:183], v136 offset:2048
	ds_read_b128 v[184:187], v136 offset:3072
	s_add_u32 s74, s74, 0x80000
	s_addc_u32 s75, s75, 0
	s_mov_b32 m0, s77
	v_lshl_add_u64 v[228:229], s[74:75], 0, v[134:135]
	ds_read_b128 v[188:191], v166 offset:32768
	ds_read_b128 v[192:195], v166 offset:33792
	ds_read_b128 v[196:199], v166 offset:34816
	ds_read_b128 v[200:203], v166 offset:35840
	ds_read_b128 v[204:207], v166 offset:36864
	ds_read_b128 v[208:211], v166 offset:37888
	ds_read_b128 v[212:215], v166 offset:38912
	ds_read_b128 v[216:219], v166 offset:39936
	global_load_lds_dwordx4 v[228:229], off
	v_lshl_add_u64 v[228:229], s[74:75], 0, v[130:131]
	s_mov_b32 m0, s78
	s_nop 0
	global_load_lds_dwordx4 v[228:229], off
	s_waitcnt vmcnt(8)
	s_waitcnt lgkmcnt(0)
	s_barrier
	s_setprio 1
	v_mfma_f32_16x16x32_bf16 v[124:127], v[148:151], v[188:191], v[124:127]
	v_mfma_f32_16x16x32_bf16 v[120:123], v[156:159], v[188:191], v[120:123]
	v_mfma_f32_16x16x32_bf16 v[116:119], v[148:151], v[196:199], v[116:119]
	v_mfma_f32_16x16x32_bf16 v[108:111], v[156:159], v[196:199], v[108:111]
	v_mfma_f32_16x16x32_bf16 v[100:103], v[148:151], v[204:207], v[100:103]
	v_mfma_f32_16x16x32_bf16 v[92:95], v[156:159], v[204:207], v[92:95]
	v_mfma_f32_16x16x32_bf16 v[84:87], v[148:151], v[212:215], v[84:87]
	v_mfma_f32_16x16x32_bf16 v[76:79], v[156:159], v[212:215], v[76:79]
	v_mfma_f32_16x16x32_bf16 v[124:127], v[152:155], v[192:195], v[124:127]
	v_mfma_f32_16x16x32_bf16 v[120:123], v[168:171], v[192:195], v[120:123]
	v_mfma_f32_16x16x32_bf16 v[116:119], v[152:155], v[200:203], v[116:119]
	v_mfma_f32_16x16x32_bf16 v[108:111], v[168:171], v[200:203], v[108:111]
	v_mfma_f32_16x16x32_bf16 v[100:103], v[152:155], v[208:211], v[100:103]
	v_mfma_f32_16x16x32_bf16 v[92:95], v[168:171], v[208:211], v[92:95]
	v_mfma_f32_16x16x32_bf16 v[84:87], v[152:155], v[216:219], v[84:87]
	v_mfma_f32_16x16x32_bf16 v[76:79], v[168:171], v[216:219], v[76:79]
	s_setprio 0
	s_setprio 1
	v_mfma_f32_16x16x32_bf16 v[112:115], v[172:175], v[188:191], v[112:115]
	v_mfma_f32_16x16x32_bf16 v[104:107], v[180:183], v[188:191], v[104:107]
	v_mfma_f32_16x16x32_bf16 v[96:99], v[172:175], v[196:199], v[96:99]
	v_mfma_f32_16x16x32_bf16 v[88:91], v[180:183], v[196:199], v[88:91]
	v_mfma_f32_16x16x32_bf16 v[80:83], v[172:175], v[204:207], v[80:83]
	v_mfma_f32_16x16x32_bf16 v[72:75], v[180:183], v[204:207], v[72:75]
	v_mfma_f32_16x16x32_bf16 v[68:71], v[172:175], v[212:215], v[68:71]
	v_mfma_f32_16x16x32_bf16 v[64:67], v[180:183], v[212:215], v[64:67]
	v_mfma_f32_16x16x32_bf16 v[112:115], v[176:179], v[192:195], v[112:115]
	v_mfma_f32_16x16x32_bf16 v[104:107], v[184:187], v[192:195], v[104:107]
	v_mfma_f32_16x16x32_bf16 v[96:99], v[176:179], v[200:203], v[96:99]
	v_mfma_f32_16x16x32_bf16 v[88:91], v[184:187], v[200:203], v[88:91]
	v_mfma_f32_16x16x32_bf16 v[80:83], v[176:179], v[208:211], v[80:83]
	v_mfma_f32_16x16x32_bf16 v[72:75], v[184:187], v[208:211], v[72:75]
	v_mfma_f32_16x16x32_bf16 v[68:71], v[176:179], v[216:219], v[68:71]
	s_barrier
; #define PG8_STAGE(bufoff, gbase, voff) do { _Pragma("unroll") for (int _i = 0; _i < 2; ++_i) \
;         __builtin_amdgcn_global_load_lds((const unsigned*)((const char*)(gbase) + (voff)[_i]), (PG8_LAS unsigned*)(lds + (bufoff) + ldsw + _i * 8192), 16, 0, 0); } while (0)
; #define PG8_LDA(dst, b, h) do { _Pragma("unroll") for (int m = 0; m < 4; ++m) _Pragma("unroll") for (int k = 0; k < 2; ++k) dst[m][k] = *(const PG8_LAS bf16x8*)(lds + PG8_SA(b, h) + aoff + m * 2048 + k * 1024); } while (0)
; #define PG8_MMA(ai, bj, At, Bt) do { __builtin_amdgcn_s_setprio(1); _Pragma("unroll") for (int m = 0; m < 4; ++m) _Pragma("unroll") for (int n = 0; n < 2; ++n) _Pragma("unroll") for (int k = 0; k < 2; ++k) \
;         acc[ai][bj][m][n] = __builtin_amdgcn_mfma_f32_16x16x32_bf16(Bt[n][k], At[m][k], acc[ai][bj][m][n], 0, 0, 0); __builtin_amdgcn_s_setprio(0); } while (0)
; #define PG8_WAIT_V(n) asm volatile("s_waitcnt vmcnt(" #n ")" ::: "memory")
; #define PG8_WAIT_L(n) asm volatile("s_waitcnt lgkmcnt(" #n ")" ::: "memory")
; #define PG8_BAR __builtin_amdgcn_s_barrier()
; #define PG8_SCHED __builtin_amdgcn_sched_barrier(0)
; template <class Epi, class Sched, bool ALIGN_EPI = false, bool SP2 = false>
; __device__ __forceinline__ void gemm_phase(PG8_LAS unsigned char* lds, const Gemm g, const Sched& S, const Epi& E) {
;     ...
;             PG8_LDA(At, 1, 1); PG8_STAGE(PG8_SB(1, 0), b3, voffB); PG8_STAGE(PG8_SB(1, 1), b3 + hstep, voffB); PG8_STAGE(PG8_SA(1, 0), a3, voffA);
;             PG8_WAIT_V(8); PG8_WAIT_L(0); PG8_BAR; PG8_MMA(1, 0, At, B0); PG8_MMA(1, 1, At, B1); PG8_BAR; PG8_SCHED;
;     ...
;         if constexpr (ALIGN_EPI) { if (wr == 0) PG8_BAR; }
	v_mfma_f32_16x16x32_bf16 v[64:67], v[184:187], v[216:219], v[64:67]
	s_setprio 0
	s_add_i32 s52, s52, s3
	v_lshl_add_u64 v[220:221], v[220:221], 0, s[12:13]
	s_mov_b32 m0, s52
	ds_read_b128 v[188:191], v166 offset:49152
	ds_read_b128 v[192:195], v166 offset:50176
	ds_read_b128 v[196:199], v166 offset:51200
	ds_read_b128 v[200:203], v166 offset:52224
	ds_read_b128 v[204:207], v166 offset:53248
	ds_read_b128 v[208:211], v166 offset:54272
	ds_read_b128 v[212:215], v166 offset:55296
	ds_read_b128 v[216:219], v166 offset:56320
	global_load_lds_dwordx4 v[220:221], off
	s_add_i32 m0, s52, 0x2000
	s_add_u32 s72, s72, 0x80080
	v_lshl_add_u64 v[220:221], v[222:223], 0, s[12:13]
	s_addc_u32 s73, s73, 0
	s_add_i32 s52, s53, s3
	global_load_lds_dwordx4 v[220:221], off
	v_lshl_add_u64 v[220:221], s[72:73], 0, v[132:133]
	s_mov_b32 m0, s52
	s_nop 0
	global_load_lds_dwordx4 v[220:221], off
	v_lshl_add_u64 v[220:221], s[72:73], 0, v[128:129]
	s_add_i32 m0, s52, 0x2000
	s_nop 0
	global_load_lds_dwordx4 v[220:221], off
	v_lshl_add_u64 v[220:221], v[224:225], 0, s[12:13]
	s_mov_b32 m0, s80
	s_nop 0
	global_load_lds_dwordx4 v[220:221], off
	v_lshl_add_u64 v[220:221], v[226:227], 0, s[12:13]
	s_mov_b32 m0, s81
	s_nop 0
	global_load_lds_dwordx4 v[220:221], off
	s_waitcnt vmcnt(8)
	s_waitcnt lgkmcnt(0)
	s_barrier
	s_setprio 1
	v_mfma_f32_16x16x32_bf16 v[60:63], v[148:151], v[188:191], v[60:63]
	v_mfma_f32_16x16x32_bf16 v[56:59], v[156:159], v[188:191], v[56:59]
	v_mfma_f32_16x16x32_bf16 v[52:55], v[148:151], v[196:199], v[52:55]
	v_mfma_f32_16x16x32_bf16 v[44:47], v[156:159], v[196:199], v[44:47]
	v_mfma_f32_16x16x32_bf16 v[36:39], v[148:151], v[204:207], v[36:39]
	v_mfma_f32_16x16x32_bf16 v[28:31], v[156:159], v[204:207], v[28:31]
	v_mfma_f32_16x16x32_bf16 v[20:23], v[148:151], v[212:215], v[20:23]
	v_mfma_f32_16x16x32_bf16 v[12:15], v[156:159], v[212:215], v[12:15]
	v_mfma_f32_16x16x32_bf16 v[60:63], v[152:155], v[192:195], v[60:63]
	v_mfma_f32_16x16x32_bf16 v[56:59], v[168:171], v[192:195], v[56:59]
	v_mfma_f32_16x16x32_bf16 v[52:55], v[152:155], v[200:203], v[52:55]
	v_mfma_f32_16x16x32_bf16 v[44:47], v[168:171], v[200:203], v[44:47]
	v_mfma_f32_16x16x32_bf16 v[36:39], v[152:155], v[208:211], v[36:39]
	v_mfma_f32_16x16x32_bf16 v[28:31], v[168:171], v[208:211], v[28:31]
	v_mfma_f32_16x16x32_bf16 v[20:23], v[152:155], v[216:219], v[20:23]
	v_mfma_f32_16x16x32_bf16 v[12:15], v[168:171], v[216:219], v[12:15]
	s_setprio 0
	s_setprio 1
	v_mfma_f32_16x16x32_bf16 v[48:51], v[172:175], v[188:191], v[48:51]
	v_mfma_f32_16x16x32_bf16 v[40:43], v[180:183], v[188:191], v[40:43]
	v_mfma_f32_16x16x32_bf16 v[32:35], v[172:175], v[196:199], v[32:35]
	v_mfma_f32_16x16x32_bf16 v[24:27], v[180:183], v[196:199], v[24:27]
	v_mfma_f32_16x16x32_bf16 v[16:19], v[172:175], v[204:207], v[16:19]
	v_mfma_f32_16x16x32_bf16 v[8:11], v[180:183], v[204:207], v[8:11]
	v_mfma_f32_16x16x32_bf16 v[4:7], v[172:175], v[212:215], v[4:7]
	v_mfma_f32_16x16x32_bf16 v[0:3], v[180:183], v[212:215], v[0:3]
	v_mfma_f32_16x16x32_bf16 v[48:51], v[176:179], v[192:195], v[48:51]
	v_mfma_f32_16x16x32_bf16 v[40:43], v[184:187], v[192:195], v[40:43]
	v_mfma_f32_16x16x32_bf16 v[32:35], v[176:179], v[200:203], v[32:35]
	v_mfma_f32_16x16x32_bf16 v[24:27], v[184:187], v[200:203], v[24:27]
	v_mfma_f32_16x16x32_bf16 v[16:19], v[176:179], v[208:211], v[16:19]
	v_mfma_f32_16x16x32_bf16 v[8:11], v[184:187], v[208:211], v[8:11]
	v_mfma_f32_16x16x32_bf16 v[4:7], v[176:179], v[216:219], v[4:7]
	s_barrier
	v_mfma_f32_16x16x32_bf16 v[0:3], v[184:187], v[216:219], v[0:3]
	s_setprio 0
	s_add_i32 s93, s93, 2
	s_add_u32 s70, s70, 0x100
	s_addc_u32 s71, s71, 0
	s_add_u32 s91, s91, 0x100
	s_addc_u32 s92, s92, 0
	s_cmp_gt_u32 s93, 29
	s_cbranch_scc0 .LBB0_200
	s_and_b64 vcc, exec, s[14:15]
	s_cbranch_vccz .LBB0_203
	s_barrier

; #define PG8_STAGE(bufoff, gbase, voff) do { _Pragma("unroll") for (int _i = 0; _i < 2; ++_i) \
;         __builtin_amdgcn_global_load_lds((const unsigned*)((const char*)(gbase) + (voff)[_i]), (PG8_LAS unsigned*)(lds + (bufoff) + ldsw + _i * 8192), 16, 0, 0); } while (0)
; #define PG8_LDA(dst, b, h) do { _Pragma("unroll") for (int m = 0; m < 4; ++m) _Pragma("unroll") for (int k = 0; k < 2; ++k) dst[m][k] = *(const PG8_LAS bf16x8*)(lds + PG8_SA(b, h) + aoff + m * 2048 + k * 1024); } while (0)
; #define PG8_LDB(dst, b, h) do { _Pragma("unroll") for (int n = 0; n < 2; ++n) _Pragma("unroll") for (int k = 0; k < 2; ++k) dst[n][k] = *(const PG8_LAS bf16x8*)(lds + PG8_SB(b, h) + boff + n * 2048 + k * 1024); } while (0)
; #define PG8_MMA(ai, bj, At, Bt) do { __builtin_amdgcn_s_setprio(1); _Pragma("unroll") for (int m = 0; m < 4; ++m) _Pragma("unroll") for (int n = 0; n < 2; ++n) _Pragma("unroll") for (int k = 0; k < 2; ++k) \
;         acc[ai][bj][m][n] = __builtin_amdgcn_mfma_f32_16x16x32_bf16(Bt[n][k], At[m][k], acc[ai][bj][m][n], 0, 0, 0); __builtin_amdgcn_s_setprio(0); } while (0)
; #define PG8_WAIT_V(n) asm volatile("s_waitcnt vmcnt(" #n ")" ::: "memory")
; #define PG8_WAIT_L(n) asm volatile("s_waitcnt lgkmcnt(" #n ")" ::: "memory")
; #define PG8_BAR __builtin_amdgcn_s_barrier()
; #define PG8_SCHED __builtin_amdgcn_sched_barrier(0)
; template <class Epi, class Sched, bool ALIGN_EPI = false, bool SP2 = false>
; __device__ __forceinline__ void gemm_phase(PG8_LAS unsigned char* lds, const Gemm g, const Sched& S, const Epi& E) {
;     ...
;             const char* a1 = cA + (size_t)(t + 1) * kstep;
;             const char* a2 = last ? nA : cA + (size_t)(t + 2) * kstep; const char* b2 = last ? nB : cB + (size_t)(t + 2) * kstep;
;             const char* a3 = a2 + kstep; const char* b3 = b2 + kstep;
;             if constexpr (SP2) {
;             PG8_LDB(B0, 0, 0); PG8_LDB(B1, 0, 1); PG8_SCHED; PG8_LDA(At, 0, 0); PG8_STAGE(PG8_SA(1, 1), a1 + hstep, voffA);
;             PG8_WAIT_V(8); PG8_WAIT_L(0); PG8_BAR; PG8_MMA(0, 0, At, B0); PG8_MMA(0, 1, At, B1); PG8_BAR; PG8_SCHED;
;             PG8_LDA(At, 0, 1); PG8_STAGE(PG8_SB(0, 0), b2, voffB); PG8_STAGE(PG8_SB(0, 1), b2 + hstep, voffB); PG8_STAGE(PG8_SA(0, 0), a2, voffA);
;             PG8_WAIT_V(8); PG8_WAIT_L(0); PG8_BAR; PG8_MMA(1, 0, At, B0); PG8_MMA(1, 1, At, B1); PG8_BAR; PG8_SCHED;
.LBB0_374:
	ds_read_b128 v[128:131], v230
	ds_read_b128 v[132:135], v230 offset:1024
	ds_read_b128 v[158:161], v230 offset:2048
	ds_read_b128 v[162:165], v230 offset:3072
	ds_read_b128 v[166:169], v231
	ds_read_b128 v[170:173], v231 offset:1024
	ds_read_b128 v[174:177], v231 offset:2048
	ds_read_b128 v[178:181], v231 offset:3072
	s_add_u32 s52, s76, 0xfff80080
	s_addc_u32 s53, s77, -1
	s_cmp_eq_u32 vcc_hi, 28
	s_cselect_b32 s81, s11, s53
	s_cselect_b32 s80, s55, s52
	s_cselect_b32 s79, s51, vcc_lo
	s_cselect_b32 s78, s73, s75
	v_lshl_add_u64 v[214:215], s[76:77], 0, v[150:151]
	s_add_i32 m0, s28, 0xc000
	ds_read_b128 v[182:185], v232
	ds_read_b128 v[186:189], v232 offset:1024
	ds_read_b128 v[190:193], v232 offset:2048
	ds_read_b128 v[194:197], v232 offset:3072
	ds_read_b128 v[198:201], v232 offset:4096
	ds_read_b128 v[202:205], v232 offset:5120
	ds_read_b128 v[206:209], v232 offset:6144
	ds_read_b128 v[210:213], v232 offset:7168
	global_load_lds_dwordx4 v[214:215], off
	v_lshl_add_u64 v[214:215], s[76:77], 0, v[152:153]
	s_add_i32 m0, s28, 0xe000
	s_nop 0
	global_load_lds_dwordx4 v[214:215], off
	s_waitcnt vmcnt(8)
	s_waitcnt lgkmcnt(0)
	s_barrier
	s_setprio 1
	v_mfma_f32_16x16x32_bf16 v[124:127], v[128:131], v[182:185], v[124:127]
	v_mfma_f32_16x16x32_bf16 v[120:123], v[158:161], v[182:185], v[120:123]
	v_mfma_f32_16x16x32_bf16 v[116:119], v[128:131], v[190:193], v[116:119]
	v_mfma_f32_16x16x32_bf16 v[112:115], v[158:161], v[190:193], v[112:115]
	v_mfma_f32_16x16x32_bf16 v[108:111], v[128:131], v[198:201], v[108:111]
	v_mfma_f32_16x16x32_bf16 v[104:107], v[158:161], v[198:201], v[104:107]
	v_mfma_f32_16x16x32_bf16 v[100:103], v[128:131], v[206:209], v[100:103]
	v_mfma_f32_16x16x32_bf16 v[96:99], v[158:161], v[206:209], v[96:99]
	v_mfma_f32_16x16x32_bf16 v[124:127], v[132:135], v[186:189], v[124:127]
	v_mfma_f32_16x16x32_bf16 v[120:123], v[162:165], v[186:189], v[120:123]
	v_mfma_f32_16x16x32_bf16 v[116:119], v[132:135], v[194:197], v[116:119]
	v_mfma_f32_16x16x32_bf16 v[112:115], v[162:165], v[194:197], v[112:115]
	v_mfma_f32_16x16x32_bf16 v[108:111], v[132:135], v[202:205], v[108:111]
	v_mfma_f32_16x16x32_bf16 v[104:107], v[162:165], v[202:205], v[104:107]
	v_mfma_f32_16x16x32_bf16 v[100:103], v[132:135], v[210:213], v[100:103]
	v_mfma_f32_16x16x32_bf16 v[96:99], v[162:165], v[210:213], v[96:99]
	s_setprio 0
	s_setprio 1
	v_mfma_f32_16x16x32_bf16 v[60:63], v[166:169], v[182:185], v[60:63]
	v_mfma_f32_16x16x32_bf16 v[56:59], v[174:177], v[182:185], v[56:59]
	v_mfma_f32_16x16x32_bf16 v[52:55], v[166:169], v[190:193], v[52:55]
	v_mfma_f32_16x16x32_bf16 v[48:51], v[174:177], v[190:193], v[48:51]
	v_mfma_f32_16x16x32_bf16 v[44:47], v[166:169], v[198:201], v[44:47]
	v_mfma_f32_16x16x32_bf16 v[40:43], v[174:177], v[198:201], v[40:43]
	v_mfma_f32_16x16x32_bf16 v[36:39], v[166:169], v[206:209], v[36:39]
	v_mfma_f32_16x16x32_bf16 v[32:35], v[174:177], v[206:209], v[32:35]
	v_mfma_f32_16x16x32_bf16 v[60:63], v[170:173], v[186:189], v[60:63]
	v_mfma_f32_16x16x32_bf16 v[56:59], v[178:181], v[186:189], v[56:59]
	v_mfma_f32_16x16x32_bf16 v[52:55], v[170:173], v[194:197], v[52:55]
	v_mfma_f32_16x16x32_bf16 v[48:51], v[178:181], v[194:197], v[48:51]
	v_mfma_f32_16x16x32_bf16 v[44:47], v[170:173], v[202:205], v[44:47]
	v_mfma_f32_16x16x32_bf16 v[40:43], v[178:181], v[202:205], v[40:43]
	v_mfma_f32_16x16x32_bf16 v[36:39], v[170:173], v[210:213], v[36:39]
	s_barrier
	v_mfma_f32_16x16x32_bf16 v[32:35], v[178:181], v[210:213], v[32:35]
	s_setprio 0
	s_add_i32 s52, s93, s3
	v_lshl_add_u64 v[214:215], s[78:79], 0, v[138:139]
	s_mov_b32 m0, s52
	ds_read_b128 v[182:185], v232 offset:16384
	ds_read_b128 v[186:189], v232 offset:17408
	ds_read_b128 v[190:193], v232 offset:18432
	ds_read_b128 v[194:197], v232 offset:19456
	ds_read_b128 v[198:201], v232 offset:20480
	ds_read_b128 v[202:205], v232 offset:21504
	ds_read_b128 v[206:209], v232 offset:22528
	ds_read_b128 v[210:213], v232 offset:23552
	global_load_lds_dwordx4 v[214:215], off
	s_add_i32 m0, s52, 0x2000
	s_add_u32 s52, s78, 0x80000
	v_lshl_add_u64 v[216:217], s[78:79], 0, v[142:143]
	s_addc_u32 s53, s79, 0
	s_add_i32 s56, s10, s3
	global_load_lds_dwordx4 v[216:217], off
	v_lshl_add_u64 v[218:219], s[52:53], 0, v[138:139]
	s_mov_b32 m0, s56
	v_lshl_add_u64 v[220:221], s[80:81], 0, v[140:141]
	global_load_lds_dwordx4 v[218:219], off
	v_lshl_add_u64 v[218:219], s[52:53], 0, v[142:143]
	s_add_i32 m0, s56, 0x2000
	s_nop 0
	global_load_lds_dwordx4 v[218:219], off
	v_lshl_add_u64 v[218:219], s[80:81], 0, v[136:137]
	s_mov_b32 m0, s28
	s_nop 0
	global_load_lds_dwordx4 v[218:219], off
	s_mov_b32 m0, s29
	s_nop 0
	global_load_lds_dwordx4 v[220:221], off
	s_waitcnt vmcnt(8)
	s_waitcnt lgkmcnt(0)
	s_barrier
; #define PG8_STAGE(bufoff, gbase, voff) do { _Pragma("unroll") for (int _i = 0; _i < 2; ++_i) \
;         __builtin_amdgcn_global_load_lds((const unsigned*)((const char*)(gbase) + (voff)[_i]), (PG8_LAS unsigned*)(lds + (bufoff) + ldsw + _i * 8192), 16, 0, 0); } while (0)
; #define PG8_LDA(dst, b, h) do { _Pragma("unroll") for (int m = 0; m < 4; ++m) _Pragma("unroll") for (int k = 0; k < 2; ++k) dst[m][k] = *(const PG8_LAS bf16x8*)(lds + PG8_SA(b, h) + aoff + m * 2048 + k * 1024); } while (0)
; #define PG8_LDB(dst, b, h) do { _Pragma("unroll") for (int n = 0; n < 2; ++n) _Pragma("unroll") for (int k = 0; k < 2; ++k) dst[n][k] = *(const PG8_LAS bf16x8*)(lds + PG8_SB(b, h) + boff + n * 2048 + k * 1024); } while (0)
; #define PG8_MMA(ai, bj, At, Bt) do { __builtin_amdgcn_s_setprio(1); _Pragma("unroll") for (int m = 0; m < 4; ++m) _Pragma("unroll") for (int n = 0; n < 2; ++n) _Pragma("unroll") for (int k = 0; k < 2; ++k) \
;         acc[ai][bj][m][n] = __builtin_amdgcn_mfma_f32_16x16x32_bf16(Bt[n][k], At[m][k], acc[ai][bj][m][n], 0, 0, 0); __builtin_amdgcn_s_setprio(0); } while (0)
; #define PG8_WAIT_V(n) asm volatile("s_waitcnt vmcnt(" #n ")" ::: "memory")
; #define PG8_WAIT_L(n) asm volatile("s_waitcnt lgkmcnt(" #n ")" ::: "memory")
; #define PG8_BAR __builtin_amdgcn_s_barrier()
; #define PG8_SCHED __builtin_amdgcn_sched_barrier(0)
; template <class Epi, class Sched, bool ALIGN_EPI = false, bool SP2 = false>
; __device__ __forceinline__ void gemm_phase(PG8_LAS unsigned char* lds, const Gemm g, const Sched& S, const Epi& E) {
;     ...
;             PG8_WAIT_V(8); PG8_WAIT_L(0); PG8_BAR; PG8_MMA(1, 0, At, B0); PG8_MMA(1, 1, At, B1); PG8_BAR; PG8_SCHED;
;             PG8_LDB(B0, 1, 0); PG8_LDB(B1, 1, 1); PG8_SCHED; PG8_LDA(At, 1, 0); PG8_STAGE(PG8_SA(0, 1), a2 + hstep, voffA);
;             PG8_WAIT_V(8); PG8_WAIT_L(0); PG8_BAR; PG8_MMA(0, 0, At, B0); PG8_MMA(0, 1, At, B1); PG8_BAR; PG8_SCHED;
	s_setprio 1
	v_mfma_f32_16x16x32_bf16 v[92:95], v[128:131], v[182:185], v[92:95]
	v_mfma_f32_16x16x32_bf16 v[88:91], v[158:161], v[182:185], v[88:91]
	v_mfma_f32_16x16x32_bf16 v[84:87], v[128:131], v[190:193], v[84:87]
	v_mfma_f32_16x16x32_bf16 v[80:83], v[158:161], v[190:193], v[80:83]
	v_mfma_f32_16x16x32_bf16 v[76:79], v[128:131], v[198:201], v[76:79]
	v_mfma_f32_16x16x32_bf16 v[72:75], v[158:161], v[198:201], v[72:75]
	v_mfma_f32_16x16x32_bf16 v[68:71], v[128:131], v[206:209], v[68:71]
	v_mfma_f32_16x16x32_bf16 v[64:67], v[158:161], v[206:209], v[64:67]
	v_mfma_f32_16x16x32_bf16 v[92:95], v[132:135], v[186:189], v[92:95]
	v_mfma_f32_16x16x32_bf16 v[88:91], v[162:165], v[186:189], v[88:91]
	v_mfma_f32_16x16x32_bf16 v[84:87], v[132:135], v[194:197], v[84:87]
	v_mfma_f32_16x16x32_bf16 v[80:83], v[162:165], v[194:197], v[80:83]
	v_mfma_f32_16x16x32_bf16 v[76:79], v[132:135], v[202:205], v[76:79]
	v_mfma_f32_16x16x32_bf16 v[72:75], v[162:165], v[202:205], v[72:75]
	v_mfma_f32_16x16x32_bf16 v[68:71], v[132:135], v[210:213], v[68:71]
	v_mfma_f32_16x16x32_bf16 v[64:67], v[162:165], v[210:213], v[64:67]
	s_setprio 0
	s_setprio 1
	v_mfma_f32_16x16x32_bf16 v[28:31], v[166:169], v[182:185], v[28:31]
	v_mfma_f32_16x16x32_bf16 v[24:27], v[174:177], v[182:185], v[24:27]
	v_mfma_f32_16x16x32_bf16 v[20:23], v[166:169], v[190:193], v[20:23]
	v_mfma_f32_16x16x32_bf16 v[16:19], v[174:177], v[190:193], v[16:19]
	v_mfma_f32_16x16x32_bf16 v[12:15], v[166:169], v[198:201], v[12:15]
	v_mfma_f32_16x16x32_bf16 v[8:11], v[174:177], v[198:201], v[8:11]
	v_mfma_f32_16x16x32_bf16 v[4:7], v[166:169], v[206:209], v[4:7]
	v_mfma_f32_16x16x32_bf16 v[0:3], v[174:177], v[206:209], v[0:3]
	v_mfma_f32_16x16x32_bf16 v[28:31], v[170:173], v[186:189], v[28:31]
	v_mfma_f32_16x16x32_bf16 v[24:27], v[178:181], v[186:189], v[24:27]
	v_mfma_f32_16x16x32_bf16 v[20:23], v[170:173], v[194:197], v[20:23]
	v_mfma_f32_16x16x32_bf16 v[16:19], v[178:181], v[194:197], v[16:19]
	v_mfma_f32_16x16x32_bf16 v[12:15], v[170:173], v[202:205], v[12:15]
	v_mfma_f32_16x16x32_bf16 v[8:11], v[178:181], v[202:205], v[8:11]
	v_mfma_f32_16x16x32_bf16 v[4:7], v[170:173], v[210:213], v[4:7]
	s_barrier
	v_mfma_f32_16x16x32_bf16 v[0:3], v[178:181], v[210:213], v[0:3]
	s_setprio 0
	s_add_i32 s56, 0, 0x18000
	s_add_i32 s57, 0, 0x1c000
	v_add_u32_e32 v162, s56, v228
	v_add_u32_e32 v178, s57, v228
	ds_read_b128 v[128:131], v162
	ds_read_b128 v[132:135], v162 offset:1024
	ds_read_b128 v[158:161], v162 offset:2048
	ds_read_b128 v[162:165], v162 offset:3072
	ds_read_b128 v[166:169], v178
	ds_read_b128 v[170:173], v178 offset:1024
	ds_read_b128 v[174:177], v178 offset:2048
	ds_read_b128 v[178:181], v178 offset:3072
	s_add_u32 s52, s80, 0x80000
	s_addc_u32 s53, s81, 0
	s_mov_b32 m0, s33
	v_lshl_add_u64 v[234:235], s[52:53], 0, v[136:137]
	ds_read_b128 v[182:185], v232 offset:32768
	ds_read_b128 v[186:189], v232 offset:33792
	ds_read_b128 v[190:193], v232 offset:34816
	ds_read_b128 v[194:197], v232 offset:35840
	ds_read_b128 v[198:201], v232 offset:36864
	ds_read_b128 v[202:205], v232 offset:37888
	ds_read_b128 v[206:209], v232 offset:38912
	ds_read_b128 v[210:213], v232 offset:39936
	global_load_lds_dwordx4 v[234:235], off
	v_lshl_add_u64 v[234:235], s[52:53], 0, v[140:141]
	s_mov_b32 m0, s38
	s_nop 0
	global_load_lds_dwordx4 v[234:235], off
	s_waitcnt vmcnt(8)
	s_waitcnt lgkmcnt(0)
	s_barrier
	s_setprio 1
	v_mfma_f32_16x16x32_bf16 v[124:127], v[128:131], v[182:185], v[124:127]
	v_mfma_f32_16x16x32_bf16 v[120:123], v[158:161], v[182:185], v[120:123]
	v_mfma_f32_16x16x32_bf16 v[116:119], v[128:131], v[190:193], v[116:119]
	v_mfma_f32_16x16x32_bf16 v[112:115], v[158:161], v[190:193], v[112:115]
	v_mfma_f32_16x16x32_bf16 v[108:111], v[128:131], v[198:201], v[108:111]
	v_mfma_f32_16x16x32_bf16 v[104:107], v[158:161], v[198:201], v[104:107]
	v_mfma_f32_16x16x32_bf16 v[100:103], v[128:131], v[206:209], v[100:103]
	v_mfma_f32_16x16x32_bf16 v[96:99], v[158:161], v[206:209], v[96:99]
	v_mfma_f32_16x16x32_bf16 v[124:127], v[132:135], v[186:189], v[124:127]
	v_mfma_f32_16x16x32_bf16 v[120:123], v[162:165], v[186:189], v[120:123]
	v_mfma_f32_16x16x32_bf16 v[116:119], v[132:135], v[194:197], v[116:119]
	v_mfma_f32_16x16x32_bf16 v[112:115], v[162:165], v[194:197], v[112:115]
	v_mfma_f32_16x16x32_bf16 v[108:111], v[132:135], v[202:205], v[108:111]
	v_mfma_f32_16x16x32_bf16 v[104:107], v[162:165], v[202:205], v[104:107]
	v_mfma_f32_16x16x32_bf16 v[100:103], v[132:135], v[210:213], v[100:103]
	v_mfma_f32_16x16x32_bf16 v[96:99], v[162:165], v[210:213], v[96:99]
	s_setprio 0
	s_setprio 1
	v_mfma_f32_16x16x32_bf16 v[60:63], v[166:169], v[182:185], v[60:63]
	v_mfma_f32_16x16x32_bf16 v[56:59], v[174:177], v[182:185], v[56:59]
	v_mfma_f32_16x16x32_bf16 v[52:55], v[166:169], v[190:193], v[52:55]
	v_mfma_f32_16x16x32_bf16 v[48:51], v[174:177], v[190:193], v[48:51]
	v_mfma_f32_16x16x32_bf16 v[44:47], v[166:169], v[198:201], v[44:47]
	v_mfma_f32_16x16x32_bf16 v[40:43], v[174:177], v[198:201], v[40:43]
	v_mfma_f32_16x16x32_bf16 v[36:39], v[166:169], v[206:209], v[36:39]
	v_mfma_f32_16x16x32_bf16 v[32:35], v[174:177], v[206:209], v[32:35]
	v_mfma_f32_16x16x32_bf16 v[60:63], v[170:173], v[186:189], v[60:63]
	v_mfma_f32_16x16x32_bf16 v[56:59], v[178:181], v[186:189], v[56:59]
	v_mfma_f32_16x16x32_bf16 v[52:55], v[170:173], v[194:197], v[52:55]
	v_mfma_f32_16x16x32_bf16 v[48:51], v[178:181], v[194:197], v[48:51]
	v_mfma_f32_16x16x32_bf16 v[44:47], v[170:173], v[202:205], v[44:47]
	v_mfma_f32_16x16x32_bf16 v[40:43], v[178:181], v[202:205], v[40:43]
	v_mfma_f32_16x16x32_bf16 v[36:39], v[170:173], v[210:213], v[36:39]
	s_barrier
; #define PG8_STAGE(bufoff, gbase, voff) do { _Pragma("unroll") for (int _i = 0; _i < 2; ++_i) \
;         __builtin_amdgcn_global_load_lds((const unsigned*)((const char*)(gbase) + (voff)[_i]), (PG8_LAS unsigned*)(lds + (bufoff) + ldsw + _i * 8192), 16, 0, 0); } while (0)
; #define PG8_LDA(dst, b, h) do { _Pragma("unroll") for (int m = 0; m < 4; ++m) _Pragma("unroll") for (int k = 0; k < 2; ++k) dst[m][k] = *(const PG8_LAS bf16x8*)(lds + PG8_SA(b, h) + aoff + m * 2048 + k * 1024); } while (0)
; #define PG8_MMA(ai, bj, At, Bt) do { __builtin_amdgcn_s_setprio(1); _Pragma("unroll") for (int m = 0; m < 4; ++m) _Pragma("unroll") for (int n = 0; n < 2; ++n) _Pragma("unroll") for (int k = 0; k < 2; ++k) \
;         acc[ai][bj][m][n] = __builtin_amdgcn_mfma_f32_16x16x32_bf16(Bt[n][k], At[m][k], acc[ai][bj][m][n], 0, 0, 0); __builtin_amdgcn_s_setprio(0); } while (0)
; #define PG8_WAIT_V(n) asm volatile("s_waitcnt vmcnt(" #n ")" ::: "memory")
; #define PG8_WAIT_L(n) asm volatile("s_waitcnt lgkmcnt(" #n ")" ::: "memory")
; #define PG8_BAR __builtin_amdgcn_s_barrier()
; #define PG8_SCHED __builtin_amdgcn_sched_barrier(0)
; template <class Epi, class Sched, bool ALIGN_EPI = false, bool SP2 = false>
; __device__ __forceinline__ void gemm_phase(PG8_LAS unsigned char* lds, const Gemm g, const Sched& S, const Epi& E) {
;     ...
;             PG8_LDA(At, 1, 1); PG8_STAGE(PG8_SB(1, 0), b3, voffB); PG8_STAGE(PG8_SB(1, 1), b3 + hstep, voffB); PG8_STAGE(PG8_SA(1, 0), a3, voffA);
;             PG8_WAIT_V(8); PG8_WAIT_L(0); PG8_BAR; PG8_MMA(1, 0, At, B0); PG8_MMA(1, 1, At, B1); PG8_BAR; PG8_SCHED;
;     ...
;         if constexpr (ALIGN_EPI) { if (wr == 0) PG8_BAR; }
	v_mfma_f32_16x16x32_bf16 v[32:35], v[178:181], v[210:213], v[32:35]
	s_setprio 0
	s_add_i32 s52, s56, s3
	v_lshl_add_u64 v[214:215], v[214:215], 0, s[14:15]
	s_mov_b32 m0, s52
	ds_read_b128 v[182:185], v232 offset:49152
	ds_read_b128 v[186:189], v232 offset:50176
	ds_read_b128 v[190:193], v232 offset:51200
	ds_read_b128 v[194:197], v232 offset:52224
	ds_read_b128 v[198:201], v232 offset:53248
	ds_read_b128 v[202:205], v232 offset:54272
	ds_read_b128 v[206:209], v232 offset:55296
	ds_read_b128 v[210:213], v232 offset:56320
	global_load_lds_dwordx4 v[214:215], off
	s_add_i32 m0, s52, 0x2000
	s_add_u32 s52, s78, 0x80080
	v_lshl_add_u64 v[214:215], v[216:217], 0, s[14:15]
	s_addc_u32 s53, s79, 0
	s_add_i32 s56, s57, s3
	global_load_lds_dwordx4 v[214:215], off
	v_lshl_add_u64 v[214:215], s[52:53], 0, v[138:139]
	s_mov_b32 m0, s56
	s_nop 0
	global_load_lds_dwordx4 v[214:215], off
	v_lshl_add_u64 v[214:215], s[52:53], 0, v[142:143]
	s_add_i32 m0, s56, 0x2000
	s_nop 0
	global_load_lds_dwordx4 v[214:215], off
	v_lshl_add_u64 v[214:215], v[218:219], 0, s[14:15]
	s_mov_b32 m0, s88
	s_nop 0
	global_load_lds_dwordx4 v[214:215], off
	v_lshl_add_u64 v[214:215], v[220:221], 0, s[14:15]
	s_mov_b32 m0, s89
	s_nop 0
	global_load_lds_dwordx4 v[214:215], off
	s_waitcnt vmcnt(8)
	s_waitcnt lgkmcnt(0)
	s_barrier
	s_setprio 1
	v_mfma_f32_16x16x32_bf16 v[92:95], v[128:131], v[182:185], v[92:95]
	v_mfma_f32_16x16x32_bf16 v[88:91], v[158:161], v[182:185], v[88:91]
	v_mfma_f32_16x16x32_bf16 v[84:87], v[128:131], v[190:193], v[84:87]
	v_mfma_f32_16x16x32_bf16 v[80:83], v[158:161], v[190:193], v[80:83]
	v_mfma_f32_16x16x32_bf16 v[76:79], v[128:131], v[198:201], v[76:79]
	v_mfma_f32_16x16x32_bf16 v[72:75], v[158:161], v[198:201], v[72:75]
	v_mfma_f32_16x16x32_bf16 v[68:71], v[128:131], v[206:209], v[68:71]
	v_mfma_f32_16x16x32_bf16 v[64:67], v[158:161], v[206:209], v[64:67]
	v_mfma_f32_16x16x32_bf16 v[92:95], v[132:135], v[186:189], v[92:95]
	v_mfma_f32_16x16x32_bf16 v[88:91], v[162:165], v[186:189], v[88:91]
	v_mfma_f32_16x16x32_bf16 v[84:87], v[132:135], v[194:197], v[84:87]
	v_mfma_f32_16x16x32_bf16 v[80:83], v[162:165], v[194:197], v[80:83]
	v_mfma_f32_16x16x32_bf16 v[76:79], v[132:135], v[202:205], v[76:79]
	v_mfma_f32_16x16x32_bf16 v[72:75], v[162:165], v[202:205], v[72:75]
	v_mfma_f32_16x16x32_bf16 v[68:71], v[132:135], v[210:213], v[68:71]
	v_mfma_f32_16x16x32_bf16 v[64:67], v[162:165], v[210:213], v[64:67]
	s_setprio 0
	s_setprio 1
	v_mfma_f32_16x16x32_bf16 v[28:31], v[166:169], v[182:185], v[28:31]
	v_mfma_f32_16x16x32_bf16 v[24:27], v[174:177], v[182:185], v[24:27]
	v_mfma_f32_16x16x32_bf16 v[20:23], v[166:169], v[190:193], v[20:23]
	v_mfma_f32_16x16x32_bf16 v[16:19], v[174:177], v[190:193], v[16:19]
	v_mfma_f32_16x16x32_bf16 v[12:15], v[166:169], v[198:201], v[12:15]
	v_mfma_f32_16x16x32_bf16 v[8:11], v[174:177], v[198:201], v[8:11]
	v_mfma_f32_16x16x32_bf16 v[4:7], v[166:169], v[206:209], v[4:7]
	v_mfma_f32_16x16x32_bf16 v[0:3], v[174:177], v[206:209], v[0:3]
	v_mfma_f32_16x16x32_bf16 v[28:31], v[170:173], v[186:189], v[28:31]
	v_mfma_f32_16x16x32_bf16 v[24:27], v[178:181], v[186:189], v[24:27]
	v_mfma_f32_16x16x32_bf16 v[20:23], v[170:173], v[194:197], v[20:23]
	v_mfma_f32_16x16x32_bf16 v[16:19], v[178:181], v[194:197], v[16:19]
	v_mfma_f32_16x16x32_bf16 v[12:15], v[170:173], v[202:205], v[12:15]
	v_mfma_f32_16x16x32_bf16 v[8:11], v[178:181], v[202:205], v[8:11]
	v_mfma_f32_16x16x32_bf16 v[4:7], v[170:173], v[210:213], v[4:7]
	s_barrier
	v_mfma_f32_16x16x32_bf16 v[0:3], v[178:181], v[210:213], v[0:3]
	s_setprio 0
	s_add_i32 vcc_hi, vcc_hi, 2
	s_add_u32 s76, s76, 0x100
	s_addc_u32 s77, s77, 0
	s_add_u32 s75, s75, 0x100
	s_addc_u32 vcc_lo, vcc_lo, 0
	s_cmp_gt_u32 vcc_hi, 29
	s_cbranch_scc0 .LBB0_374
	s_and_b64 vcc, exec, s[48:49]
	s_cbranch_vccz .LBB0_377
	s_barrier

; #define PG8_STAGE(bufoff, gbase, voff) do { _Pragma("unroll") for (int _i = 0; _i < 2; ++_i) \
;         __builtin_amdgcn_global_load_lds((const unsigned*)((const char*)(gbase) + (voff)[_i]), (PG8_LAS unsigned*)(lds + (bufoff) + ldsw + _i * 8192), 16, 0, 0); } while (0)
; #define PG8_LDA(dst, b, h) do { _Pragma("unroll") for (int m = 0; m < 4; ++m) _Pragma("unroll") for (int k = 0; k < 2; ++k) dst[m][k] = *(const PG8_LAS bf16x8*)(lds + PG8_SA(b, h) + aoff + m * 2048 + k * 1024); } while (0)
; #define PG8_LDB(dst, b, h) do { _Pragma("unroll") for (int n = 0; n < 2; ++n) _Pragma("unroll") for (int k = 0; k < 2; ++k) dst[n][k] = *(const PG8_LAS bf16x8*)(lds + PG8_SB(b, h) + boff + n * 2048 + k * 1024); } while (0)
; #define PG8_MMA(ai, bj, At, Bt) do { __builtin_amdgcn_s_setprio(1); _Pragma("unroll") for (int m = 0; m < 4; ++m) _Pragma("unroll") for (int n = 0; n < 2; ++n) _Pragma("unroll") for (int k = 0; k < 2; ++k) \
;         acc[ai][bj][m][n] = __builtin_amdgcn_mfma_f32_16x16x32_bf16(Bt[n][k], At[m][k], acc[ai][bj][m][n], 0, 0, 0); __builtin_amdgcn_s_setprio(0); } while (0)
; #define PG8_WAIT_V(n) asm volatile("s_waitcnt vmcnt(" #n ")" ::: "memory")
; #define PG8_WAIT_L(n) asm volatile("s_waitcnt lgkmcnt(" #n ")" ::: "memory")
; #define PG8_BAR __builtin_amdgcn_s_barrier()
; #define PG8_SCHED __builtin_amdgcn_sched_barrier(0)
; template <class Epi, class Sched, bool ALIGN_EPI = false, bool SP2 = false>
; __device__ __forceinline__ void gemm_phase(PG8_LAS unsigned char* lds, const Gemm g, const Sched& S, const Epi& E) {
;     ...
;             const char* a1 = cA + (size_t)(t + 1) * kstep;
;             const char* a2 = last ? nA : cA + (size_t)(t + 2) * kstep; const char* b2 = last ? nB : cB + (size_t)(t + 2) * kstep;
;             const char* a3 = a2 + kstep; const char* b3 = b2 + kstep;
;             if constexpr (SP2) {
;             PG8_LDB(B0, 0, 0); PG8_LDB(B1, 0, 1); PG8_SCHED; PG8_LDA(At, 0, 0); PG8_STAGE(PG8_SA(1, 1), a1 + hstep, voffA);
;             PG8_WAIT_V(8); PG8_WAIT_L(0); PG8_BAR; PG8_MMA(0, 0, At, B0); PG8_MMA(0, 1, At, B1); PG8_BAR; PG8_SCHED;
;             PG8_LDA(At, 0, 1); PG8_STAGE(PG8_SB(0, 0), b2, voffB); PG8_STAGE(PG8_SB(0, 1), b2 + hstep, voffB); PG8_STAGE(PG8_SA(0, 0), a2, voffA);
;             PG8_WAIT_V(8); PG8_WAIT_L(0); PG8_BAR; PG8_MMA(1, 0, At, B0); PG8_MMA(1, 1, At, B1); PG8_BAR; PG8_SCHED;
.LBB0_410:
	ds_read_b128 v[166:169], v145
	ds_read_b128 v[170:173], v145 offset:1024
	ds_read_b128 v[174:177], v145 offset:2048
	ds_read_b128 v[178:181], v145 offset:3072
	ds_read_b128 v[182:185], v149
	ds_read_b128 v[186:189], v149 offset:1024
	ds_read_b128 v[190:193], v149 offset:2048
	ds_read_b128 v[194:197], v149 offset:3072
	s_add_u32 s52, s74, 0xfff80080
	s_addc_u32 s53, s75, -1
	s_cmp_eq_u32 s51, 4
	s_cselect_b32 s79, s55, s53
	s_cselect_b32 s78, s54, s52
	s_cselect_b32 s77, s69, s49
	s_cselect_b32 s76, s68, s37
	s_mov_b32 m0, s80
	v_lshl_add_u64 v[230:231], s[74:75], 0, v[160:161]
	ds_read_b128 v[198:201], v164
	ds_read_b128 v[202:205], v164 offset:1024
	ds_read_b128 v[206:209], v164 offset:2048
	ds_read_b128 v[210:213], v164 offset:3072
	ds_read_b128 v[214:217], v164 offset:4096
	ds_read_b128 v[218:221], v164 offset:5120
	ds_read_b128 v[222:225], v164 offset:6144
	ds_read_b128 v[226:229], v164 offset:7168
	global_load_lds_dwordx4 v[230:231], off
	v_lshl_add_u64 v[230:231], s[74:75], 0, v[162:163]
	s_mov_b32 m0, s81
	s_nop 0
	global_load_lds_dwordx4 v[230:231], off
	s_waitcnt vmcnt(8)
	s_waitcnt lgkmcnt(0)
	s_barrier
	s_setprio 1
	v_mfma_f32_16x16x32_bf16 v[124:127], v[166:169], v[198:201], v[124:127]
	v_mfma_f32_16x16x32_bf16 v[120:123], v[174:177], v[198:201], v[120:123]
	v_mfma_f32_16x16x32_bf16 v[116:119], v[166:169], v[206:209], v[116:119]
	v_mfma_f32_16x16x32_bf16 v[108:111], v[174:177], v[206:209], v[108:111]
	v_mfma_f32_16x16x32_bf16 v[100:103], v[166:169], v[214:217], v[100:103]
	v_mfma_f32_16x16x32_bf16 v[92:95], v[174:177], v[214:217], v[92:95]
	v_mfma_f32_16x16x32_bf16 v[84:87], v[166:169], v[222:225], v[84:87]
	v_mfma_f32_16x16x32_bf16 v[76:79], v[174:177], v[222:225], v[76:79]
	v_mfma_f32_16x16x32_bf16 v[124:127], v[170:173], v[202:205], v[124:127]
	v_mfma_f32_16x16x32_bf16 v[120:123], v[178:181], v[202:205], v[120:123]
	v_mfma_f32_16x16x32_bf16 v[116:119], v[170:173], v[210:213], v[116:119]
	v_mfma_f32_16x16x32_bf16 v[108:111], v[178:181], v[210:213], v[108:111]
	v_mfma_f32_16x16x32_bf16 v[100:103], v[170:173], v[218:221], v[100:103]
	v_mfma_f32_16x16x32_bf16 v[92:95], v[178:181], v[218:221], v[92:95]
	v_mfma_f32_16x16x32_bf16 v[84:87], v[170:173], v[226:229], v[84:87]
	v_mfma_f32_16x16x32_bf16 v[76:79], v[178:181], v[226:229], v[76:79]
	s_setprio 0
	s_setprio 1
	v_mfma_f32_16x16x32_bf16 v[112:115], v[182:185], v[198:201], v[112:115]
	v_mfma_f32_16x16x32_bf16 v[104:107], v[190:193], v[198:201], v[104:107]
	v_mfma_f32_16x16x32_bf16 v[96:99], v[182:185], v[206:209], v[96:99]
	v_mfma_f32_16x16x32_bf16 v[88:91], v[190:193], v[206:209], v[88:91]
	v_mfma_f32_16x16x32_bf16 v[80:83], v[182:185], v[214:217], v[80:83]
	v_mfma_f32_16x16x32_bf16 v[72:75], v[190:193], v[214:217], v[72:75]
	v_mfma_f32_16x16x32_bf16 v[68:71], v[182:185], v[222:225], v[68:71]
	v_mfma_f32_16x16x32_bf16 v[64:67], v[190:193], v[222:225], v[64:67]
	v_mfma_f32_16x16x32_bf16 v[112:115], v[186:189], v[202:205], v[112:115]
	v_mfma_f32_16x16x32_bf16 v[104:107], v[194:197], v[202:205], v[104:107]
	v_mfma_f32_16x16x32_bf16 v[96:99], v[186:189], v[210:213], v[96:99]
	v_mfma_f32_16x16x32_bf16 v[88:91], v[194:197], v[210:213], v[88:91]
	v_mfma_f32_16x16x32_bf16 v[80:83], v[186:189], v[218:221], v[80:83]
	v_mfma_f32_16x16x32_bf16 v[72:75], v[194:197], v[218:221], v[72:75]
	v_mfma_f32_16x16x32_bf16 v[68:71], v[186:189], v[226:229], v[68:71]
	s_barrier
	v_mfma_f32_16x16x32_bf16 v[64:67], v[194:197], v[226:229], v[64:67]
	s_setprio 0
	s_mov_b32 m0, s84
	v_lshl_add_u64 v[230:231], s[76:77], 0, v[138:139]
	s_add_u32 s52, s76, 0x80000
	ds_read_b128 v[198:201], v164 offset:16384
	ds_read_b128 v[202:205], v164 offset:17408
	ds_read_b128 v[206:209], v164 offset:18432
	ds_read_b128 v[210:213], v164 offset:19456
	ds_read_b128 v[214:217], v164 offset:20480
	ds_read_b128 v[218:221], v164 offset:21504
	ds_read_b128 v[222:225], v164 offset:22528
	ds_read_b128 v[226:229], v164 offset:23552
	global_load_lds_dwordx4 v[230:231], off
	v_lshl_add_u64 v[232:233], s[76:77], 0, v[142:143]
	s_mov_b32 m0, s85
	s_addc_u32 s53, s77, 0
	global_load_lds_dwordx4 v[232:233], off
	v_lshl_add_u64 v[234:235], s[52:53], 0, v[138:139]
	s_mov_b32 m0, s86
	v_lshl_add_u64 v[236:237], s[78:79], 0, v[140:141]
	global_load_lds_dwordx4 v[234:235], off
	v_lshl_add_u64 v[234:235], s[52:53], 0, v[142:143]
	s_mov_b32 m0, s87
	s_nop 0
	global_load_lds_dwordx4 v[234:235], off
	v_lshl_add_u64 v[234:235], s[78:79], 0, v[136:137]
	s_mov_b32 m0, s10
	s_nop 0
	global_load_lds_dwordx4 v[234:235], off
	s_mov_b32 m0, s11
	s_nop 0
	global_load_lds_dwordx4 v[236:237], off
	s_waitcnt vmcnt(8)
	s_waitcnt lgkmcnt(0)
	s_barrier
; #define PG8_STAGE(bufoff, gbase, voff) do { _Pragma("unroll") for (int _i = 0; _i < 2; ++_i) \
;         __builtin_amdgcn_global_load_lds((const unsigned*)((const char*)(gbase) + (voff)[_i]), (PG8_LAS unsigned*)(lds + (bufoff) + ldsw + _i * 8192), 16, 0, 0); } while (0)
; #define PG8_LDA(dst, b, h) do { _Pragma("unroll") for (int m = 0; m < 4; ++m) _Pragma("unroll") for (int k = 0; k < 2; ++k) dst[m][k] = *(const PG8_LAS bf16x8*)(lds + PG8_SA(b, h) + aoff + m * 2048 + k * 1024); } while (0)
; #define PG8_LDB(dst, b, h) do { _Pragma("unroll") for (int n = 0; n < 2; ++n) _Pragma("unroll") for (int k = 0; k < 2; ++k) dst[n][k] = *(const PG8_LAS bf16x8*)(lds + PG8_SB(b, h) + boff + n * 2048 + k * 1024); } while (0)
; #define PG8_MMA(ai, bj, At, Bt) do { __builtin_amdgcn_s_setprio(1); _Pragma("unroll") for (int m = 0; m < 4; ++m) _Pragma("unroll") for (int n = 0; n < 2; ++n) _Pragma("unroll") for (int k = 0; k < 2; ++k) \
;         acc[ai][bj][m][n] = __builtin_amdgcn_mfma_f32_16x16x32_bf16(Bt[n][k], At[m][k], acc[ai][bj][m][n], 0, 0, 0); __builtin_amdgcn_s_setprio(0); } while (0)
; #define PG8_WAIT_V(n) asm volatile("s_waitcnt vmcnt(" #n ")" ::: "memory")
; #define PG8_WAIT_L(n) asm volatile("s_waitcnt lgkmcnt(" #n ")" ::: "memory")
; #define PG8_BAR __builtin_amdgcn_s_barrier()
; #define PG8_SCHED __builtin_amdgcn_sched_barrier(0)
; template <class Epi, class Sched, bool ALIGN_EPI = false, bool SP2 = false>
; __device__ __forceinline__ void gemm_phase(PG8_LAS unsigned char* lds, const Gemm g, const Sched& S, const Epi& E) {
;     ...
;             PG8_WAIT_V(8); PG8_WAIT_L(0); PG8_BAR; PG8_MMA(1, 0, At, B0); PG8_MMA(1, 1, At, B1); PG8_BAR; PG8_SCHED;
;             PG8_LDB(B0, 1, 0); PG8_LDB(B1, 1, 1); PG8_SCHED; PG8_LDA(At, 1, 0); PG8_STAGE(PG8_SA(0, 1), a2 + hstep, voffA);
;             PG8_WAIT_V(8); PG8_WAIT_L(0); PG8_BAR; PG8_MMA(0, 0, At, B0); PG8_MMA(0, 1, At, B1); PG8_BAR; PG8_SCHED;
	s_setprio 1
	v_mfma_f32_16x16x32_bf16 v[60:63], v[166:169], v[198:201], v[60:63]
	v_mfma_f32_16x16x32_bf16 v[56:59], v[174:177], v[198:201], v[56:59]
	v_mfma_f32_16x16x32_bf16 v[52:55], v[166:169], v[206:209], v[52:55]
	v_mfma_f32_16x16x32_bf16 v[44:47], v[174:177], v[206:209], v[44:47]
	v_mfma_f32_16x16x32_bf16 v[36:39], v[166:169], v[214:217], v[36:39]
	v_mfma_f32_16x16x32_bf16 v[28:31], v[174:177], v[214:217], v[28:31]
	v_mfma_f32_16x16x32_bf16 v[20:23], v[166:169], v[222:225], v[20:23]
	v_mfma_f32_16x16x32_bf16 v[12:15], v[174:177], v[222:225], v[12:15]
	v_mfma_f32_16x16x32_bf16 v[60:63], v[170:173], v[202:205], v[60:63]
	v_mfma_f32_16x16x32_bf16 v[56:59], v[178:181], v[202:205], v[56:59]
	v_mfma_f32_16x16x32_bf16 v[52:55], v[170:173], v[210:213], v[52:55]
	v_mfma_f32_16x16x32_bf16 v[44:47], v[178:181], v[210:213], v[44:47]
	v_mfma_f32_16x16x32_bf16 v[36:39], v[170:173], v[218:221], v[36:39]
	v_mfma_f32_16x16x32_bf16 v[28:31], v[178:181], v[218:221], v[28:31]
	v_mfma_f32_16x16x32_bf16 v[20:23], v[170:173], v[226:229], v[20:23]
	v_mfma_f32_16x16x32_bf16 v[12:15], v[178:181], v[226:229], v[12:15]
	s_setprio 0
	s_setprio 1
	v_mfma_f32_16x16x32_bf16 v[48:51], v[182:185], v[198:201], v[48:51]
	v_mfma_f32_16x16x32_bf16 v[40:43], v[190:193], v[198:201], v[40:43]
	v_mfma_f32_16x16x32_bf16 v[32:35], v[182:185], v[206:209], v[32:35]
	v_mfma_f32_16x16x32_bf16 v[24:27], v[190:193], v[206:209], v[24:27]
	v_mfma_f32_16x16x32_bf16 v[16:19], v[182:185], v[214:217], v[16:19]
	v_mfma_f32_16x16x32_bf16 v[8:11], v[190:193], v[214:217], v[8:11]
	v_mfma_f32_16x16x32_bf16 v[4:7], v[182:185], v[222:225], v[4:7]
	v_mfma_f32_16x16x32_bf16 v[0:3], v[190:193], v[222:225], v[0:3]
	v_mfma_f32_16x16x32_bf16 v[48:51], v[186:189], v[202:205], v[48:51]
	v_mfma_f32_16x16x32_bf16 v[40:43], v[194:197], v[202:205], v[40:43]
	v_mfma_f32_16x16x32_bf16 v[32:35], v[186:189], v[210:213], v[32:35]
	v_mfma_f32_16x16x32_bf16 v[24:27], v[194:197], v[210:213], v[24:27]
	v_mfma_f32_16x16x32_bf16 v[16:19], v[186:189], v[218:221], v[16:19]
	v_mfma_f32_16x16x32_bf16 v[8:11], v[194:197], v[218:221], v[8:11]
	v_mfma_f32_16x16x32_bf16 v[4:7], v[186:189], v[226:229], v[4:7]
	s_barrier
	v_mfma_f32_16x16x32_bf16 v[0:3], v[194:197], v[226:229], v[0:3]
	s_setprio 0
	ds_read_b128 v[166:169], v148
	ds_read_b128 v[170:173], v148 offset:1024
	ds_read_b128 v[174:177], v148 offset:2048
	ds_read_b128 v[178:181], v148 offset:3072
	ds_read_b128 v[182:185], v165
	ds_read_b128 v[186:189], v165 offset:1024
	ds_read_b128 v[190:193], v165 offset:2048
	ds_read_b128 v[194:197], v165 offset:3072
	s_add_u32 s52, s78, 0x80000
	s_addc_u32 s53, s79, 0
	s_mov_b32 m0, s28
	v_lshl_add_u64 v[238:239], s[52:53], 0, v[136:137]
	ds_read_b128 v[198:201], v164 offset:32768
	ds_read_b128 v[202:205], v164 offset:33792
	ds_read_b128 v[206:209], v164 offset:34816
	ds_read_b128 v[210:213], v164 offset:35840
	ds_read_b128 v[214:217], v164 offset:36864
	ds_read_b128 v[218:221], v164 offset:37888
	ds_read_b128 v[222:225], v164 offset:38912
	ds_read_b128 v[226:229], v164 offset:39936
	global_load_lds_dwordx4 v[238:239], off
	v_lshl_add_u64 v[238:239], s[52:53], 0, v[140:141]
	s_mov_b32 m0, s29
	s_nop 0
	global_load_lds_dwordx4 v[238:239], off
	s_waitcnt vmcnt(8)
	s_waitcnt lgkmcnt(0)
	s_barrier
	s_setprio 1
	v_mfma_f32_16x16x32_bf16 v[124:127], v[166:169], v[198:201], v[124:127]
	v_mfma_f32_16x16x32_bf16 v[120:123], v[174:177], v[198:201], v[120:123]
	v_mfma_f32_16x16x32_bf16 v[116:119], v[166:169], v[206:209], v[116:119]
	v_mfma_f32_16x16x32_bf16 v[108:111], v[174:177], v[206:209], v[108:111]
	v_mfma_f32_16x16x32_bf16 v[100:103], v[166:169], v[214:217], v[100:103]
	v_mfma_f32_16x16x32_bf16 v[92:95], v[174:177], v[214:217], v[92:95]
	v_mfma_f32_16x16x32_bf16 v[84:87], v[166:169], v[222:225], v[84:87]
	v_mfma_f32_16x16x32_bf16 v[76:79], v[174:177], v[222:225], v[76:79]
	v_mfma_f32_16x16x32_bf16 v[124:127], v[170:173], v[202:205], v[124:127]
	v_mfma_f32_16x16x32_bf16 v[120:123], v[178:181], v[202:205], v[120:123]
	v_mfma_f32_16x16x32_bf16 v[116:119], v[170:173], v[210:213], v[116:119]
	v_mfma_f32_16x16x32_bf16 v[108:111], v[178:181], v[210:213], v[108:111]
	v_mfma_f32_16x16x32_bf16 v[100:103], v[170:173], v[218:221], v[100:103]
	v_mfma_f32_16x16x32_bf16 v[92:95], v[178:181], v[218:221], v[92:95]
	v_mfma_f32_16x16x32_bf16 v[84:87], v[170:173], v[226:229], v[84:87]
	v_mfma_f32_16x16x32_bf16 v[76:79], v[178:181], v[226:229], v[76:79]
	s_setprio 0
	s_setprio 1
	v_mfma_f32_16x16x32_bf16 v[112:115], v[182:185], v[198:201], v[112:115]
	v_mfma_f32_16x16x32_bf16 v[104:107], v[190:193], v[198:201], v[104:107]
	v_mfma_f32_16x16x32_bf16 v[96:99], v[182:185], v[206:209], v[96:99]
	v_mfma_f32_16x16x32_bf16 v[88:91], v[190:193], v[206:209], v[88:91]
	v_mfma_f32_16x16x32_bf16 v[80:83], v[182:185], v[214:217], v[80:83]
	v_mfma_f32_16x16x32_bf16 v[72:75], v[190:193], v[214:217], v[72:75]
	v_mfma_f32_16x16x32_bf16 v[68:71], v[182:185], v[222:225], v[68:71]
	v_mfma_f32_16x16x32_bf16 v[64:67], v[190:193], v[222:225], v[64:67]
	v_mfma_f32_16x16x32_bf16 v[112:115], v[186:189], v[202:205], v[112:115]
	v_mfma_f32_16x16x32_bf16 v[104:107], v[194:197], v[202:205], v[104:107]
	v_mfma_f32_16x16x32_bf16 v[96:99], v[186:189], v[210:213], v[96:99]
	v_mfma_f32_16x16x32_bf16 v[88:91], v[194:197], v[210:213], v[88:91]
	v_mfma_f32_16x16x32_bf16 v[80:83], v[186:189], v[218:221], v[80:83]
	v_mfma_f32_16x16x32_bf16 v[72:75], v[194:197], v[218:221], v[72:75]
	v_mfma_f32_16x16x32_bf16 v[68:71], v[186:189], v[226:229], v[68:71]
	s_barrier
; #define PG8_STAGE(bufoff, gbase, voff) do { _Pragma("unroll") for (int _i = 0; _i < 2; ++_i) \
;         __builtin_amdgcn_global_load_lds((const unsigned*)((const char*)(gbase) + (voff)[_i]), (PG8_LAS unsigned*)(lds + (bufoff) + ldsw + _i * 8192), 16, 0, 0); } while (0)
; #define PG8_LDA(dst, b, h) do { _Pragma("unroll") for (int m = 0; m < 4; ++m) _Pragma("unroll") for (int k = 0; k < 2; ++k) dst[m][k] = *(const PG8_LAS bf16x8*)(lds + PG8_SA(b, h) + aoff + m * 2048 + k * 1024); } while (0)
; #define PG8_MMA(ai, bj, At, Bt) do { __builtin_amdgcn_s_setprio(1); _Pragma("unroll") for (int m = 0; m < 4; ++m) _Pragma("unroll") for (int n = 0; n < 2; ++n) _Pragma("unroll") for (int k = 0; k < 2; ++k) \
;         acc[ai][bj][m][n] = __builtin_amdgcn_mfma_f32_16x16x32_bf16(Bt[n][k], At[m][k], acc[ai][bj][m][n], 0, 0, 0); __builtin_amdgcn_s_setprio(0); } while (0)
; #define PG8_WAIT_V(n) asm volatile("s_waitcnt vmcnt(" #n ")" ::: "memory")
; #define PG8_WAIT_L(n) asm volatile("s_waitcnt lgkmcnt(" #n ")" ::: "memory")
; #define PG8_BAR __builtin_amdgcn_s_barrier()
; #define PG8_SCHED __builtin_amdgcn_sched_barrier(0)
; template <class Epi, class Sched, bool ALIGN_EPI = false, bool SP2 = false>
; __device__ __forceinline__ void gemm_phase(PG8_LAS unsigned char* lds, const Gemm g, const Sched& S, const Epi& E) {
;     ...
;             PG8_LDA(At, 1, 1); PG8_STAGE(PG8_SB(1, 0), b3, voffB); PG8_STAGE(PG8_SB(1, 1), b3 + hstep, voffB); PG8_STAGE(PG8_SA(1, 0), a3, voffA);
;             PG8_WAIT_V(8); PG8_WAIT_L(0); PG8_BAR; PG8_MMA(1, 0, At, B0); PG8_MMA(1, 1, At, B1); PG8_BAR; PG8_SCHED;
;     ...
;         if constexpr (ALIGN_EPI) { if (wr == 0) PG8_BAR; }
	v_mfma_f32_16x16x32_bf16 v[64:67], v[194:197], v[226:229], v[64:67]
	s_setprio 0
	s_mov_b32 m0, s89
	v_lshl_add_u64 v[230:231], v[230:231], 0, s[12:13]
	ds_read_b128 v[198:201], v164 offset:49152
	ds_read_b128 v[202:205], v164 offset:50176
	ds_read_b128 v[206:209], v164 offset:51200
	ds_read_b128 v[210:213], v164 offset:52224
	ds_read_b128 v[214:217], v164 offset:53248
	ds_read_b128 v[218:221], v164 offset:54272
	ds_read_b128 v[222:225], v164 offset:55296
	ds_read_b128 v[226:229], v164 offset:56320
	global_load_lds_dwordx4 v[230:231], off
	s_add_i32 m0, s89, 0x2000
	s_add_u32 s52, s76, 0x80080
	v_lshl_add_u64 v[230:231], v[232:233], 0, s[12:13]
	s_addc_u32 s53, s77, 0
	s_add_i32 s56, s88, s3
	global_load_lds_dwordx4 v[230:231], off
	v_lshl_add_u64 v[230:231], s[52:53], 0, v[138:139]
	s_mov_b32 m0, s56
	s_nop 0
	global_load_lds_dwordx4 v[230:231], off
	v_lshl_add_u64 v[230:231], s[52:53], 0, v[142:143]
	s_add_i32 m0, s56, 0x2000
	s_nop 0
	global_load_lds_dwordx4 v[230:231], off
	v_lshl_add_u64 v[230:231], v[234:235], 0, s[12:13]
	s_mov_b32 m0, s38
	s_nop 0
	global_load_lds_dwordx4 v[230:231], off
	v_lshl_add_u64 v[230:231], v[236:237], 0, s[12:13]
	s_mov_b32 m0, s39
	s_nop 0
	global_load_lds_dwordx4 v[230:231], off
	s_waitcnt vmcnt(8)
	s_waitcnt lgkmcnt(0)
	s_barrier
	s_setprio 1
	v_mfma_f32_16x16x32_bf16 v[60:63], v[166:169], v[198:201], v[60:63]
	v_mfma_f32_16x16x32_bf16 v[56:59], v[174:177], v[198:201], v[56:59]
	v_mfma_f32_16x16x32_bf16 v[52:55], v[166:169], v[206:209], v[52:55]
	v_mfma_f32_16x16x32_bf16 v[44:47], v[174:177], v[206:209], v[44:47]
	v_mfma_f32_16x16x32_bf16 v[36:39], v[166:169], v[214:217], v[36:39]
	v_mfma_f32_16x16x32_bf16 v[28:31], v[174:177], v[214:217], v[28:31]
	v_mfma_f32_16x16x32_bf16 v[20:23], v[166:169], v[222:225], v[20:23]
	v_mfma_f32_16x16x32_bf16 v[12:15], v[174:177], v[222:225], v[12:15]
	v_mfma_f32_16x16x32_bf16 v[60:63], v[170:173], v[202:205], v[60:63]
	v_mfma_f32_16x16x32_bf16 v[56:59], v[178:181], v[202:205], v[56:59]
	v_mfma_f32_16x16x32_bf16 v[52:55], v[170:173], v[210:213], v[52:55]
	v_mfma_f32_16x16x32_bf16 v[44:47], v[178:181], v[210:213], v[44:47]
	v_mfma_f32_16x16x32_bf16 v[36:39], v[170:173], v[218:221], v[36:39]
	v_mfma_f32_16x16x32_bf16 v[28:31], v[178:181], v[218:221], v[28:31]
	v_mfma_f32_16x16x32_bf16 v[20:23], v[170:173], v[226:229], v[20:23]
	v_mfma_f32_16x16x32_bf16 v[12:15], v[178:181], v[226:229], v[12:15]
	s_setprio 0
	s_setprio 1
	v_mfma_f32_16x16x32_bf16 v[48:51], v[182:185], v[198:201], v[48:51]
	v_mfma_f32_16x16x32_bf16 v[40:43], v[190:193], v[198:201], v[40:43]
	v_mfma_f32_16x16x32_bf16 v[32:35], v[182:185], v[206:209], v[32:35]
	v_mfma_f32_16x16x32_bf16 v[24:27], v[190:193], v[206:209], v[24:27]
	v_mfma_f32_16x16x32_bf16 v[16:19], v[182:185], v[214:217], v[16:19]
	v_mfma_f32_16x16x32_bf16 v[8:11], v[190:193], v[214:217], v[8:11]
	v_mfma_f32_16x16x32_bf16 v[4:7], v[182:185], v[222:225], v[4:7]
	v_mfma_f32_16x16x32_bf16 v[0:3], v[190:193], v[222:225], v[0:3]
	v_mfma_f32_16x16x32_bf16 v[48:51], v[186:189], v[202:205], v[48:51]
	v_mfma_f32_16x16x32_bf16 v[40:43], v[194:197], v[202:205], v[40:43]
	v_mfma_f32_16x16x32_bf16 v[32:35], v[186:189], v[210:213], v[32:35]
	v_mfma_f32_16x16x32_bf16 v[24:27], v[194:197], v[210:213], v[24:27]
	v_mfma_f32_16x16x32_bf16 v[16:19], v[186:189], v[218:221], v[16:19]
	v_mfma_f32_16x16x32_bf16 v[8:11], v[194:197], v[218:221], v[8:11]
	v_mfma_f32_16x16x32_bf16 v[4:7], v[186:189], v[226:229], v[4:7]
	s_barrier
	v_mfma_f32_16x16x32_bf16 v[0:3], v[194:197], v[226:229], v[0:3]
	s_setprio 0
	s_add_i32 s51, s51, 2
	s_add_u32 s74, s74, 0x100
	s_addc_u32 s75, s75, 0
	s_add_u32 s37, s37, 0x100
	s_addc_u32 s49, s49, 0
	s_cmp_gt_u32 s51, 5
	s_cbranch_scc0 .LBB0_410
	s_and_b64 vcc, exec, s[14:15]
	s_cbranch_vccz .LBB0_413
	s_barrier

; #define PG8_STAGE(bufoff, gbase, voff) do { _Pragma("unroll") for (int _i = 0; _i < 2; ++_i) \
;         __builtin_amdgcn_global_load_lds((const unsigned*)((const char*)(gbase) + (voff)[_i]), (PG8_LAS unsigned*)(lds + (bufoff) + ldsw + _i * 8192), 16, 0, 0); } while (0)
; #define PG8_LDA(dst, b, h) do { _Pragma("unroll") for (int m = 0; m < 4; ++m) _Pragma("unroll") for (int k = 0; k < 2; ++k) dst[m][k] = *(const PG8_LAS bf16x8*)(lds + PG8_SA(b, h) + aoff + m * 2048 + k * 1024); } while (0)
; #define PG8_LDB(dst, b, h) do { _Pragma("unroll") for (int n = 0; n < 2; ++n) _Pragma("unroll") for (int k = 0; k < 2; ++k) dst[n][k] = *(const PG8_LAS bf16x8*)(lds + PG8_SB(b, h) + boff + n * 2048 + k * 1024); } while (0)
; #define PG8_MMA(ai, bj, At, Bt) do { __builtin_amdgcn_s_setprio(1); _Pragma("unroll") for (int m = 0; m < 4; ++m) _Pragma("unroll") for (int n = 0; n < 2; ++n) _Pragma("unroll") for (int k = 0; k < 2; ++k) \
;         acc[ai][bj][m][n] = __builtin_amdgcn_mfma_f32_16x16x32_bf16(Bt[n][k], At[m][k], acc[ai][bj][m][n], 0, 0, 0); __builtin_amdgcn_s_setprio(0); } while (0)
; #define PG8_WAIT_V(n) asm volatile("s_waitcnt vmcnt(" #n ")" ::: "memory")
; #define PG8_WAIT_L(n) asm volatile("s_waitcnt lgkmcnt(" #n ")" ::: "memory")
; #define PG8_BAR __builtin_amdgcn_s_barrier()
; #define PG8_SCHED __builtin_amdgcn_sched_barrier(0)
; template <class Epi, class Sched, bool ALIGN_EPI = false, bool SP2 = false>
; __device__ __forceinline__ void gemm_phase(PG8_LAS unsigned char* lds, const Gemm g, const Sched& S, const Epi& E) {
;     ...
;             const char* a1 = cA + (size_t)(t + 1) * kstep;
;             const char* a2 = last ? nA : cA + (size_t)(t + 2) * kstep; const char* b2 = last ? nB : cB + (size_t)(t + 2) * kstep;
;             const char* a3 = a2 + kstep; const char* b3 = b2 + kstep;
;             if constexpr (SP2) {
;             PG8_LDB(B0, 0, 0); PG8_LDB(B1, 0, 1); PG8_SCHED; PG8_LDA(At, 0, 0); PG8_STAGE(PG8_SA(1, 1), a1 + hstep, voffA);
;             PG8_WAIT_V(8); PG8_WAIT_L(0); PG8_BAR; PG8_MMA(0, 0, At, B0); PG8_MMA(0, 1, At, B1); PG8_BAR; PG8_SCHED;
;             PG8_LDA(At, 0, 1); PG8_STAGE(PG8_SB(0, 0), b2, voffB); PG8_STAGE(PG8_SB(0, 1), b2 + hstep, voffB); PG8_STAGE(PG8_SA(0, 0), a2, voffA);
;             PG8_WAIT_V(8); PG8_WAIT_L(0); PG8_BAR; PG8_MMA(1, 0, At, B0); PG8_MMA(1, 1, At, B1); PG8_BAR; PG8_SCHED;
.LBB0_545:
	ds_read_b128 v[112:115], v174
	ds_read_b128 v[116:119], v174 offset:1024
	ds_read_b128 v[120:123], v174 offset:2048
	ds_read_b128 v[124:127], v174 offset:3072
	ds_read_b128 v[164:167], v175
	ds_read_b128 v[168:171], v175 offset:1024
	ds_read_b128 v[178:181], v175 offset:2048
	ds_read_b128 v[182:185], v175 offset:3072
	s_add_u32 s52, s68, 0xfff80080
	s_addc_u32 s53, s69, -1
	s_cmp_eq_u32 s88, 28
	s_cselect_b32 s73, s41, s53
	s_cselect_b32 s72, s84, s52
	s_cselect_b32 s71, s37, s87
	s_cselect_b32 s70, s85, s86
	v_lshl_add_u64 v[218:219], s[68:69], 0, v[156:157]
	s_add_i32 m0, s39, 0xc000
	ds_read_b128 v[186:189], v176
	ds_read_b128 v[190:193], v176 offset:1024
	ds_read_b128 v[194:197], v176 offset:2048
	ds_read_b128 v[198:201], v176 offset:3072
	ds_read_b128 v[202:205], v176 offset:4096
	ds_read_b128 v[206:209], v176 offset:5120
	ds_read_b128 v[210:213], v176 offset:6144
	ds_read_b128 v[214:217], v176 offset:7168
	global_load_lds_dwordx4 v[218:219], off
	v_lshl_add_u64 v[218:219], s[68:69], 0, v[158:159]
	s_add_i32 m0, s39, 0xe000
	s_nop 0
	global_load_lds_dwordx4 v[218:219], off
	s_waitcnt vmcnt(8)
	s_waitcnt lgkmcnt(0)
	s_barrier
	s_setprio 1
	v_mfma_f32_16x16x32_bf16 v[140:143], v[112:115], v[186:189], v[140:143]
	v_mfma_f32_16x16x32_bf16 v[136:139], v[120:123], v[186:189], v[136:139]
	v_mfma_f32_16x16x32_bf16 v[108:111], v[112:115], v[194:197], v[108:111]
	v_mfma_f32_16x16x32_bf16 v[104:107], v[120:123], v[194:197], v[104:107]
	v_mfma_f32_16x16x32_bf16 v[92:95], v[112:115], v[202:205], v[92:95]
	v_mfma_f32_16x16x32_bf16 v[88:91], v[120:123], v[202:205], v[88:91]
	v_mfma_f32_16x16x32_bf16 v[76:79], v[112:115], v[210:213], v[76:79]
	v_mfma_f32_16x16x32_bf16 v[72:75], v[120:123], v[210:213], v[72:75]
	v_mfma_f32_16x16x32_bf16 v[140:143], v[116:119], v[190:193], v[140:143]
	v_mfma_f32_16x16x32_bf16 v[136:139], v[124:127], v[190:193], v[136:139]
	v_mfma_f32_16x16x32_bf16 v[108:111], v[116:119], v[198:201], v[108:111]
	v_mfma_f32_16x16x32_bf16 v[104:107], v[124:127], v[198:201], v[104:107]
	v_mfma_f32_16x16x32_bf16 v[92:95], v[116:119], v[206:209], v[92:95]
	v_mfma_f32_16x16x32_bf16 v[88:91], v[124:127], v[206:209], v[88:91]
	v_mfma_f32_16x16x32_bf16 v[76:79], v[116:119], v[214:217], v[76:79]
	v_mfma_f32_16x16x32_bf16 v[72:75], v[124:127], v[214:217], v[72:75]
	s_setprio 0
	s_setprio 1
	v_mfma_f32_16x16x32_bf16 v[132:135], v[164:167], v[186:189], v[132:135]
	v_mfma_f32_16x16x32_bf16 v[128:131], v[178:181], v[186:189], v[128:131]
	v_mfma_f32_16x16x32_bf16 v[100:103], v[164:167], v[194:197], v[100:103]
	v_mfma_f32_16x16x32_bf16 v[96:99], v[178:181], v[194:197], v[96:99]
	v_mfma_f32_16x16x32_bf16 v[84:87], v[164:167], v[202:205], v[84:87]
	v_mfma_f32_16x16x32_bf16 v[80:83], v[178:181], v[202:205], v[80:83]
	v_mfma_f32_16x16x32_bf16 v[68:71], v[164:167], v[210:213], v[68:71]
	v_mfma_f32_16x16x32_bf16 v[64:67], v[178:181], v[210:213], v[64:67]
	v_mfma_f32_16x16x32_bf16 v[132:135], v[168:171], v[190:193], v[132:135]
	v_mfma_f32_16x16x32_bf16 v[128:131], v[182:185], v[190:193], v[128:131]
	v_mfma_f32_16x16x32_bf16 v[100:103], v[168:171], v[198:201], v[100:103]
	v_mfma_f32_16x16x32_bf16 v[96:99], v[182:185], v[198:201], v[96:99]
	v_mfma_f32_16x16x32_bf16 v[84:87], v[168:171], v[206:209], v[84:87]
	v_mfma_f32_16x16x32_bf16 v[80:83], v[182:185], v[206:209], v[80:83]
	v_mfma_f32_16x16x32_bf16 v[68:71], v[168:171], v[214:217], v[68:71]
	s_barrier
	v_mfma_f32_16x16x32_bf16 v[64:67], v[182:185], v[214:217], v[64:67]
	s_setprio 0
	s_add_i32 s52, s81, s29
	v_lshl_add_u64 v[218:219], s[70:71], 0, v[152:153]
	s_mov_b32 m0, s52
	ds_read_b128 v[186:189], v176 offset:16384
	ds_read_b128 v[190:193], v176 offset:17408
	ds_read_b128 v[194:197], v176 offset:18432
	ds_read_b128 v[198:201], v176 offset:19456
	ds_read_b128 v[202:205], v176 offset:20480
	ds_read_b128 v[206:209], v176 offset:21504
	ds_read_b128 v[210:213], v176 offset:22528
	ds_read_b128 v[214:217], v176 offset:23552
	global_load_lds_dwordx4 v[218:219], off
	s_add_i32 m0, s52, 0x2000
	s_add_u32 s52, s70, 0x80000
	v_lshl_add_u64 v[220:221], s[70:71], 0, v[148:149]
	s_addc_u32 s53, s71, 0
	s_add_i32 s56, s82, s29
	global_load_lds_dwordx4 v[220:221], off
	v_lshl_add_u64 v[222:223], s[52:53], 0, v[152:153]
	s_mov_b32 m0, s56
	v_lshl_add_u64 v[224:225], s[72:73], 0, v[150:151]
	global_load_lds_dwordx4 v[222:223], off
	v_lshl_add_u64 v[222:223], s[52:53], 0, v[148:149]
	s_add_i32 m0, s56, 0x2000
	s_nop 0
	global_load_lds_dwordx4 v[222:223], off
	v_lshl_add_u64 v[222:223], s[72:73], 0, v[154:155]
	s_mov_b32 m0, s39
	s_nop 0
	global_load_lds_dwordx4 v[222:223], off
	s_mov_b32 m0, s55
	s_nop 0
	global_load_lds_dwordx4 v[224:225], off
	s_waitcnt vmcnt(8)
	s_waitcnt lgkmcnt(0)
	s_barrier
; #define PG8_STAGE(bufoff, gbase, voff) do { _Pragma("unroll") for (int _i = 0; _i < 2; ++_i) \
;         __builtin_amdgcn_global_load_lds((const unsigned*)((const char*)(gbase) + (voff)[_i]), (PG8_LAS unsigned*)(lds + (bufoff) + ldsw + _i * 8192), 16, 0, 0); } while (0)
; #define PG8_LDA(dst, b, h) do { _Pragma("unroll") for (int m = 0; m < 4; ++m) _Pragma("unroll") for (int k = 0; k < 2; ++k) dst[m][k] = *(const PG8_LAS bf16x8*)(lds + PG8_SA(b, h) + aoff + m * 2048 + k * 1024); } while (0)
; #define PG8_LDB(dst, b, h) do { _Pragma("unroll") for (int n = 0; n < 2; ++n) _Pragma("unroll") for (int k = 0; k < 2; ++k) dst[n][k] = *(const PG8_LAS bf16x8*)(lds + PG8_SB(b, h) + boff + n * 2048 + k * 1024); } while (0)
; #define PG8_MMA(ai, bj, At, Bt) do { __builtin_amdgcn_s_setprio(1); _Pragma("unroll") for (int m = 0; m < 4; ++m) _Pragma("unroll") for (int n = 0; n < 2; ++n) _Pragma("unroll") for (int k = 0; k < 2; ++k) \
;         acc[ai][bj][m][n] = __builtin_amdgcn_mfma_f32_16x16x32_bf16(Bt[n][k], At[m][k], acc[ai][bj][m][n], 0, 0, 0); __builtin_amdgcn_s_setprio(0); } while (0)
; #define PG8_WAIT_V(n) asm volatile("s_waitcnt vmcnt(" #n ")" ::: "memory")
; #define PG8_WAIT_L(n) asm volatile("s_waitcnt lgkmcnt(" #n ")" ::: "memory")
; #define PG8_BAR __builtin_amdgcn_s_barrier()
; #define PG8_SCHED __builtin_amdgcn_sched_barrier(0)
; template <class Epi, class Sched, bool ALIGN_EPI = false, bool SP2 = false>
; __device__ __forceinline__ void gemm_phase(PG8_LAS unsigned char* lds, const Gemm g, const Sched& S, const Epi& E) {
;     ...
;             PG8_WAIT_V(8); PG8_WAIT_L(0); PG8_BAR; PG8_MMA(1, 0, At, B0); PG8_MMA(1, 1, At, B1); PG8_BAR; PG8_SCHED;
;             PG8_LDB(B0, 1, 0); PG8_LDB(B1, 1, 1); PG8_SCHED; PG8_LDA(At, 1, 0); PG8_STAGE(PG8_SA(0, 1), a2 + hstep, voffA);
;             PG8_WAIT_V(8); PG8_WAIT_L(0); PG8_BAR; PG8_MMA(0, 0, At, B0); PG8_MMA(0, 1, At, B1); PG8_BAR; PG8_SCHED;
	s_setprio 1
	v_mfma_f32_16x16x32_bf16 v[60:63], v[112:115], v[186:189], v[60:63]
	v_mfma_f32_16x16x32_bf16 v[56:59], v[120:123], v[186:189], v[56:59]
	v_mfma_f32_16x16x32_bf16 v[44:47], v[112:115], v[194:197], v[44:47]
	v_mfma_f32_16x16x32_bf16 v[40:43], v[120:123], v[194:197], v[40:43]
	v_mfma_f32_16x16x32_bf16 v[28:31], v[112:115], v[202:205], v[28:31]
	v_mfma_f32_16x16x32_bf16 v[24:27], v[120:123], v[202:205], v[24:27]
	v_mfma_f32_16x16x32_bf16 v[12:15], v[112:115], v[210:213], v[12:15]
	v_mfma_f32_16x16x32_bf16 v[8:11], v[120:123], v[210:213], v[8:11]
	v_mfma_f32_16x16x32_bf16 v[60:63], v[116:119], v[190:193], v[60:63]
	v_mfma_f32_16x16x32_bf16 v[56:59], v[124:127], v[190:193], v[56:59]
	v_mfma_f32_16x16x32_bf16 v[44:47], v[116:119], v[198:201], v[44:47]
	v_mfma_f32_16x16x32_bf16 v[40:43], v[124:127], v[198:201], v[40:43]
	v_mfma_f32_16x16x32_bf16 v[28:31], v[116:119], v[206:209], v[28:31]
	v_mfma_f32_16x16x32_bf16 v[24:27], v[124:127], v[206:209], v[24:27]
	v_mfma_f32_16x16x32_bf16 v[12:15], v[116:119], v[214:217], v[12:15]
	v_mfma_f32_16x16x32_bf16 v[8:11], v[124:127], v[214:217], v[8:11]
	s_setprio 0
	s_setprio 1
	v_mfma_f32_16x16x32_bf16 v[52:55], v[164:167], v[186:189], v[52:55]
	v_mfma_f32_16x16x32_bf16 v[48:51], v[178:181], v[186:189], v[48:51]
	v_mfma_f32_16x16x32_bf16 v[36:39], v[164:167], v[194:197], v[36:39]
	v_mfma_f32_16x16x32_bf16 v[32:35], v[178:181], v[194:197], v[32:35]
	v_mfma_f32_16x16x32_bf16 v[20:23], v[164:167], v[202:205], v[20:23]
	v_mfma_f32_16x16x32_bf16 v[16:19], v[178:181], v[202:205], v[16:19]
	v_mfma_f32_16x16x32_bf16 v[4:7], v[164:167], v[210:213], v[4:7]
	v_mfma_f32_16x16x32_bf16 v[0:3], v[178:181], v[210:213], v[0:3]
	v_mfma_f32_16x16x32_bf16 v[52:55], v[168:171], v[190:193], v[52:55]
	v_mfma_f32_16x16x32_bf16 v[48:51], v[182:185], v[190:193], v[48:51]
	v_mfma_f32_16x16x32_bf16 v[36:39], v[168:171], v[198:201], v[36:39]
	v_mfma_f32_16x16x32_bf16 v[32:35], v[182:185], v[198:201], v[32:35]
	v_mfma_f32_16x16x32_bf16 v[20:23], v[168:171], v[206:209], v[20:23]
	v_mfma_f32_16x16x32_bf16 v[16:19], v[182:185], v[206:209], v[16:19]
	v_mfma_f32_16x16x32_bf16 v[4:7], v[168:171], v[214:217], v[4:7]
	s_barrier
	v_mfma_f32_16x16x32_bf16 v[0:3], v[182:185], v[214:217], v[0:3]
	s_setprio 0
	s_add_i32 s56, 0, 0x18000
	s_add_i32 s57, 0, 0x1c000
	v_add_u32_e32 v124, s56, v172
	v_add_u32_e32 v177, s57, v172
	ds_read_b128 v[112:115], v124
	ds_read_b128 v[116:119], v124 offset:1024
	ds_read_b128 v[120:123], v124 offset:2048
	ds_read_b128 v[124:127], v124 offset:3072
	ds_read_b128 v[164:167], v177
	ds_read_b128 v[168:171], v177 offset:1024
	ds_read_b128 v[178:181], v177 offset:2048
	ds_read_b128 v[182:185], v177 offset:3072
	s_add_u32 s52, s72, 0x80000
	s_addc_u32 s53, s73, 0
	s_mov_b32 m0, s74
	v_lshl_add_u64 v[226:227], s[52:53], 0, v[154:155]
	ds_read_b128 v[186:189], v176 offset:32768
	ds_read_b128 v[190:193], v176 offset:33792
	ds_read_b128 v[194:197], v176 offset:34816
	ds_read_b128 v[198:201], v176 offset:35840
	ds_read_b128 v[202:205], v176 offset:36864
	ds_read_b128 v[206:209], v176 offset:37888
	ds_read_b128 v[210:213], v176 offset:38912
	ds_read_b128 v[214:217], v176 offset:39936
	global_load_lds_dwordx4 v[226:227], off
	v_lshl_add_u64 v[226:227], s[52:53], 0, v[150:151]
	s_mov_b32 m0, s75
	s_nop 0
	global_load_lds_dwordx4 v[226:227], off
	s_waitcnt vmcnt(8)
	s_waitcnt lgkmcnt(0)
	s_barrier
	s_setprio 1
	v_mfma_f32_16x16x32_bf16 v[140:143], v[112:115], v[186:189], v[140:143]
	v_mfma_f32_16x16x32_bf16 v[136:139], v[120:123], v[186:189], v[136:139]
	v_mfma_f32_16x16x32_bf16 v[108:111], v[112:115], v[194:197], v[108:111]
	v_mfma_f32_16x16x32_bf16 v[104:107], v[120:123], v[194:197], v[104:107]
	v_mfma_f32_16x16x32_bf16 v[92:95], v[112:115], v[202:205], v[92:95]
	v_mfma_f32_16x16x32_bf16 v[88:91], v[120:123], v[202:205], v[88:91]
	v_mfma_f32_16x16x32_bf16 v[76:79], v[112:115], v[210:213], v[76:79]
	v_mfma_f32_16x16x32_bf16 v[72:75], v[120:123], v[210:213], v[72:75]
	v_mfma_f32_16x16x32_bf16 v[140:143], v[116:119], v[190:193], v[140:143]
	v_mfma_f32_16x16x32_bf16 v[136:139], v[124:127], v[190:193], v[136:139]
	v_mfma_f32_16x16x32_bf16 v[108:111], v[116:119], v[198:201], v[108:111]
	v_mfma_f32_16x16x32_bf16 v[104:107], v[124:127], v[198:201], v[104:107]
	v_mfma_f32_16x16x32_bf16 v[92:95], v[116:119], v[206:209], v[92:95]
	v_mfma_f32_16x16x32_bf16 v[88:91], v[124:127], v[206:209], v[88:91]
	v_mfma_f32_16x16x32_bf16 v[76:79], v[116:119], v[214:217], v[76:79]
	v_mfma_f32_16x16x32_bf16 v[72:75], v[124:127], v[214:217], v[72:75]
	s_setprio 0
	s_setprio 1
	v_mfma_f32_16x16x32_bf16 v[132:135], v[164:167], v[186:189], v[132:135]
	v_mfma_f32_16x16x32_bf16 v[128:131], v[178:181], v[186:189], v[128:131]
	v_mfma_f32_16x16x32_bf16 v[100:103], v[164:167], v[194:197], v[100:103]
	v_mfma_f32_16x16x32_bf16 v[96:99], v[178:181], v[194:197], v[96:99]
	v_mfma_f32_16x16x32_bf16 v[84:87], v[164:167], v[202:205], v[84:87]
	v_mfma_f32_16x16x32_bf16 v[80:83], v[178:181], v[202:205], v[80:83]
	v_mfma_f32_16x16x32_bf16 v[68:71], v[164:167], v[210:213], v[68:71]
	v_mfma_f32_16x16x32_bf16 v[64:67], v[178:181], v[210:213], v[64:67]
	v_mfma_f32_16x16x32_bf16 v[132:135], v[168:171], v[190:193], v[132:135]
	v_mfma_f32_16x16x32_bf16 v[128:131], v[182:185], v[190:193], v[128:131]
	v_mfma_f32_16x16x32_bf16 v[100:103], v[168:171], v[198:201], v[100:103]
	v_mfma_f32_16x16x32_bf16 v[96:99], v[182:185], v[198:201], v[96:99]
	v_mfma_f32_16x16x32_bf16 v[84:87], v[168:171], v[206:209], v[84:87]
	v_mfma_f32_16x16x32_bf16 v[80:83], v[182:185], v[206:209], v[80:83]
	v_mfma_f32_16x16x32_bf16 v[68:71], v[168:171], v[214:217], v[68:71]
	s_barrier
; #define PG8_STAGE(bufoff, gbase, voff) do { _Pragma("unroll") for (int _i = 0; _i < 2; ++_i) \
;         __builtin_amdgcn_global_load_lds((const unsigned*)((const char*)(gbase) + (voff)[_i]), (PG8_LAS unsigned*)(lds + (bufoff) + ldsw + _i * 8192), 16, 0, 0); } while (0)
; #define PG8_LDA(dst, b, h) do { _Pragma("unroll") for (int m = 0; m < 4; ++m) _Pragma("unroll") for (int k = 0; k < 2; ++k) dst[m][k] = *(const PG8_LAS bf16x8*)(lds + PG8_SA(b, h) + aoff + m * 2048 + k * 1024); } while (0)
; #define PG8_MMA(ai, bj, At, Bt) do { __builtin_amdgcn_s_setprio(1); _Pragma("unroll") for (int m = 0; m < 4; ++m) _Pragma("unroll") for (int n = 0; n < 2; ++n) _Pragma("unroll") for (int k = 0; k < 2; ++k) \
;         acc[ai][bj][m][n] = __builtin_amdgcn_mfma_f32_16x16x32_bf16(Bt[n][k], At[m][k], acc[ai][bj][m][n], 0, 0, 0); __builtin_amdgcn_s_setprio(0); } while (0)
; #define PG8_WAIT_V(n) asm volatile("s_waitcnt vmcnt(" #n ")" ::: "memory")
; #define PG8_WAIT_L(n) asm volatile("s_waitcnt lgkmcnt(" #n ")" ::: "memory")
; #define PG8_BAR __builtin_amdgcn_s_barrier()
; #define PG8_SCHED __builtin_amdgcn_sched_barrier(0)
; template <class Epi, class Sched, bool ALIGN_EPI = false, bool SP2 = false>
; __device__ __forceinline__ void gemm_phase(PG8_LAS unsigned char* lds, const Gemm g, const Sched& S, const Epi& E) {
;     ...
;             PG8_LDA(At, 1, 1); PG8_STAGE(PG8_SB(1, 0), b3, voffB); PG8_STAGE(PG8_SB(1, 1), b3 + hstep, voffB); PG8_STAGE(PG8_SA(1, 0), a3, voffA);
;             PG8_WAIT_V(8); PG8_WAIT_L(0); PG8_BAR; PG8_MMA(1, 0, At, B0); PG8_MMA(1, 1, At, B1); PG8_BAR; PG8_SCHED;
;     ...
;         if constexpr (ALIGN_EPI) { if (wr == 0) PG8_BAR; }
	v_mfma_f32_16x16x32_bf16 v[64:67], v[182:185], v[214:217], v[64:67]
	s_setprio 0
	s_add_i32 s52, s56, s29
	v_lshl_add_u64 v[218:219], v[218:219], 0, s[12:13]
	s_mov_b32 m0, s52
	ds_read_b128 v[186:189], v176 offset:49152
	ds_read_b128 v[190:193], v176 offset:50176
	ds_read_b128 v[194:197], v176 offset:51200
	ds_read_b128 v[198:201], v176 offset:52224
	ds_read_b128 v[202:205], v176 offset:53248
	ds_read_b128 v[206:209], v176 offset:54272
	ds_read_b128 v[210:213], v176 offset:55296
	ds_read_b128 v[214:217], v176 offset:56320
	global_load_lds_dwordx4 v[218:219], off
	s_add_i32 m0, s52, 0x2000
	s_add_u32 s52, s70, 0x80080
	v_lshl_add_u64 v[218:219], v[220:221], 0, s[12:13]
	s_addc_u32 s53, s71, 0
	s_add_i32 s56, s57, s29
	global_load_lds_dwordx4 v[218:219], off
	v_lshl_add_u64 v[218:219], s[52:53], 0, v[152:153]
	s_mov_b32 m0, s56
	s_nop 0
	global_load_lds_dwordx4 v[218:219], off
	v_lshl_add_u64 v[218:219], s[52:53], 0, v[148:149]
	s_add_i32 m0, s56, 0x2000
	s_nop 0
	global_load_lds_dwordx4 v[218:219], off
	v_lshl_add_u64 v[218:219], v[222:223], 0, s[12:13]
	s_mov_b32 m0, s77
	s_nop 0
	global_load_lds_dwordx4 v[218:219], off
	v_lshl_add_u64 v[218:219], v[224:225], 0, s[12:13]
	s_mov_b32 m0, s78
	s_nop 0
	global_load_lds_dwordx4 v[218:219], off
	s_waitcnt vmcnt(8)
	s_waitcnt lgkmcnt(0)
	s_barrier
	s_setprio 1
	v_mfma_f32_16x16x32_bf16 v[60:63], v[112:115], v[186:189], v[60:63]
	v_mfma_f32_16x16x32_bf16 v[56:59], v[120:123], v[186:189], v[56:59]
	v_mfma_f32_16x16x32_bf16 v[44:47], v[112:115], v[194:197], v[44:47]
	v_mfma_f32_16x16x32_bf16 v[40:43], v[120:123], v[194:197], v[40:43]
	v_mfma_f32_16x16x32_bf16 v[28:31], v[112:115], v[202:205], v[28:31]
	v_mfma_f32_16x16x32_bf16 v[24:27], v[120:123], v[202:205], v[24:27]
	v_mfma_f32_16x16x32_bf16 v[12:15], v[112:115], v[210:213], v[12:15]
	v_mfma_f32_16x16x32_bf16 v[8:11], v[120:123], v[210:213], v[8:11]
	v_mfma_f32_16x16x32_bf16 v[60:63], v[116:119], v[190:193], v[60:63]
	v_mfma_f32_16x16x32_bf16 v[56:59], v[124:127], v[190:193], v[56:59]
	v_mfma_f32_16x16x32_bf16 v[44:47], v[116:119], v[198:201], v[44:47]
	v_mfma_f32_16x16x32_bf16 v[40:43], v[124:127], v[198:201], v[40:43]
	v_mfma_f32_16x16x32_bf16 v[28:31], v[116:119], v[206:209], v[28:31]
	v_mfma_f32_16x16x32_bf16 v[24:27], v[124:127], v[206:209], v[24:27]
	v_mfma_f32_16x16x32_bf16 v[12:15], v[116:119], v[214:217], v[12:15]
	v_mfma_f32_16x16x32_bf16 v[8:11], v[124:127], v[214:217], v[8:11]
	s_setprio 0
	s_setprio 1
	v_mfma_f32_16x16x32_bf16 v[52:55], v[164:167], v[186:189], v[52:55]
	v_mfma_f32_16x16x32_bf16 v[48:51], v[178:181], v[186:189], v[48:51]
	v_mfma_f32_16x16x32_bf16 v[36:39], v[164:167], v[194:197], v[36:39]
	v_mfma_f32_16x16x32_bf16 v[32:35], v[178:181], v[194:197], v[32:35]
	v_mfma_f32_16x16x32_bf16 v[20:23], v[164:167], v[202:205], v[20:23]
	v_mfma_f32_16x16x32_bf16 v[16:19], v[178:181], v[202:205], v[16:19]
	v_mfma_f32_16x16x32_bf16 v[4:7], v[164:167], v[210:213], v[4:7]
	v_mfma_f32_16x16x32_bf16 v[0:3], v[178:181], v[210:213], v[0:3]
	v_mfma_f32_16x16x32_bf16 v[52:55], v[168:171], v[190:193], v[52:55]
	v_mfma_f32_16x16x32_bf16 v[48:51], v[182:185], v[190:193], v[48:51]
	v_mfma_f32_16x16x32_bf16 v[36:39], v[168:171], v[198:201], v[36:39]
	v_mfma_f32_16x16x32_bf16 v[32:35], v[182:185], v[198:201], v[32:35]
	v_mfma_f32_16x16x32_bf16 v[20:23], v[168:171], v[206:209], v[20:23]
	v_mfma_f32_16x16x32_bf16 v[16:19], v[182:185], v[206:209], v[16:19]
	v_mfma_f32_16x16x32_bf16 v[4:7], v[168:171], v[214:217], v[4:7]
	s_barrier
	v_mfma_f32_16x16x32_bf16 v[0:3], v[182:185], v[214:217], v[0:3]
	s_setprio 0
	s_add_i32 s88, s88, 2
	s_add_u32 s68, s68, 0x100
	s_addc_u32 s69, s69, 0
	s_add_u32 s86, s86, 0x100
	s_addc_u32 s87, s87, 0
	s_cmp_gt_u32 s88, 29
	s_cbranch_scc0 .LBB0_545
	s_and_b64 vcc, exec, s[14:15]
	s_cbranch_vccz .LBB0_548
	s_barrier

; #define PG8_STAGE(bufoff, gbase, voff) do { _Pragma("unroll") for (int _i = 0; _i < 2; ++_i) \
;         __builtin_amdgcn_global_load_lds((const unsigned*)((const char*)(gbase) + (voff)[_i]), (PG8_LAS unsigned*)(lds + (bufoff) + ldsw + _i * 8192), 16, 0, 0); } while (0)
; #define PG8_LDA(dst, b, h) do { _Pragma("unroll") for (int m = 0; m < 4; ++m) _Pragma("unroll") for (int k = 0; k < 2; ++k) dst[m][k] = *(const PG8_LAS bf16x8*)(lds + PG8_SA(b, h) + aoff + m * 2048 + k * 1024); } while (0)
; #define PG8_LDB(dst, b, h) do { _Pragma("unroll") for (int n = 0; n < 2; ++n) _Pragma("unroll") for (int k = 0; k < 2; ++k) dst[n][k] = *(const PG8_LAS bf16x8*)(lds + PG8_SB(b, h) + boff + n * 2048 + k * 1024); } while (0)
; #define PG8_MMA(ai, bj, At, Bt) do { __builtin_amdgcn_s_setprio(1); _Pragma("unroll") for (int m = 0; m < 4; ++m) _Pragma("unroll") for (int n = 0; n < 2; ++n) _Pragma("unroll") for (int k = 0; k < 2; ++k) \
;         acc[ai][bj][m][n] = __builtin_amdgcn_mfma_f32_16x16x32_bf16(Bt[n][k], At[m][k], acc[ai][bj][m][n], 0, 0, 0); __builtin_amdgcn_s_setprio(0); } while (0)
; #define PG8_WAIT_V(n) asm volatile("s_waitcnt vmcnt(" #n ")" ::: "memory")
; #define PG8_WAIT_L(n) asm volatile("s_waitcnt lgkmcnt(" #n ")" ::: "memory")
; #define PG8_BAR __builtin_amdgcn_s_barrier()
; #define PG8_SCHED __builtin_amdgcn_sched_barrier(0)
; template <class Epi, class Sched, bool ALIGN_EPI = false, bool SP2 = false>
; __device__ __forceinline__ void gemm_phase(PG8_LAS unsigned char* lds, const Gemm g, const Sched& S, const Epi& E) {
;     ...
;             const char* a1 = cA + (size_t)(t + 1) * kstep;
;             const char* a2 = last ? nA : cA + (size_t)(t + 2) * kstep; const char* b2 = last ? nB : cB + (size_t)(t + 2) * kstep;
;             const char* a3 = a2 + kstep; const char* b3 = b2 + kstep;
;             if constexpr (SP2) {
;             PG8_LDB(B0, 0, 0); PG8_LDB(B1, 0, 1); PG8_SCHED; PG8_LDA(At, 0, 0); PG8_STAGE(PG8_SA(1, 1), a1 + hstep, voffA);
;             PG8_WAIT_V(8); PG8_WAIT_L(0); PG8_BAR; PG8_MMA(0, 0, At, B0); PG8_MMA(0, 1, At, B1); PG8_BAR; PG8_SCHED;
;             PG8_LDA(At, 0, 1); PG8_STAGE(PG8_SB(0, 0), b2, voffB); PG8_STAGE(PG8_SB(0, 1), b2 + hstep, voffB); PG8_STAGE(PG8_SA(0, 0), a2, voffA);
;             PG8_WAIT_V(8); PG8_WAIT_L(0); PG8_BAR; PG8_MMA(1, 0, At, B0); PG8_MMA(1, 1, At, B1); PG8_BAR; PG8_SCHED;
.LBB0_624:
	ds_read_b128 v[128:131], v214
	ds_read_b128 v[132:135], v214 offset:1024
	ds_read_b128 v[158:161], v214 offset:2048
	ds_read_b128 v[162:165], v214 offset:3072
	ds_read_b128 v[166:169], v215
	ds_read_b128 v[170:173], v215 offset:1024
	ds_read_b128 v[174:177], v215 offset:2048
	ds_read_b128 v[178:181], v215 offset:3072
	s_add_u32 s52, s74, 0xffe00080
	s_addc_u32 s53, s75, -1
	s_cmpk_eq_i32 vcc_hi, 0x7c
	s_cselect_b32 s79, s51, s53
	s_cselect_b32 s78, s71, s52
	s_cselect_b32 s77, s49, vcc_lo
	s_cselect_b32 s76, s73, s93
	v_lshl_add_u64 v[226:227], s[74:75], 0, v[150:151]
	s_add_i32 m0, s83, 0xc000
	ds_read_b128 v[182:185], v216
	ds_read_b128 v[186:189], v216 offset:1024
	ds_read_b128 v[190:193], v216 offset:2048
	ds_read_b128 v[194:197], v216 offset:3072
	ds_read_b128 v[198:201], v216 offset:4096
	ds_read_b128 v[202:205], v216 offset:5120
	ds_read_b128 v[218:221], v216 offset:6144
	ds_read_b128 v[222:225], v216 offset:7168
	global_load_lds_dwordx4 v[226:227], off
	v_lshl_add_u64 v[226:227], s[74:75], 0, v[152:153]
	s_add_i32 m0, s83, 0xe000
	s_nop 0
	global_load_lds_dwordx4 v[226:227], off
	s_waitcnt vmcnt(8)
	s_waitcnt lgkmcnt(0)
	s_barrier
	s_setprio 1
	v_mfma_f32_16x16x32_bf16 v[124:127], v[128:131], v[182:185], v[124:127]
	v_mfma_f32_16x16x32_bf16 v[120:123], v[158:161], v[182:185], v[120:123]
	v_mfma_f32_16x16x32_bf16 v[116:119], v[128:131], v[190:193], v[116:119]
	v_mfma_f32_16x16x32_bf16 v[112:115], v[158:161], v[190:193], v[112:115]
	v_mfma_f32_16x16x32_bf16 v[108:111], v[128:131], v[198:201], v[108:111]
	v_mfma_f32_16x16x32_bf16 v[104:107], v[158:161], v[198:201], v[104:107]
	v_mfma_f32_16x16x32_bf16 v[100:103], v[128:131], v[218:221], v[100:103]
	v_mfma_f32_16x16x32_bf16 v[96:99], v[158:161], v[218:221], v[96:99]
	v_mfma_f32_16x16x32_bf16 v[124:127], v[132:135], v[186:189], v[124:127]
	v_mfma_f32_16x16x32_bf16 v[120:123], v[162:165], v[186:189], v[120:123]
	v_mfma_f32_16x16x32_bf16 v[116:119], v[132:135], v[194:197], v[116:119]
	v_mfma_f32_16x16x32_bf16 v[112:115], v[162:165], v[194:197], v[112:115]
	v_mfma_f32_16x16x32_bf16 v[108:111], v[132:135], v[202:205], v[108:111]
	v_mfma_f32_16x16x32_bf16 v[104:107], v[162:165], v[202:205], v[104:107]
	v_mfma_f32_16x16x32_bf16 v[100:103], v[132:135], v[222:225], v[100:103]
	v_mfma_f32_16x16x32_bf16 v[96:99], v[162:165], v[222:225], v[96:99]
	s_setprio 0
	s_setprio 1
	v_mfma_f32_16x16x32_bf16 v[60:63], v[166:169], v[182:185], v[60:63]
	v_mfma_f32_16x16x32_bf16 v[56:59], v[174:177], v[182:185], v[56:59]
	v_mfma_f32_16x16x32_bf16 v[52:55], v[166:169], v[190:193], v[52:55]
	v_mfma_f32_16x16x32_bf16 v[48:51], v[174:177], v[190:193], v[48:51]
	v_mfma_f32_16x16x32_bf16 v[44:47], v[166:169], v[198:201], v[44:47]
	v_mfma_f32_16x16x32_bf16 v[40:43], v[174:177], v[198:201], v[40:43]
	v_mfma_f32_16x16x32_bf16 v[36:39], v[166:169], v[218:221], v[36:39]
	v_mfma_f32_16x16x32_bf16 v[32:35], v[174:177], v[218:221], v[32:35]
	v_mfma_f32_16x16x32_bf16 v[60:63], v[170:173], v[186:189], v[60:63]
	v_mfma_f32_16x16x32_bf16 v[56:59], v[178:181], v[186:189], v[56:59]
	v_mfma_f32_16x16x32_bf16 v[52:55], v[170:173], v[194:197], v[52:55]
	v_mfma_f32_16x16x32_bf16 v[48:51], v[178:181], v[194:197], v[48:51]
	v_mfma_f32_16x16x32_bf16 v[44:47], v[170:173], v[202:205], v[44:47]
	v_mfma_f32_16x16x32_bf16 v[40:43], v[178:181], v[202:205], v[40:43]
	v_mfma_f32_16x16x32_bf16 v[36:39], v[170:173], v[222:225], v[36:39]
	s_barrier
	v_mfma_f32_16x16x32_bf16 v[32:35], v[178:181], v[222:225], v[32:35]
	s_setprio 0
	s_add_i32 s52, s33, s82
	v_lshl_add_u64 v[226:227], s[76:77], 0, v[138:139]
	s_mov_b32 m0, s52
	ds_read_b128 v[182:185], v216 offset:16384
	ds_read_b128 v[186:189], v216 offset:17408
	ds_read_b128 v[190:193], v216 offset:18432
	ds_read_b128 v[194:197], v216 offset:19456
	ds_read_b128 v[198:201], v216 offset:20480
	ds_read_b128 v[202:205], v216 offset:21504
	ds_read_b128 v[218:221], v216 offset:22528
	ds_read_b128 v[222:225], v216 offset:23552
	global_load_lds_dwordx4 v[226:227], off
	s_add_i32 m0, s52, 0x2000
	s_add_u32 s52, s76, 0x200000
	v_lshl_add_u64 v[228:229], s[76:77], 0, v[142:143]
	s_addc_u32 s53, s77, 0
	s_add_i32 s56, s92, s82
	global_load_lds_dwordx4 v[228:229], off
	v_lshl_add_u64 v[230:231], s[52:53], 0, v[138:139]
	s_mov_b32 m0, s56
	v_lshl_add_u64 v[232:233], s[78:79], 0, v[140:141]
	global_load_lds_dwordx4 v[230:231], off
	v_lshl_add_u64 v[230:231], s[52:53], 0, v[142:143]
	s_add_i32 m0, s56, 0x2000
	s_nop 0
	global_load_lds_dwordx4 v[230:231], off
	v_lshl_add_u64 v[230:231], s[78:79], 0, v[136:137]
	s_mov_b32 m0, s83
	s_nop 0
	global_load_lds_dwordx4 v[230:231], off
	s_mov_b32 m0, s84
	s_nop 0
	global_load_lds_dwordx4 v[232:233], off
	s_waitcnt vmcnt(8)
	s_waitcnt lgkmcnt(0)
	s_barrier
; #define PG8_STAGE(bufoff, gbase, voff) do { _Pragma("unroll") for (int _i = 0; _i < 2; ++_i) \
;         __builtin_amdgcn_global_load_lds((const unsigned*)((const char*)(gbase) + (voff)[_i]), (PG8_LAS unsigned*)(lds + (bufoff) + ldsw + _i * 8192), 16, 0, 0); } while (0)
; #define PG8_LDA(dst, b, h) do { _Pragma("unroll") for (int m = 0; m < 4; ++m) _Pragma("unroll") for (int k = 0; k < 2; ++k) dst[m][k] = *(const PG8_LAS bf16x8*)(lds + PG8_SA(b, h) + aoff + m * 2048 + k * 1024); } while (0)
; #define PG8_LDB(dst, b, h) do { _Pragma("unroll") for (int n = 0; n < 2; ++n) _Pragma("unroll") for (int k = 0; k < 2; ++k) dst[n][k] = *(const PG8_LAS bf16x8*)(lds + PG8_SB(b, h) + boff + n * 2048 + k * 1024); } while (0)
; #define PG8_MMA(ai, bj, At, Bt) do { __builtin_amdgcn_s_setprio(1); _Pragma("unroll") for (int m = 0; m < 4; ++m) _Pragma("unroll") for (int n = 0; n < 2; ++n) _Pragma("unroll") for (int k = 0; k < 2; ++k) \
;         acc[ai][bj][m][n] = __builtin_amdgcn_mfma_f32_16x16x32_bf16(Bt[n][k], At[m][k], acc[ai][bj][m][n], 0, 0, 0); __builtin_amdgcn_s_setprio(0); } while (0)
; #define PG8_WAIT_V(n) asm volatile("s_waitcnt vmcnt(" #n ")" ::: "memory")
; #define PG8_WAIT_L(n) asm volatile("s_waitcnt lgkmcnt(" #n ")" ::: "memory")
; #define PG8_BAR __builtin_amdgcn_s_barrier()
; #define PG8_SCHED __builtin_amdgcn_sched_barrier(0)
; template <class Epi, class Sched, bool ALIGN_EPI = false, bool SP2 = false>
; __device__ __forceinline__ void gemm_phase(PG8_LAS unsigned char* lds, const Gemm g, const Sched& S, const Epi& E) {
;     ...
;             PG8_WAIT_V(8); PG8_WAIT_L(0); PG8_BAR; PG8_MMA(1, 0, At, B0); PG8_MMA(1, 1, At, B1); PG8_BAR; PG8_SCHED;
;             PG8_LDB(B0, 1, 0); PG8_LDB(B1, 1, 1); PG8_SCHED; PG8_LDA(At, 1, 0); PG8_STAGE(PG8_SA(0, 1), a2 + hstep, voffA);
;             PG8_WAIT_V(8); PG8_WAIT_L(0); PG8_BAR; PG8_MMA(0, 0, At, B0); PG8_MMA(0, 1, At, B1); PG8_BAR; PG8_SCHED;
	s_setprio 1
	v_mfma_f32_16x16x32_bf16 v[92:95], v[128:131], v[182:185], v[92:95]
	v_mfma_f32_16x16x32_bf16 v[88:91], v[158:161], v[182:185], v[88:91]
	v_mfma_f32_16x16x32_bf16 v[84:87], v[128:131], v[190:193], v[84:87]
	v_mfma_f32_16x16x32_bf16 v[80:83], v[158:161], v[190:193], v[80:83]
	v_mfma_f32_16x16x32_bf16 v[76:79], v[128:131], v[198:201], v[76:79]
	v_mfma_f32_16x16x32_bf16 v[72:75], v[158:161], v[198:201], v[72:75]
	v_mfma_f32_16x16x32_bf16 v[68:71], v[128:131], v[218:221], v[68:71]
	v_mfma_f32_16x16x32_bf16 v[64:67], v[158:161], v[218:221], v[64:67]
	v_mfma_f32_16x16x32_bf16 v[92:95], v[132:135], v[186:189], v[92:95]
	v_mfma_f32_16x16x32_bf16 v[88:91], v[162:165], v[186:189], v[88:91]
	v_mfma_f32_16x16x32_bf16 v[84:87], v[132:135], v[194:197], v[84:87]
	v_mfma_f32_16x16x32_bf16 v[80:83], v[162:165], v[194:197], v[80:83]
	v_mfma_f32_16x16x32_bf16 v[76:79], v[132:135], v[202:205], v[76:79]
	v_mfma_f32_16x16x32_bf16 v[72:75], v[162:165], v[202:205], v[72:75]
	v_mfma_f32_16x16x32_bf16 v[68:71], v[132:135], v[222:225], v[68:71]
	v_mfma_f32_16x16x32_bf16 v[64:67], v[162:165], v[222:225], v[64:67]
	s_setprio 0
	s_setprio 1
	v_mfma_f32_16x16x32_bf16 v[28:31], v[166:169], v[182:185], v[28:31]
	v_mfma_f32_16x16x32_bf16 v[24:27], v[174:177], v[182:185], v[24:27]
	v_mfma_f32_16x16x32_bf16 v[20:23], v[166:169], v[190:193], v[20:23]
	v_mfma_f32_16x16x32_bf16 v[16:19], v[174:177], v[190:193], v[16:19]
	v_mfma_f32_16x16x32_bf16 v[12:15], v[166:169], v[198:201], v[12:15]
	v_mfma_f32_16x16x32_bf16 v[8:11], v[174:177], v[198:201], v[8:11]
	v_mfma_f32_16x16x32_bf16 v[4:7], v[166:169], v[218:221], v[4:7]
	v_mfma_f32_16x16x32_bf16 v[0:3], v[174:177], v[218:221], v[0:3]
	v_mfma_f32_16x16x32_bf16 v[28:31], v[170:173], v[186:189], v[28:31]
	v_mfma_f32_16x16x32_bf16 v[24:27], v[178:181], v[186:189], v[24:27]
	v_mfma_f32_16x16x32_bf16 v[20:23], v[170:173], v[194:197], v[20:23]
	v_mfma_f32_16x16x32_bf16 v[16:19], v[178:181], v[194:197], v[16:19]
	v_mfma_f32_16x16x32_bf16 v[12:15], v[170:173], v[202:205], v[12:15]
	v_mfma_f32_16x16x32_bf16 v[8:11], v[178:181], v[202:205], v[8:11]
	v_mfma_f32_16x16x32_bf16 v[4:7], v[170:173], v[222:225], v[4:7]
	s_barrier
	v_mfma_f32_16x16x32_bf16 v[0:3], v[178:181], v[222:225], v[0:3]
	s_setprio 0
	s_add_i32 s56, 0, 0x18000
	s_add_i32 s57, 0, 0x1c000
	v_add_u32_e32 v162, s56, v212
	v_add_u32_e32 v178, s57, v212
	ds_read_b128 v[128:131], v162
	ds_read_b128 v[132:135], v162 offset:1024
	ds_read_b128 v[158:161], v162 offset:2048
	ds_read_b128 v[162:165], v162 offset:3072
	ds_read_b128 v[166:169], v178
	ds_read_b128 v[170:173], v178 offset:1024
	ds_read_b128 v[174:177], v178 offset:2048
	ds_read_b128 v[178:181], v178 offset:3072
	s_add_u32 s52, s78, 0x200000
	s_addc_u32 s53, s79, 0
	s_mov_b32 m0, s85
	v_lshl_add_u64 v[234:235], s[52:53], 0, v[136:137]
	ds_read_b128 v[182:185], v216 offset:32768
	ds_read_b128 v[186:189], v216 offset:33792
	ds_read_b128 v[190:193], v216 offset:34816
	ds_read_b128 v[194:197], v216 offset:35840
	ds_read_b128 v[198:201], v216 offset:36864
	ds_read_b128 v[202:205], v216 offset:37888
	ds_read_b128 v[218:221], v216 offset:38912
	ds_read_b128 v[222:225], v216 offset:39936
	global_load_lds_dwordx4 v[234:235], off
	v_lshl_add_u64 v[234:235], s[52:53], 0, v[140:141]
	s_mov_b32 m0, s86
	s_nop 0
	global_load_lds_dwordx4 v[234:235], off
	s_waitcnt vmcnt(8)
	s_waitcnt lgkmcnt(0)
	s_barrier
	s_setprio 1
	v_mfma_f32_16x16x32_bf16 v[124:127], v[128:131], v[182:185], v[124:127]
	v_mfma_f32_16x16x32_bf16 v[120:123], v[158:161], v[182:185], v[120:123]
	v_mfma_f32_16x16x32_bf16 v[116:119], v[128:131], v[190:193], v[116:119]
	v_mfma_f32_16x16x32_bf16 v[112:115], v[158:161], v[190:193], v[112:115]
	v_mfma_f32_16x16x32_bf16 v[108:111], v[128:131], v[198:201], v[108:111]
	v_mfma_f32_16x16x32_bf16 v[104:107], v[158:161], v[198:201], v[104:107]
	v_mfma_f32_16x16x32_bf16 v[100:103], v[128:131], v[218:221], v[100:103]
	v_mfma_f32_16x16x32_bf16 v[96:99], v[158:161], v[218:221], v[96:99]
	v_mfma_f32_16x16x32_bf16 v[124:127], v[132:135], v[186:189], v[124:127]
	v_mfma_f32_16x16x32_bf16 v[120:123], v[162:165], v[186:189], v[120:123]
	v_mfma_f32_16x16x32_bf16 v[116:119], v[132:135], v[194:197], v[116:119]
	v_mfma_f32_16x16x32_bf16 v[112:115], v[162:165], v[194:197], v[112:115]
	v_mfma_f32_16x16x32_bf16 v[108:111], v[132:135], v[202:205], v[108:111]
	v_mfma_f32_16x16x32_bf16 v[104:107], v[162:165], v[202:205], v[104:107]
	v_mfma_f32_16x16x32_bf16 v[100:103], v[132:135], v[222:225], v[100:103]
	v_mfma_f32_16x16x32_bf16 v[96:99], v[162:165], v[222:225], v[96:99]
	s_setprio 0
	s_setprio 1
	v_mfma_f32_16x16x32_bf16 v[60:63], v[166:169], v[182:185], v[60:63]
	v_mfma_f32_16x16x32_bf16 v[56:59], v[174:177], v[182:185], v[56:59]
	v_mfma_f32_16x16x32_bf16 v[52:55], v[166:169], v[190:193], v[52:55]
	v_mfma_f32_16x16x32_bf16 v[48:51], v[174:177], v[190:193], v[48:51]
	v_mfma_f32_16x16x32_bf16 v[44:47], v[166:169], v[198:201], v[44:47]
	v_mfma_f32_16x16x32_bf16 v[40:43], v[174:177], v[198:201], v[40:43]
	v_mfma_f32_16x16x32_bf16 v[36:39], v[166:169], v[218:221], v[36:39]
	v_mfma_f32_16x16x32_bf16 v[32:35], v[174:177], v[218:221], v[32:35]
	v_mfma_f32_16x16x32_bf16 v[60:63], v[170:173], v[186:189], v[60:63]
	v_mfma_f32_16x16x32_bf16 v[56:59], v[178:181], v[186:189], v[56:59]
	v_mfma_f32_16x16x32_bf16 v[52:55], v[170:173], v[194:197], v[52:55]
	v_mfma_f32_16x16x32_bf16 v[48:51], v[178:181], v[194:197], v[48:51]
	v_mfma_f32_16x16x32_bf16 v[44:47], v[170:173], v[202:205], v[44:47]
	v_mfma_f32_16x16x32_bf16 v[40:43], v[178:181], v[202:205], v[40:43]
	v_mfma_f32_16x16x32_bf16 v[36:39], v[170:173], v[222:225], v[36:39]
	s_barrier
; #define PG8_STAGE(bufoff, gbase, voff) do { _Pragma("unroll") for (int _i = 0; _i < 2; ++_i) \
;         __builtin_amdgcn_global_load_lds((const unsigned*)((const char*)(gbase) + (voff)[_i]), (PG8_LAS unsigned*)(lds + (bufoff) + ldsw + _i * 8192), 16, 0, 0); } while (0)
; #define PG8_LDA(dst, b, h) do { _Pragma("unroll") for (int m = 0; m < 4; ++m) _Pragma("unroll") for (int k = 0; k < 2; ++k) dst[m][k] = *(const PG8_LAS bf16x8*)(lds + PG8_SA(b, h) + aoff + m * 2048 + k * 1024); } while (0)
; #define PG8_MMA(ai, bj, At, Bt) do { __builtin_amdgcn_s_setprio(1); _Pragma("unroll") for (int m = 0; m < 4; ++m) _Pragma("unroll") for (int n = 0; n < 2; ++n) _Pragma("unroll") for (int k = 0; k < 2; ++k) \
;         acc[ai][bj][m][n] = __builtin_amdgcn_mfma_f32_16x16x32_bf16(Bt[n][k], At[m][k], acc[ai][bj][m][n], 0, 0, 0); __builtin_amdgcn_s_setprio(0); } while (0)
; #define PG8_WAIT_V(n) asm volatile("s_waitcnt vmcnt(" #n ")" ::: "memory")
; #define PG8_WAIT_L(n) asm volatile("s_waitcnt lgkmcnt(" #n ")" ::: "memory")
; #define PG8_BAR __builtin_amdgcn_s_barrier()
; #define PG8_SCHED __builtin_amdgcn_sched_barrier(0)
; template <class Epi, class Sched, bool ALIGN_EPI = false, bool SP2 = false>
; __device__ __forceinline__ void gemm_phase(PG8_LAS unsigned char* lds, const Gemm g, const Sched& S, const Epi& E) {
;     ...
;             PG8_LDA(At, 1, 1); PG8_STAGE(PG8_SB(1, 0), b3, voffB); PG8_STAGE(PG8_SB(1, 1), b3 + hstep, voffB); PG8_STAGE(PG8_SA(1, 0), a3, voffA);
;             PG8_WAIT_V(8); PG8_WAIT_L(0); PG8_BAR; PG8_MMA(1, 0, At, B0); PG8_MMA(1, 1, At, B1); PG8_BAR; PG8_SCHED;
;     ...
;         if constexpr (ALIGN_EPI) { if (wr == 0) PG8_BAR; }
	v_mfma_f32_16x16x32_bf16 v[32:35], v[178:181], v[222:225], v[32:35]
	s_setprio 0
	s_add_i32 s52, s56, s82
	v_lshl_add_u64 v[226:227], v[226:227], 0, s[36:37]
	s_mov_b32 m0, s52
	ds_read_b128 v[182:185], v216 offset:49152
	ds_read_b128 v[186:189], v216 offset:50176
	ds_read_b128 v[190:193], v216 offset:51200
	ds_read_b128 v[194:197], v216 offset:52224
	ds_read_b128 v[198:201], v216 offset:53248
	ds_read_b128 v[202:205], v216 offset:54272
	ds_read_b128 v[218:221], v216 offset:55296
	ds_read_b128 v[222:225], v216 offset:56320
	global_load_lds_dwordx4 v[226:227], off
	s_add_i32 m0, s52, 0x2000
	s_add_u32 s52, s76, 0x200080
	v_lshl_add_u64 v[226:227], v[228:229], 0, s[36:37]
	s_addc_u32 s53, s77, 0
	s_add_i32 s56, s57, s82
	global_load_lds_dwordx4 v[226:227], off
	v_lshl_add_u64 v[226:227], s[52:53], 0, v[138:139]
	s_mov_b32 m0, s56
	s_nop 0
	global_load_lds_dwordx4 v[226:227], off
	v_lshl_add_u64 v[226:227], s[52:53], 0, v[142:143]
	s_add_i32 m0, s56, 0x2000
	s_nop 0
	global_load_lds_dwordx4 v[226:227], off
	v_lshl_add_u64 v[226:227], v[230:231], 0, s[36:37]
	s_mov_b32 m0, s94
	s_nop 0
	global_load_lds_dwordx4 v[226:227], off
	v_lshl_add_u64 v[226:227], v[232:233], 0, s[36:37]
	s_mov_b32 m0, s95
	s_nop 0
	global_load_lds_dwordx4 v[226:227], off
	s_waitcnt vmcnt(8)
	s_waitcnt lgkmcnt(0)
	s_barrier
	s_setprio 1
	v_mfma_f32_16x16x32_bf16 v[92:95], v[128:131], v[182:185], v[92:95]
	v_mfma_f32_16x16x32_bf16 v[88:91], v[158:161], v[182:185], v[88:91]
	v_mfma_f32_16x16x32_bf16 v[84:87], v[128:131], v[190:193], v[84:87]
	v_mfma_f32_16x16x32_bf16 v[80:83], v[158:161], v[190:193], v[80:83]
	v_mfma_f32_16x16x32_bf16 v[76:79], v[128:131], v[198:201], v[76:79]
	v_mfma_f32_16x16x32_bf16 v[72:75], v[158:161], v[198:201], v[72:75]
	v_mfma_f32_16x16x32_bf16 v[68:71], v[128:131], v[218:221], v[68:71]
	v_mfma_f32_16x16x32_bf16 v[64:67], v[158:161], v[218:221], v[64:67]
	v_mfma_f32_16x16x32_bf16 v[92:95], v[132:135], v[186:189], v[92:95]
	v_mfma_f32_16x16x32_bf16 v[88:91], v[162:165], v[186:189], v[88:91]
	v_mfma_f32_16x16x32_bf16 v[84:87], v[132:135], v[194:197], v[84:87]
	v_mfma_f32_16x16x32_bf16 v[80:83], v[162:165], v[194:197], v[80:83]
	v_mfma_f32_16x16x32_bf16 v[76:79], v[132:135], v[202:205], v[76:79]
	v_mfma_f32_16x16x32_bf16 v[72:75], v[162:165], v[202:205], v[72:75]
	v_mfma_f32_16x16x32_bf16 v[68:71], v[132:135], v[222:225], v[68:71]
	v_mfma_f32_16x16x32_bf16 v[64:67], v[162:165], v[222:225], v[64:67]
	s_setprio 0
	s_setprio 1
	v_mfma_f32_16x16x32_bf16 v[28:31], v[166:169], v[182:185], v[28:31]
	v_mfma_f32_16x16x32_bf16 v[24:27], v[174:177], v[182:185], v[24:27]
	v_mfma_f32_16x16x32_bf16 v[20:23], v[166:169], v[190:193], v[20:23]
	v_mfma_f32_16x16x32_bf16 v[16:19], v[174:177], v[190:193], v[16:19]
	v_mfma_f32_16x16x32_bf16 v[12:15], v[166:169], v[198:201], v[12:15]
	v_mfma_f32_16x16x32_bf16 v[8:11], v[174:177], v[198:201], v[8:11]
	v_mfma_f32_16x16x32_bf16 v[4:7], v[166:169], v[218:221], v[4:7]
	v_mfma_f32_16x16x32_bf16 v[0:3], v[174:177], v[218:221], v[0:3]
	v_mfma_f32_16x16x32_bf16 v[28:31], v[170:173], v[186:189], v[28:31]
	v_mfma_f32_16x16x32_bf16 v[24:27], v[178:181], v[186:189], v[24:27]
	v_mfma_f32_16x16x32_bf16 v[20:23], v[170:173], v[194:197], v[20:23]
	v_mfma_f32_16x16x32_bf16 v[16:19], v[178:181], v[194:197], v[16:19]
	v_mfma_f32_16x16x32_bf16 v[12:15], v[170:173], v[202:205], v[12:15]
	v_mfma_f32_16x16x32_bf16 v[8:11], v[178:181], v[202:205], v[8:11]
	v_mfma_f32_16x16x32_bf16 v[4:7], v[170:173], v[222:225], v[4:7]
	s_barrier
	v_mfma_f32_16x16x32_bf16 v[0:3], v[178:181], v[222:225], v[0:3]
	s_setprio 0
	s_add_i32 vcc_hi, vcc_hi, 2
	s_add_u32 s74, s74, 0x100
	s_addc_u32 s75, s75, 0
	s_add_u32 s93, s93, 0x100
	s_addc_u32 vcc_lo, vcc_lo, 0
	s_cmpk_gt_u32 vcc_hi, 0x7d
	s_cbranch_scc0 .LBB0_624
	s_and_b64 vcc, exec, s[40:41]
	s_cbranch_vccz .LBB0_627
	s_barrier

; #define PG8_STAGE(bufoff, gbase, voff) do { _Pragma("unroll") for (int _i = 0; _i < 2; ++_i) \
;         __builtin_amdgcn_global_load_lds((const unsigned*)((const char*)(gbase) + (voff)[_i]), (PG8_LAS unsigned*)(lds + (bufoff) + ldsw + _i * 8192), 16, 0, 0); } while (0)
; #define PG8_LDA(dst, b, h) do { _Pragma("unroll") for (int m = 0; m < 4; ++m) _Pragma("unroll") for (int k = 0; k < 2; ++k) dst[m][k] = *(const PG8_LAS bf16x8*)(lds + PG8_SA(b, h) + aoff + m * 2048 + k * 1024); } while (0)
; #define PG8_LDB(dst, b, h) do { _Pragma("unroll") for (int n = 0; n < 2; ++n) _Pragma("unroll") for (int k = 0; k < 2; ++k) dst[n][k] = *(const PG8_LAS bf16x8*)(lds + PG8_SB(b, h) + boff + n * 2048 + k * 1024); } while (0)
; #define PG8_MMA(ai, bj, At, Bt) do { __builtin_amdgcn_s_setprio(1); _Pragma("unroll") for (int m = 0; m < 4; ++m) _Pragma("unroll") for (int n = 0; n < 2; ++n) _Pragma("unroll") for (int k = 0; k < 2; ++k) \
;         acc[ai][bj][m][n] = __builtin_amdgcn_mfma_f32_16x16x32_bf16(Bt[n][k], At[m][k], acc[ai][bj][m][n], 0, 0, 0); __builtin_amdgcn_s_setprio(0); } while (0)
; #define PG8_WAIT_V(n) asm volatile("s_waitcnt vmcnt(" #n ")" ::: "memory")
; #define PG8_WAIT_L(n) asm volatile("s_waitcnt lgkmcnt(" #n ")" ::: "memory")
; #define PG8_BAR __builtin_amdgcn_s_barrier()
; #define PG8_SCHED __builtin_amdgcn_sched_barrier(0)
; template <class Epi, class Sched, bool ALIGN_EPI = false, bool SP2 = false>
; __device__ __forceinline__ void gemm_phase(PG8_LAS unsigned char* lds, const Gemm g, const Sched& S, const Epi& E) {
;     ...
;             const char* a1 = cA + (size_t)(t + 1) * kstep;
;             const char* a2 = last ? nA : cA + (size_t)(t + 2) * kstep; const char* b2 = last ? nB : cB + (size_t)(t + 2) * kstep;
;             const char* a3 = a2 + kstep; const char* b3 = b2 + kstep;
;             if constexpr (SP2) {
;             PG8_LDB(B0, 0, 0); PG8_LDB(B1, 0, 1); PG8_SCHED; PG8_LDA(At, 0, 0); PG8_STAGE(PG8_SA(1, 1), a1 + hstep, voffA);
;             PG8_WAIT_V(8); PG8_WAIT_L(0); PG8_BAR; PG8_MMA(0, 0, At, B0); PG8_MMA(0, 1, At, B1); PG8_BAR; PG8_SCHED;
;             PG8_LDA(At, 0, 1); PG8_STAGE(PG8_SB(0, 0), b2, voffB); PG8_STAGE(PG8_SB(0, 1), b2 + hstep, voffB); PG8_STAGE(PG8_SA(0, 0), a2, voffA);
;             PG8_WAIT_V(8); PG8_WAIT_L(0); PG8_BAR; PG8_MMA(1, 0, At, B0); PG8_MMA(1, 1, At, B1); PG8_BAR; PG8_SCHED;
.LBB0_660:
	ds_read_b128 v[166:169], v145
	ds_read_b128 v[170:173], v145 offset:1024
	ds_read_b128 v[174:177], v145 offset:2048
	ds_read_b128 v[178:181], v145 offset:3072
	ds_read_b128 v[182:185], v149
	ds_read_b128 v[186:189], v149 offset:1024
	ds_read_b128 v[190:193], v149 offset:2048
	ds_read_b128 v[194:197], v149 offset:3072
	s_add_u32 s52, s72, 0xffe00080
	s_addc_u32 s53, s73, -1
	s_cmp_eq_u32 s49, 28
	s_cselect_b32 s77, s51, s53
	s_cselect_b32 s76, s50, s52
	s_cselect_b32 s75, s55, s41
	s_cselect_b32 s74, s54, s37
	s_mov_b32 m0, s82
	v_lshl_add_u64 v[230:231], s[72:73], 0, v[160:161]
	ds_read_b128 v[198:201], v164
	ds_read_b128 v[202:205], v164 offset:1024
	ds_read_b128 v[206:209], v164 offset:2048
	ds_read_b128 v[210:213], v164 offset:3072
	ds_read_b128 v[214:217], v164 offset:4096
	ds_read_b128 v[218:221], v164 offset:5120
	ds_read_b128 v[222:225], v164 offset:6144
	ds_read_b128 v[226:229], v164 offset:7168
	global_load_lds_dwordx4 v[230:231], off
	v_lshl_add_u64 v[230:231], s[72:73], 0, v[162:163]
	s_mov_b32 m0, s83
	s_nop 0
	global_load_lds_dwordx4 v[230:231], off
	s_waitcnt vmcnt(8)
	s_waitcnt lgkmcnt(0)
	s_barrier
	s_setprio 1
	v_mfma_f32_16x16x32_bf16 v[124:127], v[166:169], v[198:201], v[124:127]
	v_mfma_f32_16x16x32_bf16 v[120:123], v[174:177], v[198:201], v[120:123]
	v_mfma_f32_16x16x32_bf16 v[116:119], v[166:169], v[206:209], v[116:119]
	v_mfma_f32_16x16x32_bf16 v[108:111], v[174:177], v[206:209], v[108:111]
	v_mfma_f32_16x16x32_bf16 v[100:103], v[166:169], v[214:217], v[100:103]
	v_mfma_f32_16x16x32_bf16 v[92:95], v[174:177], v[214:217], v[92:95]
	v_mfma_f32_16x16x32_bf16 v[84:87], v[166:169], v[222:225], v[84:87]
	v_mfma_f32_16x16x32_bf16 v[76:79], v[174:177], v[222:225], v[76:79]
	v_mfma_f32_16x16x32_bf16 v[124:127], v[170:173], v[202:205], v[124:127]
	v_mfma_f32_16x16x32_bf16 v[120:123], v[178:181], v[202:205], v[120:123]
	v_mfma_f32_16x16x32_bf16 v[116:119], v[170:173], v[210:213], v[116:119]
	v_mfma_f32_16x16x32_bf16 v[108:111], v[178:181], v[210:213], v[108:111]
	v_mfma_f32_16x16x32_bf16 v[100:103], v[170:173], v[218:221], v[100:103]
	v_mfma_f32_16x16x32_bf16 v[92:95], v[178:181], v[218:221], v[92:95]
	v_mfma_f32_16x16x32_bf16 v[84:87], v[170:173], v[226:229], v[84:87]
	v_mfma_f32_16x16x32_bf16 v[76:79], v[178:181], v[226:229], v[76:79]
	s_setprio 0
	s_setprio 1
	v_mfma_f32_16x16x32_bf16 v[112:115], v[182:185], v[198:201], v[112:115]
	v_mfma_f32_16x16x32_bf16 v[104:107], v[190:193], v[198:201], v[104:107]
	v_mfma_f32_16x16x32_bf16 v[96:99], v[182:185], v[206:209], v[96:99]
	v_mfma_f32_16x16x32_bf16 v[88:91], v[190:193], v[206:209], v[88:91]
	v_mfma_f32_16x16x32_bf16 v[80:83], v[182:185], v[214:217], v[80:83]
	v_mfma_f32_16x16x32_bf16 v[72:75], v[190:193], v[214:217], v[72:75]
	v_mfma_f32_16x16x32_bf16 v[68:71], v[182:185], v[222:225], v[68:71]
	v_mfma_f32_16x16x32_bf16 v[64:67], v[190:193], v[222:225], v[64:67]
	v_mfma_f32_16x16x32_bf16 v[112:115], v[186:189], v[202:205], v[112:115]
	v_mfma_f32_16x16x32_bf16 v[104:107], v[194:197], v[202:205], v[104:107]
	v_mfma_f32_16x16x32_bf16 v[96:99], v[186:189], v[210:213], v[96:99]
	v_mfma_f32_16x16x32_bf16 v[88:91], v[194:197], v[210:213], v[88:91]
	v_mfma_f32_16x16x32_bf16 v[80:83], v[186:189], v[218:221], v[80:83]
	v_mfma_f32_16x16x32_bf16 v[72:75], v[194:197], v[218:221], v[72:75]
	v_mfma_f32_16x16x32_bf16 v[68:71], v[186:189], v[226:229], v[68:71]
	s_barrier
	v_mfma_f32_16x16x32_bf16 v[64:67], v[194:197], v[226:229], v[64:67]
	s_setprio 0
	s_mov_b32 m0, s84
	v_lshl_add_u64 v[230:231], s[74:75], 0, v[138:139]
	s_add_u32 s52, s74, 0x200000
	ds_read_b128 v[198:201], v164 offset:16384
	ds_read_b128 v[202:205], v164 offset:17408
	ds_read_b128 v[206:209], v164 offset:18432
	ds_read_b128 v[210:213], v164 offset:19456
	ds_read_b128 v[214:217], v164 offset:20480
	ds_read_b128 v[218:221], v164 offset:21504
	ds_read_b128 v[222:225], v164 offset:22528
	ds_read_b128 v[226:229], v164 offset:23552
	global_load_lds_dwordx4 v[230:231], off
	v_lshl_add_u64 v[232:233], s[74:75], 0, v[142:143]
	s_mov_b32 m0, s85
	s_addc_u32 s53, s75, 0
	global_load_lds_dwordx4 v[232:233], off
	v_lshl_add_u64 v[234:235], s[52:53], 0, v[138:139]
	s_mov_b32 m0, s86
	v_lshl_add_u64 v[236:237], s[76:77], 0, v[140:141]
	global_load_lds_dwordx4 v[234:235], off
	v_lshl_add_u64 v[234:235], s[52:53], 0, v[142:143]
	s_mov_b32 m0, s87
	s_nop 0
	global_load_lds_dwordx4 v[234:235], off
	v_lshl_add_u64 v[234:235], s[76:77], 0, v[136:137]
	s_mov_b32 m0, s28
	s_nop 0
	global_load_lds_dwordx4 v[234:235], off
	s_mov_b32 m0, s29
	s_nop 0
	global_load_lds_dwordx4 v[236:237], off
	s_waitcnt vmcnt(8)
	s_waitcnt lgkmcnt(0)
	s_barrier
; #define PG8_STAGE(bufoff, gbase, voff) do { _Pragma("unroll") for (int _i = 0; _i < 2; ++_i) \
;         __builtin_amdgcn_global_load_lds((const unsigned*)((const char*)(gbase) + (voff)[_i]), (PG8_LAS unsigned*)(lds + (bufoff) + ldsw + _i * 8192), 16, 0, 0); } while (0)
; #define PG8_LDA(dst, b, h) do { _Pragma("unroll") for (int m = 0; m < 4; ++m) _Pragma("unroll") for (int k = 0; k < 2; ++k) dst[m][k] = *(const PG8_LAS bf16x8*)(lds + PG8_SA(b, h) + aoff + m * 2048 + k * 1024); } while (0)
; #define PG8_LDB(dst, b, h) do { _Pragma("unroll") for (int n = 0; n < 2; ++n) _Pragma("unroll") for (int k = 0; k < 2; ++k) dst[n][k] = *(const PG8_LAS bf16x8*)(lds + PG8_SB(b, h) + boff + n * 2048 + k * 1024); } while (0)
; #define PG8_MMA(ai, bj, At, Bt) do { __builtin_amdgcn_s_setprio(1); _Pragma("unroll") for (int m = 0; m < 4; ++m) _Pragma("unroll") for (int n = 0; n < 2; ++n) _Pragma("unroll") for (int k = 0; k < 2; ++k) \
;         acc[ai][bj][m][n] = __builtin_amdgcn_mfma_f32_16x16x32_bf16(Bt[n][k], At[m][k], acc[ai][bj][m][n], 0, 0, 0); __builtin_amdgcn_s_setprio(0); } while (0)
; #define PG8_WAIT_V(n) asm volatile("s_waitcnt vmcnt(" #n ")" ::: "memory")
; #define PG8_WAIT_L(n) asm volatile("s_waitcnt lgkmcnt(" #n ")" ::: "memory")
; #define PG8_BAR __builtin_amdgcn_s_barrier()
; #define PG8_SCHED __builtin_amdgcn_sched_barrier(0)
; template <class Epi, class Sched, bool ALIGN_EPI = false, bool SP2 = false>
; __device__ __forceinline__ void gemm_phase(PG8_LAS unsigned char* lds, const Gemm g, const Sched& S, const Epi& E) {
;     ...
;             PG8_WAIT_V(8); PG8_WAIT_L(0); PG8_BAR; PG8_MMA(1, 0, At, B0); PG8_MMA(1, 1, At, B1); PG8_BAR; PG8_SCHED;
;             PG8_LDB(B0, 1, 0); PG8_LDB(B1, 1, 1); PG8_SCHED; PG8_LDA(At, 1, 0); PG8_STAGE(PG8_SA(0, 1), a2 + hstep, voffA);
;             PG8_WAIT_V(8); PG8_WAIT_L(0); PG8_BAR; PG8_MMA(0, 0, At, B0); PG8_MMA(0, 1, At, B1); PG8_BAR; PG8_SCHED;
	s_setprio 1
	v_mfma_f32_16x16x32_bf16 v[60:63], v[166:169], v[198:201], v[60:63]
	v_mfma_f32_16x16x32_bf16 v[56:59], v[174:177], v[198:201], v[56:59]
	v_mfma_f32_16x16x32_bf16 v[52:55], v[166:169], v[206:209], v[52:55]
	v_mfma_f32_16x16x32_bf16 v[44:47], v[174:177], v[206:209], v[44:47]
	v_mfma_f32_16x16x32_bf16 v[36:39], v[166:169], v[214:217], v[36:39]
	v_mfma_f32_16x16x32_bf16 v[28:31], v[174:177], v[214:217], v[28:31]
	v_mfma_f32_16x16x32_bf16 v[20:23], v[166:169], v[222:225], v[20:23]
	v_mfma_f32_16x16x32_bf16 v[12:15], v[174:177], v[222:225], v[12:15]
	v_mfma_f32_16x16x32_bf16 v[60:63], v[170:173], v[202:205], v[60:63]
	v_mfma_f32_16x16x32_bf16 v[56:59], v[178:181], v[202:205], v[56:59]
	v_mfma_f32_16x16x32_bf16 v[52:55], v[170:173], v[210:213], v[52:55]
	v_mfma_f32_16x16x32_bf16 v[44:47], v[178:181], v[210:213], v[44:47]
	v_mfma_f32_16x16x32_bf16 v[36:39], v[170:173], v[218:221], v[36:39]
	v_mfma_f32_16x16x32_bf16 v[28:31], v[178:181], v[218:221], v[28:31]
	v_mfma_f32_16x16x32_bf16 v[20:23], v[170:173], v[226:229], v[20:23]
	v_mfma_f32_16x16x32_bf16 v[12:15], v[178:181], v[226:229], v[12:15]
	s_setprio 0
	s_setprio 1
	v_mfma_f32_16x16x32_bf16 v[48:51], v[182:185], v[198:201], v[48:51]
	v_mfma_f32_16x16x32_bf16 v[40:43], v[190:193], v[198:201], v[40:43]
	v_mfma_f32_16x16x32_bf16 v[32:35], v[182:185], v[206:209], v[32:35]
	v_mfma_f32_16x16x32_bf16 v[24:27], v[190:193], v[206:209], v[24:27]
	v_mfma_f32_16x16x32_bf16 v[16:19], v[182:185], v[214:217], v[16:19]
	v_mfma_f32_16x16x32_bf16 v[8:11], v[190:193], v[214:217], v[8:11]
	v_mfma_f32_16x16x32_bf16 v[4:7], v[182:185], v[222:225], v[4:7]
	v_mfma_f32_16x16x32_bf16 v[0:3], v[190:193], v[222:225], v[0:3]
	v_mfma_f32_16x16x32_bf16 v[48:51], v[186:189], v[202:205], v[48:51]
	v_mfma_f32_16x16x32_bf16 v[40:43], v[194:197], v[202:205], v[40:43]
	v_mfma_f32_16x16x32_bf16 v[32:35], v[186:189], v[210:213], v[32:35]
	v_mfma_f32_16x16x32_bf16 v[24:27], v[194:197], v[210:213], v[24:27]
	v_mfma_f32_16x16x32_bf16 v[16:19], v[186:189], v[218:221], v[16:19]
	v_mfma_f32_16x16x32_bf16 v[8:11], v[194:197], v[218:221], v[8:11]
	v_mfma_f32_16x16x32_bf16 v[4:7], v[186:189], v[226:229], v[4:7]
	s_barrier
	v_mfma_f32_16x16x32_bf16 v[0:3], v[194:197], v[226:229], v[0:3]
	s_setprio 0
	ds_read_b128 v[166:169], v148
	ds_read_b128 v[170:173], v148 offset:1024
	ds_read_b128 v[174:177], v148 offset:2048
	ds_read_b128 v[178:181], v148 offset:3072
	ds_read_b128 v[182:185], v165
	ds_read_b128 v[186:189], v165 offset:1024
	ds_read_b128 v[190:193], v165 offset:2048
	ds_read_b128 v[194:197], v165 offset:3072
	s_add_u32 s52, s76, 0x200000
	s_addc_u32 s53, s77, 0
	s_mov_b32 m0, s33
	v_lshl_add_u64 v[238:239], s[52:53], 0, v[136:137]
	ds_read_b128 v[198:201], v164 offset:32768
	ds_read_b128 v[202:205], v164 offset:33792
	ds_read_b128 v[206:209], v164 offset:34816
	ds_read_b128 v[210:213], v164 offset:35840
	ds_read_b128 v[214:217], v164 offset:36864
	ds_read_b128 v[218:221], v164 offset:37888
	ds_read_b128 v[222:225], v164 offset:38912
	ds_read_b128 v[226:229], v164 offset:39936
	global_load_lds_dwordx4 v[238:239], off
	v_lshl_add_u64 v[238:239], s[52:53], 0, v[140:141]
	s_mov_b32 m0, s38
	s_nop 0
	global_load_lds_dwordx4 v[238:239], off
	s_waitcnt vmcnt(8)
	s_waitcnt lgkmcnt(0)
	s_barrier
	s_setprio 1
	v_mfma_f32_16x16x32_bf16 v[124:127], v[166:169], v[198:201], v[124:127]
	v_mfma_f32_16x16x32_bf16 v[120:123], v[174:177], v[198:201], v[120:123]
	v_mfma_f32_16x16x32_bf16 v[116:119], v[166:169], v[206:209], v[116:119]
	v_mfma_f32_16x16x32_bf16 v[108:111], v[174:177], v[206:209], v[108:111]
	v_mfma_f32_16x16x32_bf16 v[100:103], v[166:169], v[214:217], v[100:103]
	v_mfma_f32_16x16x32_bf16 v[92:95], v[174:177], v[214:217], v[92:95]
	v_mfma_f32_16x16x32_bf16 v[84:87], v[166:169], v[222:225], v[84:87]
	v_mfma_f32_16x16x32_bf16 v[76:79], v[174:177], v[222:225], v[76:79]
	v_mfma_f32_16x16x32_bf16 v[124:127], v[170:173], v[202:205], v[124:127]
	v_mfma_f32_16x16x32_bf16 v[120:123], v[178:181], v[202:205], v[120:123]
	v_mfma_f32_16x16x32_bf16 v[116:119], v[170:173], v[210:213], v[116:119]
	v_mfma_f32_16x16x32_bf16 v[108:111], v[178:181], v[210:213], v[108:111]
	v_mfma_f32_16x16x32_bf16 v[100:103], v[170:173], v[218:221], v[100:103]
	v_mfma_f32_16x16x32_bf16 v[92:95], v[178:181], v[218:221], v[92:95]
	v_mfma_f32_16x16x32_bf16 v[84:87], v[170:173], v[226:229], v[84:87]
	v_mfma_f32_16x16x32_bf16 v[76:79], v[178:181], v[226:229], v[76:79]
	s_setprio 0
	s_setprio 1
	v_mfma_f32_16x16x32_bf16 v[112:115], v[182:185], v[198:201], v[112:115]
	v_mfma_f32_16x16x32_bf16 v[104:107], v[190:193], v[198:201], v[104:107]
	v_mfma_f32_16x16x32_bf16 v[96:99], v[182:185], v[206:209], v[96:99]
	v_mfma_f32_16x16x32_bf16 v[88:91], v[190:193], v[206:209], v[88:91]
	v_mfma_f32_16x16x32_bf16 v[80:83], v[182:185], v[214:217], v[80:83]
	v_mfma_f32_16x16x32_bf16 v[72:75], v[190:193], v[214:217], v[72:75]
	v_mfma_f32_16x16x32_bf16 v[68:71], v[182:185], v[222:225], v[68:71]
	v_mfma_f32_16x16x32_bf16 v[64:67], v[190:193], v[222:225], v[64:67]
	v_mfma_f32_16x16x32_bf16 v[112:115], v[186:189], v[202:205], v[112:115]
	v_mfma_f32_16x16x32_bf16 v[104:107], v[194:197], v[202:205], v[104:107]
	v_mfma_f32_16x16x32_bf16 v[96:99], v[186:189], v[210:213], v[96:99]
	v_mfma_f32_16x16x32_bf16 v[88:91], v[194:197], v[210:213], v[88:91]
	v_mfma_f32_16x16x32_bf16 v[80:83], v[186:189], v[218:221], v[80:83]
	v_mfma_f32_16x16x32_bf16 v[72:75], v[194:197], v[218:221], v[72:75]
	v_mfma_f32_16x16x32_bf16 v[68:71], v[186:189], v[226:229], v[68:71]
	s_barrier
; #define PG8_STAGE(bufoff, gbase, voff) do { _Pragma("unroll") for (int _i = 0; _i < 2; ++_i) \
;         __builtin_amdgcn_global_load_lds((const unsigned*)((const char*)(gbase) + (voff)[_i]), (PG8_LAS unsigned*)(lds + (bufoff) + ldsw + _i * 8192), 16, 0, 0); } while (0)
; #define PG8_LDA(dst, b, h) do { _Pragma("unroll") for (int m = 0; m < 4; ++m) _Pragma("unroll") for (int k = 0; k < 2; ++k) dst[m][k] = *(const PG8_LAS bf16x8*)(lds + PG8_SA(b, h) + aoff + m * 2048 + k * 1024); } while (0)
; #define PG8_MMA(ai, bj, At, Bt) do { __builtin_amdgcn_s_setprio(1); _Pragma("unroll") for (int m = 0; m < 4; ++m) _Pragma("unroll") for (int n = 0; n < 2; ++n) _Pragma("unroll") for (int k = 0; k < 2; ++k) \
;         acc[ai][bj][m][n] = __builtin_amdgcn_mfma_f32_16x16x32_bf16(Bt[n][k], At[m][k], acc[ai][bj][m][n], 0, 0, 0); __builtin_amdgcn_s_setprio(0); } while (0)
; #define PG8_WAIT_V(n) asm volatile("s_waitcnt vmcnt(" #n ")" ::: "memory")
; #define PG8_WAIT_L(n) asm volatile("s_waitcnt lgkmcnt(" #n ")" ::: "memory")
; #define PG8_BAR __builtin_amdgcn_s_barrier()
; #define PG8_SCHED __builtin_amdgcn_sched_barrier(0)
; template <class Epi, class Sched, bool ALIGN_EPI = false, bool SP2 = false>
; __device__ __forceinline__ void gemm_phase(PG8_LAS unsigned char* lds, const Gemm g, const Sched& S, const Epi& E) {
;     ...
;             PG8_LDA(At, 1, 1); PG8_STAGE(PG8_SB(1, 0), b3, voffB); PG8_STAGE(PG8_SB(1, 1), b3 + hstep, voffB); PG8_STAGE(PG8_SA(1, 0), a3, voffA);
;             PG8_WAIT_V(8); PG8_WAIT_L(0); PG8_BAR; PG8_MMA(1, 0, At, B0); PG8_MMA(1, 1, At, B1); PG8_BAR; PG8_SCHED;
;     ...
;         if constexpr (ALIGN_EPI) { if (wr == 0) PG8_BAR; }
	v_mfma_f32_16x16x32_bf16 v[64:67], v[194:197], v[226:229], v[64:67]
	s_setprio 0
	s_mov_b32 m0, s89
	v_lshl_add_u64 v[230:231], v[230:231], 0, s[12:13]
	ds_read_b128 v[198:201], v164 offset:49152
	ds_read_b128 v[202:205], v164 offset:50176
	ds_read_b128 v[206:209], v164 offset:51200
	ds_read_b128 v[210:213], v164 offset:52224
	ds_read_b128 v[214:217], v164 offset:53248
	ds_read_b128 v[218:221], v164 offset:54272
	ds_read_b128 v[222:225], v164 offset:55296
	ds_read_b128 v[226:229], v164 offset:56320
	global_load_lds_dwordx4 v[230:231], off
	s_add_i32 m0, s89, 0x2000
	s_add_u32 s52, s74, 0x200080
	v_lshl_add_u64 v[230:231], v[232:233], 0, s[12:13]
	s_addc_u32 s53, s75, 0
	s_add_i32 s56, s88, s3
	global_load_lds_dwordx4 v[230:231], off
	v_lshl_add_u64 v[230:231], s[52:53], 0, v[138:139]
	s_mov_b32 m0, s56
	s_nop 0
	global_load_lds_dwordx4 v[230:231], off
	v_lshl_add_u64 v[230:231], s[52:53], 0, v[142:143]
	s_add_i32 m0, s56, 0x2000
	s_nop 0
	global_load_lds_dwordx4 v[230:231], off
	v_lshl_add_u64 v[230:231], v[234:235], 0, s[12:13]
	s_mov_b32 m0, s71
	s_nop 0
	global_load_lds_dwordx4 v[230:231], off
	v_lshl_add_u64 v[230:231], v[236:237], 0, s[12:13]
	s_mov_b32 m0, s78
	s_nop 0
	global_load_lds_dwordx4 v[230:231], off
	s_waitcnt vmcnt(8)
	s_waitcnt lgkmcnt(0)
	s_barrier
	s_setprio 1
	v_mfma_f32_16x16x32_bf16 v[60:63], v[166:169], v[198:201], v[60:63]
	v_mfma_f32_16x16x32_bf16 v[56:59], v[174:177], v[198:201], v[56:59]
	v_mfma_f32_16x16x32_bf16 v[52:55], v[166:169], v[206:209], v[52:55]
	v_mfma_f32_16x16x32_bf16 v[44:47], v[174:177], v[206:209], v[44:47]
	v_mfma_f32_16x16x32_bf16 v[36:39], v[166:169], v[214:217], v[36:39]
	v_mfma_f32_16x16x32_bf16 v[28:31], v[174:177], v[214:217], v[28:31]
	v_mfma_f32_16x16x32_bf16 v[20:23], v[166:169], v[222:225], v[20:23]
	v_mfma_f32_16x16x32_bf16 v[12:15], v[174:177], v[222:225], v[12:15]
	v_mfma_f32_16x16x32_bf16 v[60:63], v[170:173], v[202:205], v[60:63]
	v_mfma_f32_16x16x32_bf16 v[56:59], v[178:181], v[202:205], v[56:59]
	v_mfma_f32_16x16x32_bf16 v[52:55], v[170:173], v[210:213], v[52:55]
	v_mfma_f32_16x16x32_bf16 v[44:47], v[178:181], v[210:213], v[44:47]
	v_mfma_f32_16x16x32_bf16 v[36:39], v[170:173], v[218:221], v[36:39]
	v_mfma_f32_16x16x32_bf16 v[28:31], v[178:181], v[218:221], v[28:31]
	v_mfma_f32_16x16x32_bf16 v[20:23], v[170:173], v[226:229], v[20:23]
	v_mfma_f32_16x16x32_bf16 v[12:15], v[178:181], v[226:229], v[12:15]
	s_setprio 0
	s_setprio 1
	v_mfma_f32_16x16x32_bf16 v[48:51], v[182:185], v[198:201], v[48:51]
	v_mfma_f32_16x16x32_bf16 v[40:43], v[190:193], v[198:201], v[40:43]
	v_mfma_f32_16x16x32_bf16 v[32:35], v[182:185], v[206:209], v[32:35]
	v_mfma_f32_16x16x32_bf16 v[24:27], v[190:193], v[206:209], v[24:27]
	v_mfma_f32_16x16x32_bf16 v[16:19], v[182:185], v[214:217], v[16:19]
	v_mfma_f32_16x16x32_bf16 v[8:11], v[190:193], v[214:217], v[8:11]
	v_mfma_f32_16x16x32_bf16 v[4:7], v[182:185], v[222:225], v[4:7]
	v_mfma_f32_16x16x32_bf16 v[0:3], v[190:193], v[222:225], v[0:3]
	v_mfma_f32_16x16x32_bf16 v[48:51], v[186:189], v[202:205], v[48:51]
	v_mfma_f32_16x16x32_bf16 v[40:43], v[194:197], v[202:205], v[40:43]
	v_mfma_f32_16x16x32_bf16 v[32:35], v[186:189], v[210:213], v[32:35]
	v_mfma_f32_16x16x32_bf16 v[24:27], v[194:197], v[210:213], v[24:27]
	v_mfma_f32_16x16x32_bf16 v[16:19], v[186:189], v[218:221], v[16:19]
	v_mfma_f32_16x16x32_bf16 v[8:11], v[194:197], v[218:221], v[8:11]
	v_mfma_f32_16x16x32_bf16 v[4:7], v[186:189], v[226:229], v[4:7]
	s_barrier
	v_mfma_f32_16x16x32_bf16 v[0:3], v[194:197], v[226:229], v[0:3]
	s_setprio 0
	s_add_i32 s49, s49, 2
	s_add_u32 s72, s72, 0x100
	s_addc_u32 s73, s73, 0
	s_add_u32 s37, s37, 0x100
	s_addc_u32 s41, s41, 0
	s_cmp_gt_u32 s49, 29
	s_cbranch_scc0 .LBB0_660
	s_and_b64 vcc, exec, s[14:15]
	s_cbranch_vccz .LBB0_663
	s_barrier

; #define PG8_STAGE(bufoff, gbase, voff) do { _Pragma("unroll") for (int _i = 0; _i < 2; ++_i) \
;         __builtin_amdgcn_global_load_lds((const unsigned*)((const char*)(gbase) + (voff)[_i]), (PG8_LAS unsigned*)(lds + (bufoff) + ldsw + _i * 8192), 16, 0, 0); } while (0)
; #define PG8_LDA(dst, b, h) do { _Pragma("unroll") for (int m = 0; m < 4; ++m) _Pragma("unroll") for (int k = 0; k < 2; ++k) dst[m][k] = *(const PG8_LAS bf16x8*)(lds + PG8_SA(b, h) + aoff + m * 2048 + k * 1024); } while (0)
; #define PG8_LDB(dst, b, h) do { _Pragma("unroll") for (int n = 0; n < 2; ++n) _Pragma("unroll") for (int k = 0; k < 2; ++k) dst[n][k] = *(const PG8_LAS bf16x8*)(lds + PG8_SB(b, h) + boff + n * 2048 + k * 1024); } while (0)
; #define PG8_MMA(ai, bj, At, Bt) do { __builtin_amdgcn_s_setprio(1); _Pragma("unroll") for (int m = 0; m < 4; ++m) _Pragma("unroll") for (int n = 0; n < 2; ++n) _Pragma("unroll") for (int k = 0; k < 2; ++k) \
;         acc[ai][bj][m][n] = __builtin_amdgcn_mfma_f32_16x16x32_bf16(Bt[n][k], At[m][k], acc[ai][bj][m][n], 0, 0, 0); __builtin_amdgcn_s_setprio(0); } while (0)
; #define PG8_WAIT_V(n) asm volatile("s_waitcnt vmcnt(" #n ")" ::: "memory")
; #define PG8_WAIT_L(n) asm volatile("s_waitcnt lgkmcnt(" #n ")" ::: "memory")
; #define PG8_BAR __builtin_amdgcn_s_barrier()
; #define PG8_SCHED __builtin_amdgcn_sched_barrier(0)
; template <class Epi, class Sched, bool ALIGN_EPI = false, bool SP2 = false>
; __device__ __forceinline__ void gemm_phase(PG8_LAS unsigned char* lds, const Gemm g, const Sched& S, const Epi& E) {
;     ...
;             const char* a1 = cA + (size_t)(t + 1) * kstep;
;             const char* a2 = last ? nA : cA + (size_t)(t + 2) * kstep; const char* b2 = last ? nB : cB + (size_t)(t + 2) * kstep;
;             const char* a3 = a2 + kstep; const char* b3 = b2 + kstep;
;             if constexpr (SP2) {
;             PG8_LDB(B0, 0, 0); PG8_LDB(B1, 0, 1); PG8_SCHED; PG8_LDA(At, 0, 0); PG8_STAGE(PG8_SA(1, 1), a1 + hstep, voffA);
;             PG8_WAIT_V(8); PG8_WAIT_L(0); PG8_BAR; PG8_MMA(0, 0, At, B0); PG8_MMA(0, 1, At, B1); PG8_BAR; PG8_SCHED;
;             PG8_LDA(At, 0, 1); PG8_STAGE(PG8_SB(0, 0), b2, voffB); PG8_STAGE(PG8_SB(0, 1), b2 + hstep, voffB); PG8_STAGE(PG8_SA(0, 0), a2, voffA);
;             PG8_WAIT_V(8); PG8_WAIT_L(0); PG8_BAR; PG8_MMA(1, 0, At, B0); PG8_MMA(1, 1, At, B1); PG8_BAR; PG8_SCHED;
.LBB0_809:
	ds_read_b128 v[128:131], v180
	ds_read_b128 v[132:135], v180 offset:1024
	ds_read_b128 v[136:139], v180 offset:2048
	ds_read_b128 v[140:143], v180 offset:3072
	ds_read_b128 v[160:163], v181
	ds_read_b128 v[164:167], v181 offset:1024
	ds_read_b128 v[184:187], v181 offset:2048
	ds_read_b128 v[188:191], v181 offset:3072
	s_add_u32 s52, s72, 0xfff80080
	s_addc_u32 s53, s73, -1
	s_cmp_eq_u32 s92, 28
	s_cselect_b32 s77, s5, s53
	s_cselect_b32 s76, s49, s52
	s_cselect_b32 s75, s45, s91
	s_cselect_b32 s74, s89, s90
	v_lshl_add_u64 v[168:169], s[72:73], 0, v[154:155]
	s_add_i32 m0, s71, 0xc000
	ds_read_b128 v[192:195], v182
	ds_read_b128 v[196:199], v182 offset:1024
	ds_read_b128 v[200:203], v182 offset:2048
	ds_read_b128 v[204:207], v182 offset:3072
	ds_read_b128 v[208:211], v182 offset:4096
	ds_read_b128 v[212:215], v182 offset:5120
	ds_read_b128 v[216:219], v182 offset:6144
	ds_read_b128 v[220:223], v182 offset:7168
	global_load_lds_dwordx4 v[168:169], off
	v_lshl_add_u64 v[168:169], s[72:73], 0, v[156:157]
	s_add_i32 m0, s71, 0xe000
	s_nop 0
	global_load_lds_dwordx4 v[168:169], off
	s_waitcnt vmcnt(8)
	s_waitcnt lgkmcnt(0)
	s_barrier
	s_setprio 1
	v_mfma_f32_16x16x32_bf16 v[124:127], v[128:131], v[192:195], v[124:127]
	v_mfma_f32_16x16x32_bf16 v[120:123], v[136:139], v[192:195], v[120:123]
	v_mfma_f32_16x16x32_bf16 v[108:111], v[128:131], v[200:203], v[108:111]
	v_mfma_f32_16x16x32_bf16 v[104:107], v[136:139], v[200:203], v[104:107]
	v_mfma_f32_16x16x32_bf16 v[92:95], v[128:131], v[208:211], v[92:95]
	v_mfma_f32_16x16x32_bf16 v[88:91], v[136:139], v[208:211], v[88:91]
	v_mfma_f32_16x16x32_bf16 v[76:79], v[128:131], v[216:219], v[76:79]
	v_mfma_f32_16x16x32_bf16 v[72:75], v[136:139], v[216:219], v[72:75]
	v_mfma_f32_16x16x32_bf16 v[124:127], v[132:135], v[196:199], v[124:127]
	v_mfma_f32_16x16x32_bf16 v[120:123], v[140:143], v[196:199], v[120:123]
	v_mfma_f32_16x16x32_bf16 v[108:111], v[132:135], v[204:207], v[108:111]
	v_mfma_f32_16x16x32_bf16 v[104:107], v[140:143], v[204:207], v[104:107]
	v_mfma_f32_16x16x32_bf16 v[92:95], v[132:135], v[212:215], v[92:95]
	v_mfma_f32_16x16x32_bf16 v[88:91], v[140:143], v[212:215], v[88:91]
	v_mfma_f32_16x16x32_bf16 v[76:79], v[132:135], v[220:223], v[76:79]
	v_mfma_f32_16x16x32_bf16 v[72:75], v[140:143], v[220:223], v[72:75]
	s_setprio 0
	s_setprio 1
	v_mfma_f32_16x16x32_bf16 v[116:119], v[160:163], v[192:195], v[116:119]
	v_mfma_f32_16x16x32_bf16 v[112:115], v[184:187], v[192:195], v[112:115]
	v_mfma_f32_16x16x32_bf16 v[100:103], v[160:163], v[200:203], v[100:103]
	v_mfma_f32_16x16x32_bf16 v[96:99], v[184:187], v[200:203], v[96:99]
	v_mfma_f32_16x16x32_bf16 v[84:87], v[160:163], v[208:211], v[84:87]
	v_mfma_f32_16x16x32_bf16 v[80:83], v[184:187], v[208:211], v[80:83]
	v_mfma_f32_16x16x32_bf16 v[68:71], v[160:163], v[216:219], v[68:71]
	v_mfma_f32_16x16x32_bf16 v[64:67], v[184:187], v[216:219], v[64:67]
	v_mfma_f32_16x16x32_bf16 v[116:119], v[164:167], v[196:199], v[116:119]
	v_mfma_f32_16x16x32_bf16 v[112:115], v[188:191], v[196:199], v[112:115]
	v_mfma_f32_16x16x32_bf16 v[100:103], v[164:167], v[204:207], v[100:103]
	v_mfma_f32_16x16x32_bf16 v[96:99], v[188:191], v[204:207], v[96:99]
	v_mfma_f32_16x16x32_bf16 v[84:87], v[164:167], v[212:215], v[84:87]
	v_mfma_f32_16x16x32_bf16 v[80:83], v[188:191], v[212:215], v[80:83]
	v_mfma_f32_16x16x32_bf16 v[68:71], v[164:167], v[220:223], v[68:71]
	s_barrier
	v_mfma_f32_16x16x32_bf16 v[64:67], v[188:191], v[220:223], v[64:67]
	s_setprio 0
	s_add_i32 s52, s83, s78
	v_lshl_add_u64 v[168:169], s[74:75], 0, v[148:149]
	s_mov_b32 m0, s52
	ds_read_b128 v[192:195], v182 offset:16384
	ds_read_b128 v[196:199], v182 offset:17408
	ds_read_b128 v[200:203], v182 offset:18432
	ds_read_b128 v[204:207], v182 offset:19456
	ds_read_b128 v[208:211], v182 offset:20480
	ds_read_b128 v[212:215], v182 offset:21504
	ds_read_b128 v[216:219], v182 offset:22528
	ds_read_b128 v[220:223], v182 offset:23552
	global_load_lds_dwordx4 v[168:169], off
	s_add_i32 m0, s52, 0x2000
	s_add_u32 s52, s74, 0x80000
	v_lshl_add_u64 v[224:225], s[74:75], 0, v[152:153]
	s_addc_u32 s53, s75, 0
	s_add_i32 s56, s84, s78
	global_load_lds_dwordx4 v[224:225], off
	v_lshl_add_u64 v[226:227], s[52:53], 0, v[148:149]
	s_mov_b32 m0, s56
	v_lshl_add_u64 v[228:229], s[76:77], 0, v[150:151]
	global_load_lds_dwordx4 v[226:227], off
	v_lshl_add_u64 v[226:227], s[52:53], 0, v[152:153]
	s_add_i32 m0, s56, 0x2000
	s_nop 0
	global_load_lds_dwordx4 v[226:227], off
	v_lshl_add_u64 v[226:227], s[76:77], 0, v[144:145]
	s_mov_b32 m0, s71
	s_nop 0
	global_load_lds_dwordx4 v[226:227], off
	s_mov_b32 m0, s79
	s_nop 0
	global_load_lds_dwordx4 v[228:229], off
	s_waitcnt vmcnt(8)
	s_waitcnt lgkmcnt(0)
	s_barrier
; #define PG8_STAGE(bufoff, gbase, voff) do { _Pragma("unroll") for (int _i = 0; _i < 2; ++_i) \
;         __builtin_amdgcn_global_load_lds((const unsigned*)((const char*)(gbase) + (voff)[_i]), (PG8_LAS unsigned*)(lds + (bufoff) + ldsw + _i * 8192), 16, 0, 0); } while (0)
; #define PG8_LDA(dst, b, h) do { _Pragma("unroll") for (int m = 0; m < 4; ++m) _Pragma("unroll") for (int k = 0; k < 2; ++k) dst[m][k] = *(const PG8_LAS bf16x8*)(lds + PG8_SA(b, h) + aoff + m * 2048 + k * 1024); } while (0)
; #define PG8_LDB(dst, b, h) do { _Pragma("unroll") for (int n = 0; n < 2; ++n) _Pragma("unroll") for (int k = 0; k < 2; ++k) dst[n][k] = *(const PG8_LAS bf16x8*)(lds + PG8_SB(b, h) + boff + n * 2048 + k * 1024); } while (0)
; #define PG8_MMA(ai, bj, At, Bt) do { __builtin_amdgcn_s_setprio(1); _Pragma("unroll") for (int m = 0; m < 4; ++m) _Pragma("unroll") for (int n = 0; n < 2; ++n) _Pragma("unroll") for (int k = 0; k < 2; ++k) \
;         acc[ai][bj][m][n] = __builtin_amdgcn_mfma_f32_16x16x32_bf16(Bt[n][k], At[m][k], acc[ai][bj][m][n], 0, 0, 0); __builtin_amdgcn_s_setprio(0); } while (0)
; #define PG8_WAIT_V(n) asm volatile("s_waitcnt vmcnt(" #n ")" ::: "memory")
; #define PG8_WAIT_L(n) asm volatile("s_waitcnt lgkmcnt(" #n ")" ::: "memory")
; #define PG8_BAR __builtin_amdgcn_s_barrier()
; #define PG8_SCHED __builtin_amdgcn_sched_barrier(0)
; template <class Epi, class Sched, bool ALIGN_EPI = false, bool SP2 = false>
; __device__ __forceinline__ void gemm_phase(PG8_LAS unsigned char* lds, const Gemm g, const Sched& S, const Epi& E) {
;     ...
;             PG8_WAIT_V(8); PG8_WAIT_L(0); PG8_BAR; PG8_MMA(1, 0, At, B0); PG8_MMA(1, 1, At, B1); PG8_BAR; PG8_SCHED;
;             PG8_LDB(B0, 1, 0); PG8_LDB(B1, 1, 1); PG8_SCHED; PG8_LDA(At, 1, 0); PG8_STAGE(PG8_SA(0, 1), a2 + hstep, voffA);
;             PG8_WAIT_V(8); PG8_WAIT_L(0); PG8_BAR; PG8_MMA(0, 0, At, B0); PG8_MMA(0, 1, At, B1); PG8_BAR; PG8_SCHED;
	s_setprio 1
	v_mfma_f32_16x16x32_bf16 v[60:63], v[128:131], v[192:195], v[60:63]
	v_mfma_f32_16x16x32_bf16 v[56:59], v[136:139], v[192:195], v[56:59]
	v_mfma_f32_16x16x32_bf16 v[44:47], v[128:131], v[200:203], v[44:47]
	v_mfma_f32_16x16x32_bf16 v[40:43], v[136:139], v[200:203], v[40:43]
	v_mfma_f32_16x16x32_bf16 v[28:31], v[128:131], v[208:211], v[28:31]
	v_mfma_f32_16x16x32_bf16 v[24:27], v[136:139], v[208:211], v[24:27]
	v_mfma_f32_16x16x32_bf16 v[12:15], v[128:131], v[216:219], v[12:15]
	v_mfma_f32_16x16x32_bf16 v[8:11], v[136:139], v[216:219], v[8:11]
	v_mfma_f32_16x16x32_bf16 v[60:63], v[132:135], v[196:199], v[60:63]
	v_mfma_f32_16x16x32_bf16 v[56:59], v[140:143], v[196:199], v[56:59]
	v_mfma_f32_16x16x32_bf16 v[44:47], v[132:135], v[204:207], v[44:47]
	v_mfma_f32_16x16x32_bf16 v[40:43], v[140:143], v[204:207], v[40:43]
	v_mfma_f32_16x16x32_bf16 v[28:31], v[132:135], v[212:215], v[28:31]
	v_mfma_f32_16x16x32_bf16 v[24:27], v[140:143], v[212:215], v[24:27]
	v_mfma_f32_16x16x32_bf16 v[12:15], v[132:135], v[220:223], v[12:15]
	v_mfma_f32_16x16x32_bf16 v[8:11], v[140:143], v[220:223], v[8:11]
	s_setprio 0
	s_setprio 1
	v_mfma_f32_16x16x32_bf16 v[52:55], v[160:163], v[192:195], v[52:55]
	v_mfma_f32_16x16x32_bf16 v[48:51], v[184:187], v[192:195], v[48:51]
	v_mfma_f32_16x16x32_bf16 v[36:39], v[160:163], v[200:203], v[36:39]
	v_mfma_f32_16x16x32_bf16 v[32:35], v[184:187], v[200:203], v[32:35]
	v_mfma_f32_16x16x32_bf16 v[20:23], v[160:163], v[208:211], v[20:23]
	v_mfma_f32_16x16x32_bf16 v[16:19], v[184:187], v[208:211], v[16:19]
	v_mfma_f32_16x16x32_bf16 v[4:7], v[160:163], v[216:219], v[4:7]
	v_mfma_f32_16x16x32_bf16 v[0:3], v[184:187], v[216:219], v[0:3]
	v_mfma_f32_16x16x32_bf16 v[52:55], v[164:167], v[196:199], v[52:55]
	v_mfma_f32_16x16x32_bf16 v[48:51], v[188:191], v[196:199], v[48:51]
	v_mfma_f32_16x16x32_bf16 v[36:39], v[164:167], v[204:207], v[36:39]
	v_mfma_f32_16x16x32_bf16 v[32:35], v[188:191], v[204:207], v[32:35]
	v_mfma_f32_16x16x32_bf16 v[20:23], v[164:167], v[212:215], v[20:23]
	v_mfma_f32_16x16x32_bf16 v[16:19], v[188:191], v[212:215], v[16:19]
	v_mfma_f32_16x16x32_bf16 v[4:7], v[164:167], v[220:223], v[4:7]
	s_barrier
	v_mfma_f32_16x16x32_bf16 v[0:3], v[188:191], v[220:223], v[0:3]
	s_setprio 0
	s_add_i32 s56, 0, 0x18000
	s_add_i32 s57, 0, 0x1c000
	v_add_u32_e32 v140, s56, v171
	v_add_u32_e32 v188, s57, v171
	ds_read_b128 v[128:131], v140
	ds_read_b128 v[132:135], v140 offset:1024
	ds_read_b128 v[136:139], v140 offset:2048
	ds_read_b128 v[140:143], v140 offset:3072
	ds_read_b128 v[160:163], v188
	ds_read_b128 v[164:167], v188 offset:1024
	ds_read_b128 v[184:187], v188 offset:2048
	ds_read_b128 v[188:191], v188 offset:3072
	s_add_u32 s52, s76, 0x80000
	s_addc_u32 s53, s77, 0
	s_mov_b32 m0, s80
	v_lshl_add_u64 v[230:231], s[52:53], 0, v[144:145]
	ds_read_b128 v[192:195], v182 offset:32768
	ds_read_b128 v[196:199], v182 offset:33792
	ds_read_b128 v[200:203], v182 offset:34816
	ds_read_b128 v[204:207], v182 offset:35840
	ds_read_b128 v[208:211], v182 offset:36864
	ds_read_b128 v[212:215], v182 offset:37888
	ds_read_b128 v[216:219], v182 offset:38912
	ds_read_b128 v[220:223], v182 offset:39936
	global_load_lds_dwordx4 v[230:231], off
	v_lshl_add_u64 v[230:231], s[52:53], 0, v[150:151]
	s_mov_b32 m0, s81
	s_nop 0
	global_load_lds_dwordx4 v[230:231], off
	s_waitcnt vmcnt(8)
	s_waitcnt lgkmcnt(0)
	s_barrier
	s_setprio 1
	v_mfma_f32_16x16x32_bf16 v[124:127], v[128:131], v[192:195], v[124:127]
	v_mfma_f32_16x16x32_bf16 v[120:123], v[136:139], v[192:195], v[120:123]
	v_mfma_f32_16x16x32_bf16 v[108:111], v[128:131], v[200:203], v[108:111]
	v_mfma_f32_16x16x32_bf16 v[104:107], v[136:139], v[200:203], v[104:107]
	v_mfma_f32_16x16x32_bf16 v[92:95], v[128:131], v[208:211], v[92:95]
	v_mfma_f32_16x16x32_bf16 v[88:91], v[136:139], v[208:211], v[88:91]
	v_mfma_f32_16x16x32_bf16 v[76:79], v[128:131], v[216:219], v[76:79]
	v_mfma_f32_16x16x32_bf16 v[72:75], v[136:139], v[216:219], v[72:75]
	v_mfma_f32_16x16x32_bf16 v[124:127], v[132:135], v[196:199], v[124:127]
	v_mfma_f32_16x16x32_bf16 v[120:123], v[140:143], v[196:199], v[120:123]
	v_mfma_f32_16x16x32_bf16 v[108:111], v[132:135], v[204:207], v[108:111]
	v_mfma_f32_16x16x32_bf16 v[104:107], v[140:143], v[204:207], v[104:107]
	v_mfma_f32_16x16x32_bf16 v[92:95], v[132:135], v[212:215], v[92:95]
	v_mfma_f32_16x16x32_bf16 v[88:91], v[140:143], v[212:215], v[88:91]
	v_mfma_f32_16x16x32_bf16 v[76:79], v[132:135], v[220:223], v[76:79]
	v_mfma_f32_16x16x32_bf16 v[72:75], v[140:143], v[220:223], v[72:75]
	s_setprio 0
	s_setprio 1
	v_mfma_f32_16x16x32_bf16 v[116:119], v[160:163], v[192:195], v[116:119]
	v_mfma_f32_16x16x32_bf16 v[112:115], v[184:187], v[192:195], v[112:115]
	v_mfma_f32_16x16x32_bf16 v[100:103], v[160:163], v[200:203], v[100:103]
	v_mfma_f32_16x16x32_bf16 v[96:99], v[184:187], v[200:203], v[96:99]
	v_mfma_f32_16x16x32_bf16 v[84:87], v[160:163], v[208:211], v[84:87]
	v_mfma_f32_16x16x32_bf16 v[80:83], v[184:187], v[208:211], v[80:83]
	v_mfma_f32_16x16x32_bf16 v[68:71], v[160:163], v[216:219], v[68:71]
	v_mfma_f32_16x16x32_bf16 v[64:67], v[184:187], v[216:219], v[64:67]
	v_mfma_f32_16x16x32_bf16 v[116:119], v[164:167], v[196:199], v[116:119]
	v_mfma_f32_16x16x32_bf16 v[112:115], v[188:191], v[196:199], v[112:115]
	v_mfma_f32_16x16x32_bf16 v[100:103], v[164:167], v[204:207], v[100:103]
	v_mfma_f32_16x16x32_bf16 v[96:99], v[188:191], v[204:207], v[96:99]
	v_mfma_f32_16x16x32_bf16 v[84:87], v[164:167], v[212:215], v[84:87]
	v_mfma_f32_16x16x32_bf16 v[80:83], v[188:191], v[212:215], v[80:83]
	v_mfma_f32_16x16x32_bf16 v[68:71], v[164:167], v[220:223], v[68:71]
	s_barrier
; #define PG8_STAGE(bufoff, gbase, voff) do { _Pragma("unroll") for (int _i = 0; _i < 2; ++_i) \
;         __builtin_amdgcn_global_load_lds((const unsigned*)((const char*)(gbase) + (voff)[_i]), (PG8_LAS unsigned*)(lds + (bufoff) + ldsw + _i * 8192), 16, 0, 0); } while (0)
; #define PG8_LDA(dst, b, h) do { _Pragma("unroll") for (int m = 0; m < 4; ++m) _Pragma("unroll") for (int k = 0; k < 2; ++k) dst[m][k] = *(const PG8_LAS bf16x8*)(lds + PG8_SA(b, h) + aoff + m * 2048 + k * 1024); } while (0)
; #define PG8_MMA(ai, bj, At, Bt) do { __builtin_amdgcn_s_setprio(1); _Pragma("unroll") for (int m = 0; m < 4; ++m) _Pragma("unroll") for (int n = 0; n < 2; ++n) _Pragma("unroll") for (int k = 0; k < 2; ++k) \
;         acc[ai][bj][m][n] = __builtin_amdgcn_mfma_f32_16x16x32_bf16(Bt[n][k], At[m][k], acc[ai][bj][m][n], 0, 0, 0); __builtin_amdgcn_s_setprio(0); } while (0)
; #define PG8_WAIT_V(n) asm volatile("s_waitcnt vmcnt(" #n ")" ::: "memory")
; #define PG8_WAIT_L(n) asm volatile("s_waitcnt lgkmcnt(" #n ")" ::: "memory")
; #define PG8_BAR __builtin_amdgcn_s_barrier()
; #define PG8_SCHED __builtin_amdgcn_sched_barrier(0)
; template <class Epi, class Sched, bool ALIGN_EPI = false, bool SP2 = false>
; __device__ __forceinline__ void gemm_phase(PG8_LAS unsigned char* lds, const Gemm g, const Sched& S, const Epi& E) {
;     ...
;             PG8_LDA(At, 1, 1); PG8_STAGE(PG8_SB(1, 0), b3, voffB); PG8_STAGE(PG8_SB(1, 1), b3 + hstep, voffB); PG8_STAGE(PG8_SA(1, 0), a3, voffA);
;             PG8_WAIT_V(8); PG8_WAIT_L(0); PG8_BAR; PG8_MMA(1, 0, At, B0); PG8_MMA(1, 1, At, B1); PG8_BAR; PG8_SCHED;
;     ...
;         if constexpr (ALIGN_EPI) { if (wr == 0) PG8_BAR; }
	v_mfma_f32_16x16x32_bf16 v[64:67], v[188:191], v[220:223], v[64:67]
	s_setprio 0
	s_add_i32 s52, s56, s78
	v_lshl_add_u64 v[168:169], v[168:169], 0, s[40:41]
	s_mov_b32 m0, s52
	ds_read_b128 v[192:195], v182 offset:49152
	ds_read_b128 v[196:199], v182 offset:50176
	ds_read_b128 v[200:203], v182 offset:51200
	ds_read_b128 v[204:207], v182 offset:52224
	ds_read_b128 v[208:211], v182 offset:53248
	ds_read_b128 v[212:215], v182 offset:54272
	ds_read_b128 v[216:219], v182 offset:55296
	ds_read_b128 v[220:223], v182 offset:56320
	global_load_lds_dwordx4 v[168:169], off
	s_add_i32 m0, s52, 0x2000
	s_add_u32 s52, s74, 0x80080
	v_lshl_add_u64 v[168:169], v[224:225], 0, s[40:41]
	s_addc_u32 s53, s75, 0
	s_add_i32 s56, s57, s78
	global_load_lds_dwordx4 v[168:169], off
	v_lshl_add_u64 v[168:169], s[52:53], 0, v[148:149]
	s_mov_b32 m0, s56
	s_nop 0
	global_load_lds_dwordx4 v[168:169], off
	v_lshl_add_u64 v[168:169], s[52:53], 0, v[152:153]
	s_add_i32 m0, s56, 0x2000
	s_nop 0
	global_load_lds_dwordx4 v[168:169], off
	v_lshl_add_u64 v[168:169], v[226:227], 0, s[40:41]
	s_mov_b32 m0, s3
	s_nop 0
	global_load_lds_dwordx4 v[168:169], off
	v_lshl_add_u64 v[168:169], v[228:229], 0, s[40:41]
	s_mov_b32 m0, s28
	s_nop 0
	global_load_lds_dwordx4 v[168:169], off
	s_waitcnt vmcnt(8)
	s_waitcnt lgkmcnt(0)
	s_barrier
	s_setprio 1
	v_mfma_f32_16x16x32_bf16 v[60:63], v[128:131], v[192:195], v[60:63]
	v_mfma_f32_16x16x32_bf16 v[56:59], v[136:139], v[192:195], v[56:59]
	v_mfma_f32_16x16x32_bf16 v[44:47], v[128:131], v[200:203], v[44:47]
	v_mfma_f32_16x16x32_bf16 v[40:43], v[136:139], v[200:203], v[40:43]
	v_mfma_f32_16x16x32_bf16 v[28:31], v[128:131], v[208:211], v[28:31]
	v_mfma_f32_16x16x32_bf16 v[24:27], v[136:139], v[208:211], v[24:27]
	v_mfma_f32_16x16x32_bf16 v[12:15], v[128:131], v[216:219], v[12:15]
	v_mfma_f32_16x16x32_bf16 v[8:11], v[136:139], v[216:219], v[8:11]
	v_mfma_f32_16x16x32_bf16 v[60:63], v[132:135], v[196:199], v[60:63]
	v_mfma_f32_16x16x32_bf16 v[56:59], v[140:143], v[196:199], v[56:59]
	v_mfma_f32_16x16x32_bf16 v[44:47], v[132:135], v[204:207], v[44:47]
	v_mfma_f32_16x16x32_bf16 v[40:43], v[140:143], v[204:207], v[40:43]
	v_mfma_f32_16x16x32_bf16 v[28:31], v[132:135], v[212:215], v[28:31]
	v_mfma_f32_16x16x32_bf16 v[24:27], v[140:143], v[212:215], v[24:27]
	v_mfma_f32_16x16x32_bf16 v[12:15], v[132:135], v[220:223], v[12:15]
	v_mfma_f32_16x16x32_bf16 v[8:11], v[140:143], v[220:223], v[8:11]
	s_setprio 0
	s_setprio 1
	v_mfma_f32_16x16x32_bf16 v[52:55], v[160:163], v[192:195], v[52:55]
	v_mfma_f32_16x16x32_bf16 v[48:51], v[184:187], v[192:195], v[48:51]
	v_mfma_f32_16x16x32_bf16 v[36:39], v[160:163], v[200:203], v[36:39]
	v_mfma_f32_16x16x32_bf16 v[32:35], v[184:187], v[200:203], v[32:35]
	v_mfma_f32_16x16x32_bf16 v[20:23], v[160:163], v[208:211], v[20:23]
	v_mfma_f32_16x16x32_bf16 v[16:19], v[184:187], v[208:211], v[16:19]
	v_mfma_f32_16x16x32_bf16 v[4:7], v[160:163], v[216:219], v[4:7]
	v_mfma_f32_16x16x32_bf16 v[0:3], v[184:187], v[216:219], v[0:3]
	v_mfma_f32_16x16x32_bf16 v[52:55], v[164:167], v[196:199], v[52:55]
	v_mfma_f32_16x16x32_bf16 v[48:51], v[188:191], v[196:199], v[48:51]
	v_mfma_f32_16x16x32_bf16 v[36:39], v[164:167], v[204:207], v[36:39]
	v_mfma_f32_16x16x32_bf16 v[32:35], v[188:191], v[204:207], v[32:35]
	v_mfma_f32_16x16x32_bf16 v[20:23], v[164:167], v[212:215], v[20:23]
	v_mfma_f32_16x16x32_bf16 v[16:19], v[188:191], v[212:215], v[16:19]
	v_mfma_f32_16x16x32_bf16 v[4:7], v[164:167], v[220:223], v[4:7]
	s_barrier
	v_mfma_f32_16x16x32_bf16 v[0:3], v[188:191], v[220:223], v[0:3]
	s_setprio 0
	s_add_i32 s92, s92, 2
	s_add_u32 s72, s72, 0x100
	s_addc_u32 s73, s73, 0
	s_add_u32 s90, s90, 0x100
	s_addc_u32 s91, s91, 0
	s_cmp_gt_u32 s92, 29
	s_cbranch_scc0 .LBB0_809
	s_and_b64 vcc, exec, s[42:43]
	s_cbranch_vccz .LBB0_812
	s_barrier

; #define PG8_STAGE(bufoff, gbase, voff) do { _Pragma("unroll") for (int _i = 0; _i < 2; ++_i) \
;         __builtin_amdgcn_global_load_lds((const unsigned*)((const char*)(gbase) + (voff)[_i]), (PG8_LAS unsigned*)(lds + (bufoff) + ldsw + _i * 8192), 16, 0, 0); } while (0)
; #define PG8_LDA(dst, b, h) do { _Pragma("unroll") for (int m = 0; m < 4; ++m) _Pragma("unroll") for (int k = 0; k < 2; ++k) dst[m][k] = *(const PG8_LAS bf16x8*)(lds + PG8_SA(b, h) + aoff + m * 2048 + k * 1024); } while (0)
; #define PG8_LDB(dst, b, h) do { _Pragma("unroll") for (int n = 0; n < 2; ++n) _Pragma("unroll") for (int k = 0; k < 2; ++k) dst[n][k] = *(const PG8_LAS bf16x8*)(lds + PG8_SB(b, h) + boff + n * 2048 + k * 1024); } while (0)
; #define PG8_MMA(ai, bj, At, Bt) do { __builtin_amdgcn_s_setprio(1); _Pragma("unroll") for (int m = 0; m < 4; ++m) _Pragma("unroll") for (int n = 0; n < 2; ++n) _Pragma("unroll") for (int k = 0; k < 2; ++k) \
;         acc[ai][bj][m][n] = __builtin_amdgcn_mfma_f32_16x16x32_bf16(Bt[n][k], At[m][k], acc[ai][bj][m][n], 0, 0, 0); __builtin_amdgcn_s_setprio(0); } while (0)
; #define PG8_WAIT_V(n) asm volatile("s_waitcnt vmcnt(" #n ")" ::: "memory")
; #define PG8_WAIT_L(n) asm volatile("s_waitcnt lgkmcnt(" #n ")" ::: "memory")
; #define PG8_BAR __builtin_amdgcn_s_barrier()
; #define PG8_SCHED __builtin_amdgcn_sched_barrier(0)
; template <class Epi, class Sched, bool ALIGN_EPI = false, bool SP2 = false>
; __device__ __forceinline__ void gemm_phase(PG8_LAS unsigned char* lds, const Gemm g, const Sched& S, const Epi& E) {
;     ...
;             const char* a1 = cA + (size_t)(t + 1) * kstep;
;             const char* a2 = last ? nA : cA + (size_t)(t + 2) * kstep; const char* b2 = last ? nB : cB + (size_t)(t + 2) * kstep;
;             const char* a3 = a2 + kstep; const char* b3 = b2 + kstep;
;             if constexpr (SP2) {
;             PG8_LDB(B0, 0, 0); PG8_LDB(B1, 0, 1); PG8_SCHED; PG8_LDA(At, 0, 0); PG8_STAGE(PG8_SA(1, 1), a1 + hstep, voffA);
;             PG8_WAIT_V(8); PG8_WAIT_L(0); PG8_BAR; PG8_MMA(0, 0, At, B0); PG8_MMA(0, 1, At, B1); PG8_BAR; PG8_SCHED;
;             PG8_LDA(At, 0, 1); PG8_STAGE(PG8_SB(0, 0), b2, voffB); PG8_STAGE(PG8_SB(0, 1), b2 + hstep, voffB); PG8_STAGE(PG8_SA(0, 0), a2, voffA);
;             PG8_WAIT_V(8); PG8_WAIT_L(0); PG8_BAR; PG8_MMA(1, 0, At, B0); PG8_MMA(1, 1, At, B1); PG8_BAR; PG8_SCHED;
.LBB0_1051:
	ds_read_b128 v[128:131], v205
	ds_read_b128 v[132:135], v205 offset:1024
	ds_read_b128 v[154:157], v205 offset:2048
	ds_read_b128 v[158:161], v205 offset:3072
	ds_read_b128 v[162:165], v206
	ds_read_b128 v[166:169], v206 offset:1024
	ds_read_b128 v[170:173], v206 offset:2048
	ds_read_b128 v[174:177], v206 offset:3072
	s_add_u32 s54, s52, 0xfff80080
	s_addc_u32 s55, s53, -1
	s_cmp_eq_u32 s77, 28
	s_cselect_b32 s57, s43, s55
	s_cselect_b32 s56, s49, s54
	s_cselect_b32 s55, s37, s76
	s_cselect_b32 s54, s51, s75
	v_lshl_add_u64 v[218:219], s[52:53], 0, v[144:145]
	s_add_i32 m0, s61, 0xc000
	ds_read_b128 v[178:181], v207
	ds_read_b128 v[182:185], v207 offset:1024
	ds_read_b128 v[186:189], v207 offset:2048
	ds_read_b128 v[190:193], v207 offset:3072
	ds_read_b128 v[194:197], v207 offset:4096
	ds_read_b128 v[198:201], v207 offset:5120
	ds_read_b128 v[210:213], v207 offset:6144
	ds_read_b128 v[214:217], v207 offset:7168
	global_load_lds_dwordx4 v[218:219], off
	v_lshl_add_u64 v[218:219], s[52:53], 0, v[148:149]
	s_add_i32 m0, s61, 0xe000
	s_nop 0
	global_load_lds_dwordx4 v[218:219], off
	s_waitcnt vmcnt(8)
	s_waitcnt lgkmcnt(0)
	s_barrier
	s_setprio 1
	v_mfma_f32_16x16x32_bf16 v[124:127], v[128:131], v[178:181], v[124:127]
	v_mfma_f32_16x16x32_bf16 v[120:123], v[154:157], v[178:181], v[120:123]
	v_mfma_f32_16x16x32_bf16 v[116:119], v[128:131], v[186:189], v[116:119]
	v_mfma_f32_16x16x32_bf16 v[112:115], v[154:157], v[186:189], v[112:115]
	v_mfma_f32_16x16x32_bf16 v[108:111], v[128:131], v[194:197], v[108:111]
	v_mfma_f32_16x16x32_bf16 v[104:107], v[154:157], v[194:197], v[104:107]
	v_mfma_f32_16x16x32_bf16 v[100:103], v[128:131], v[210:213], v[100:103]
	v_mfma_f32_16x16x32_bf16 v[96:99], v[154:157], v[210:213], v[96:99]
	v_mfma_f32_16x16x32_bf16 v[124:127], v[132:135], v[182:185], v[124:127]
	v_mfma_f32_16x16x32_bf16 v[120:123], v[158:161], v[182:185], v[120:123]
	v_mfma_f32_16x16x32_bf16 v[116:119], v[132:135], v[190:193], v[116:119]
	v_mfma_f32_16x16x32_bf16 v[112:115], v[158:161], v[190:193], v[112:115]
	v_mfma_f32_16x16x32_bf16 v[108:111], v[132:135], v[198:201], v[108:111]
	v_mfma_f32_16x16x32_bf16 v[104:107], v[158:161], v[198:201], v[104:107]
	v_mfma_f32_16x16x32_bf16 v[100:103], v[132:135], v[214:217], v[100:103]
	v_mfma_f32_16x16x32_bf16 v[96:99], v[158:161], v[214:217], v[96:99]
	s_setprio 0
	s_setprio 1
	v_mfma_f32_16x16x32_bf16 v[60:63], v[162:165], v[178:181], v[60:63]
	v_mfma_f32_16x16x32_bf16 v[56:59], v[170:173], v[178:181], v[56:59]
	v_mfma_f32_16x16x32_bf16 v[52:55], v[162:165], v[186:189], v[52:55]
	v_mfma_f32_16x16x32_bf16 v[48:51], v[170:173], v[186:189], v[48:51]
	v_mfma_f32_16x16x32_bf16 v[44:47], v[162:165], v[194:197], v[44:47]
	v_mfma_f32_16x16x32_bf16 v[40:43], v[170:173], v[194:197], v[40:43]
	v_mfma_f32_16x16x32_bf16 v[36:39], v[162:165], v[210:213], v[36:39]
	v_mfma_f32_16x16x32_bf16 v[32:35], v[170:173], v[210:213], v[32:35]
	v_mfma_f32_16x16x32_bf16 v[60:63], v[166:169], v[182:185], v[60:63]
	v_mfma_f32_16x16x32_bf16 v[56:59], v[174:177], v[182:185], v[56:59]
	v_mfma_f32_16x16x32_bf16 v[52:55], v[166:169], v[190:193], v[52:55]
	v_mfma_f32_16x16x32_bf16 v[48:51], v[174:177], v[190:193], v[48:51]
	v_mfma_f32_16x16x32_bf16 v[44:47], v[166:169], v[198:201], v[44:47]
	v_mfma_f32_16x16x32_bf16 v[40:43], v[174:177], v[198:201], v[40:43]
	v_mfma_f32_16x16x32_bf16 v[36:39], v[166:169], v[214:217], v[36:39]
	s_barrier
	v_mfma_f32_16x16x32_bf16 v[32:35], v[174:177], v[214:217], v[32:35]
	s_setprio 0
	s_add_i32 s78, s33, s60
	v_lshl_add_u64 v[218:219], s[54:55], 0, v[138:139]
	s_mov_b32 m0, s78
	ds_read_b128 v[178:181], v207 offset:16384
	ds_read_b128 v[182:185], v207 offset:17408
	ds_read_b128 v[186:189], v207 offset:18432
	ds_read_b128 v[190:193], v207 offset:19456
	ds_read_b128 v[194:197], v207 offset:20480
	ds_read_b128 v[198:201], v207 offset:21504
	ds_read_b128 v[210:213], v207 offset:22528
	ds_read_b128 v[214:217], v207 offset:23552
	global_load_lds_dwordx4 v[218:219], off
	s_add_i32 m0, s78, 0x2000
	s_add_u32 s78, s54, 0x80000
	v_lshl_add_u64 v[220:221], s[54:55], 0, v[142:143]
	s_addc_u32 s79, s55, 0
	s_add_i32 s80, s74, s60
	global_load_lds_dwordx4 v[220:221], off
	v_lshl_add_u64 v[222:223], s[78:79], 0, v[138:139]
	s_mov_b32 m0, s80
	v_lshl_add_u64 v[224:225], s[56:57], 0, v[140:141]
	global_load_lds_dwordx4 v[222:223], off
	v_lshl_add_u64 v[222:223], s[78:79], 0, v[142:143]
	s_add_i32 m0, s80, 0x2000
	s_nop 0
	global_load_lds_dwordx4 v[222:223], off
	v_lshl_add_u64 v[222:223], s[56:57], 0, v[136:137]
	s_mov_b32 m0, s61
	s_nop 0
	global_load_lds_dwordx4 v[222:223], off
	s_mov_b32 m0, s62
	s_nop 0
	global_load_lds_dwordx4 v[224:225], off
	s_waitcnt vmcnt(8)
	s_waitcnt lgkmcnt(0)
	s_barrier
; #define PG8_STAGE(bufoff, gbase, voff) do { _Pragma("unroll") for (int _i = 0; _i < 2; ++_i) \
;         __builtin_amdgcn_global_load_lds((const unsigned*)((const char*)(gbase) + (voff)[_i]), (PG8_LAS unsigned*)(lds + (bufoff) + ldsw + _i * 8192), 16, 0, 0); } while (0)
; #define PG8_LDA(dst, b, h) do { _Pragma("unroll") for (int m = 0; m < 4; ++m) _Pragma("unroll") for (int k = 0; k < 2; ++k) dst[m][k] = *(const PG8_LAS bf16x8*)(lds + PG8_SA(b, h) + aoff + m * 2048 + k * 1024); } while (0)
; #define PG8_LDB(dst, b, h) do { _Pragma("unroll") for (int n = 0; n < 2; ++n) _Pragma("unroll") for (int k = 0; k < 2; ++k) dst[n][k] = *(const PG8_LAS bf16x8*)(lds + PG8_SB(b, h) + boff + n * 2048 + k * 1024); } while (0)
; #define PG8_MMA(ai, bj, At, Bt) do { __builtin_amdgcn_s_setprio(1); _Pragma("unroll") for (int m = 0; m < 4; ++m) _Pragma("unroll") for (int n = 0; n < 2; ++n) _Pragma("unroll") for (int k = 0; k < 2; ++k) \
;         acc[ai][bj][m][n] = __builtin_amdgcn_mfma_f32_16x16x32_bf16(Bt[n][k], At[m][k], acc[ai][bj][m][n], 0, 0, 0); __builtin_amdgcn_s_setprio(0); } while (0)
; #define PG8_WAIT_V(n) asm volatile("s_waitcnt vmcnt(" #n ")" ::: "memory")
; #define PG8_WAIT_L(n) asm volatile("s_waitcnt lgkmcnt(" #n ")" ::: "memory")
; #define PG8_BAR __builtin_amdgcn_s_barrier()
; #define PG8_SCHED __builtin_amdgcn_sched_barrier(0)
; template <class Epi, class Sched, bool ALIGN_EPI = false, bool SP2 = false>
; __device__ __forceinline__ void gemm_phase(PG8_LAS unsigned char* lds, const Gemm g, const Sched& S, const Epi& E) {
;     ...
;             PG8_WAIT_V(8); PG8_WAIT_L(0); PG8_BAR; PG8_MMA(1, 0, At, B0); PG8_MMA(1, 1, At, B1); PG8_BAR; PG8_SCHED;
;             PG8_LDB(B0, 1, 0); PG8_LDB(B1, 1, 1); PG8_SCHED; PG8_LDA(At, 1, 0); PG8_STAGE(PG8_SA(0, 1), a2 + hstep, voffA);
;             PG8_WAIT_V(8); PG8_WAIT_L(0); PG8_BAR; PG8_MMA(0, 0, At, B0); PG8_MMA(0, 1, At, B1); PG8_BAR; PG8_SCHED;
	s_setprio 1
	v_mfma_f32_16x16x32_bf16 v[92:95], v[128:131], v[178:181], v[92:95]
	v_mfma_f32_16x16x32_bf16 v[88:91], v[154:157], v[178:181], v[88:91]
	v_mfma_f32_16x16x32_bf16 v[84:87], v[128:131], v[186:189], v[84:87]
	v_mfma_f32_16x16x32_bf16 v[80:83], v[154:157], v[186:189], v[80:83]
	v_mfma_f32_16x16x32_bf16 v[76:79], v[128:131], v[194:197], v[76:79]
	v_mfma_f32_16x16x32_bf16 v[72:75], v[154:157], v[194:197], v[72:75]
	v_mfma_f32_16x16x32_bf16 v[68:71], v[128:131], v[210:213], v[68:71]
	v_mfma_f32_16x16x32_bf16 v[64:67], v[154:157], v[210:213], v[64:67]
	v_mfma_f32_16x16x32_bf16 v[92:95], v[132:135], v[182:185], v[92:95]
	v_mfma_f32_16x16x32_bf16 v[88:91], v[158:161], v[182:185], v[88:91]
	v_mfma_f32_16x16x32_bf16 v[84:87], v[132:135], v[190:193], v[84:87]
	v_mfma_f32_16x16x32_bf16 v[80:83], v[158:161], v[190:193], v[80:83]
	v_mfma_f32_16x16x32_bf16 v[76:79], v[132:135], v[198:201], v[76:79]
	v_mfma_f32_16x16x32_bf16 v[72:75], v[158:161], v[198:201], v[72:75]
	v_mfma_f32_16x16x32_bf16 v[68:71], v[132:135], v[214:217], v[68:71]
	v_mfma_f32_16x16x32_bf16 v[64:67], v[158:161], v[214:217], v[64:67]
	s_setprio 0
	s_setprio 1
	v_mfma_f32_16x16x32_bf16 v[28:31], v[162:165], v[178:181], v[28:31]
	v_mfma_f32_16x16x32_bf16 v[24:27], v[170:173], v[178:181], v[24:27]
	v_mfma_f32_16x16x32_bf16 v[20:23], v[162:165], v[186:189], v[20:23]
	v_mfma_f32_16x16x32_bf16 v[16:19], v[170:173], v[186:189], v[16:19]
	v_mfma_f32_16x16x32_bf16 v[12:15], v[162:165], v[194:197], v[12:15]
	v_mfma_f32_16x16x32_bf16 v[8:11], v[170:173], v[194:197], v[8:11]
	v_mfma_f32_16x16x32_bf16 v[4:7], v[162:165], v[210:213], v[4:7]
	v_mfma_f32_16x16x32_bf16 v[0:3], v[170:173], v[210:213], v[0:3]
	v_mfma_f32_16x16x32_bf16 v[28:31], v[166:169], v[182:185], v[28:31]
	v_mfma_f32_16x16x32_bf16 v[24:27], v[174:177], v[182:185], v[24:27]
	v_mfma_f32_16x16x32_bf16 v[20:23], v[166:169], v[190:193], v[20:23]
	v_mfma_f32_16x16x32_bf16 v[16:19], v[174:177], v[190:193], v[16:19]
	v_mfma_f32_16x16x32_bf16 v[12:15], v[166:169], v[198:201], v[12:15]
	v_mfma_f32_16x16x32_bf16 v[8:11], v[174:177], v[198:201], v[8:11]
	v_mfma_f32_16x16x32_bf16 v[4:7], v[166:169], v[214:217], v[4:7]
	s_barrier
	v_mfma_f32_16x16x32_bf16 v[0:3], v[174:177], v[214:217], v[0:3]
	s_setprio 0
	s_add_i32 s78, 0, 0x18000
	s_add_i32 s79, 0, 0x1c000
	v_add_u32_e32 v158, s78, v203
	v_add_u32_e32 v174, s79, v203
	ds_read_b128 v[128:131], v158
	ds_read_b128 v[132:135], v158 offset:1024
	ds_read_b128 v[154:157], v158 offset:2048
	ds_read_b128 v[158:161], v158 offset:3072
	ds_read_b128 v[162:165], v174
	ds_read_b128 v[166:169], v174 offset:1024
	ds_read_b128 v[170:173], v174 offset:2048
	ds_read_b128 v[174:177], v174 offset:3072
	s_add_u32 s56, s56, 0x80000
	s_addc_u32 s57, s57, 0
	s_mov_b32 m0, s63
	v_lshl_add_u64 v[226:227], s[56:57], 0, v[136:137]
	ds_read_b128 v[178:181], v207 offset:32768
	ds_read_b128 v[182:185], v207 offset:33792
	ds_read_b128 v[186:189], v207 offset:34816
	ds_read_b128 v[190:193], v207 offset:35840
	ds_read_b128 v[194:197], v207 offset:36864
	ds_read_b128 v[198:201], v207 offset:37888
	ds_read_b128 v[210:213], v207 offset:38912
	ds_read_b128 v[214:217], v207 offset:39936
	global_load_lds_dwordx4 v[226:227], off
	v_lshl_add_u64 v[226:227], s[56:57], 0, v[140:141]
	s_mov_b32 m0, s64
	s_nop 0
	global_load_lds_dwordx4 v[226:227], off
	s_waitcnt vmcnt(8)
	s_waitcnt lgkmcnt(0)
	s_barrier
	s_setprio 1
	v_mfma_f32_16x16x32_bf16 v[124:127], v[128:131], v[178:181], v[124:127]
	v_mfma_f32_16x16x32_bf16 v[120:123], v[154:157], v[178:181], v[120:123]
	v_mfma_f32_16x16x32_bf16 v[116:119], v[128:131], v[186:189], v[116:119]
	v_mfma_f32_16x16x32_bf16 v[112:115], v[154:157], v[186:189], v[112:115]
	v_mfma_f32_16x16x32_bf16 v[108:111], v[128:131], v[194:197], v[108:111]
	v_mfma_f32_16x16x32_bf16 v[104:107], v[154:157], v[194:197], v[104:107]
	v_mfma_f32_16x16x32_bf16 v[100:103], v[128:131], v[210:213], v[100:103]
	v_mfma_f32_16x16x32_bf16 v[96:99], v[154:157], v[210:213], v[96:99]
	v_mfma_f32_16x16x32_bf16 v[124:127], v[132:135], v[182:185], v[124:127]
	v_mfma_f32_16x16x32_bf16 v[120:123], v[158:161], v[182:185], v[120:123]
	v_mfma_f32_16x16x32_bf16 v[116:119], v[132:135], v[190:193], v[116:119]
	v_mfma_f32_16x16x32_bf16 v[112:115], v[158:161], v[190:193], v[112:115]
	v_mfma_f32_16x16x32_bf16 v[108:111], v[132:135], v[198:201], v[108:111]
	v_mfma_f32_16x16x32_bf16 v[104:107], v[158:161], v[198:201], v[104:107]
	v_mfma_f32_16x16x32_bf16 v[100:103], v[132:135], v[214:217], v[100:103]
	v_mfma_f32_16x16x32_bf16 v[96:99], v[158:161], v[214:217], v[96:99]
	s_setprio 0
	s_setprio 1
	v_mfma_f32_16x16x32_bf16 v[60:63], v[162:165], v[178:181], v[60:63]
	v_mfma_f32_16x16x32_bf16 v[56:59], v[170:173], v[178:181], v[56:59]
	v_mfma_f32_16x16x32_bf16 v[52:55], v[162:165], v[186:189], v[52:55]
	v_mfma_f32_16x16x32_bf16 v[48:51], v[170:173], v[186:189], v[48:51]
	v_mfma_f32_16x16x32_bf16 v[44:47], v[162:165], v[194:197], v[44:47]
	v_mfma_f32_16x16x32_bf16 v[40:43], v[170:173], v[194:197], v[40:43]
	v_mfma_f32_16x16x32_bf16 v[36:39], v[162:165], v[210:213], v[36:39]
	v_mfma_f32_16x16x32_bf16 v[32:35], v[170:173], v[210:213], v[32:35]
	v_mfma_f32_16x16x32_bf16 v[60:63], v[166:169], v[182:185], v[60:63]
	v_mfma_f32_16x16x32_bf16 v[56:59], v[174:177], v[182:185], v[56:59]
	v_mfma_f32_16x16x32_bf16 v[52:55], v[166:169], v[190:193], v[52:55]
	v_mfma_f32_16x16x32_bf16 v[48:51], v[174:177], v[190:193], v[48:51]
	v_mfma_f32_16x16x32_bf16 v[44:47], v[166:169], v[198:201], v[44:47]
	v_mfma_f32_16x16x32_bf16 v[40:43], v[174:177], v[198:201], v[40:43]
	v_mfma_f32_16x16x32_bf16 v[36:39], v[166:169], v[214:217], v[36:39]
	s_barrier
; #define PG8_STAGE(bufoff, gbase, voff) do { _Pragma("unroll") for (int _i = 0; _i < 2; ++_i) \
;         __builtin_amdgcn_global_load_lds((const unsigned*)((const char*)(gbase) + (voff)[_i]), (PG8_LAS unsigned*)(lds + (bufoff) + ldsw + _i * 8192), 16, 0, 0); } while (0)
; #define PG8_LDA(dst, b, h) do { _Pragma("unroll") for (int m = 0; m < 4; ++m) _Pragma("unroll") for (int k = 0; k < 2; ++k) dst[m][k] = *(const PG8_LAS bf16x8*)(lds + PG8_SA(b, h) + aoff + m * 2048 + k * 1024); } while (0)
; #define PG8_MMA(ai, bj, At, Bt) do { __builtin_amdgcn_s_setprio(1); _Pragma("unroll") for (int m = 0; m < 4; ++m) _Pragma("unroll") for (int n = 0; n < 2; ++n) _Pragma("unroll") for (int k = 0; k < 2; ++k) \
;         acc[ai][bj][m][n] = __builtin_amdgcn_mfma_f32_16x16x32_bf16(Bt[n][k], At[m][k], acc[ai][bj][m][n], 0, 0, 0); __builtin_amdgcn_s_setprio(0); } while (0)
; #define PG8_WAIT_V(n) asm volatile("s_waitcnt vmcnt(" #n ")" ::: "memory")
; #define PG8_WAIT_L(n) asm volatile("s_waitcnt lgkmcnt(" #n ")" ::: "memory")
; #define PG8_BAR __builtin_amdgcn_s_barrier()
; #define PG8_SCHED __builtin_amdgcn_sched_barrier(0)
; template <class Epi, class Sched, bool ALIGN_EPI = false, bool SP2 = false>
; __device__ __forceinline__ void gemm_phase(PG8_LAS unsigned char* lds, const Gemm g, const Sched& S, const Epi& E) {
;     ...
;             PG8_LDA(At, 1, 1); PG8_STAGE(PG8_SB(1, 0), b3, voffB); PG8_STAGE(PG8_SB(1, 1), b3 + hstep, voffB); PG8_STAGE(PG8_SA(1, 0), a3, voffA);
;             PG8_WAIT_V(8); PG8_WAIT_L(0); PG8_BAR; PG8_MMA(1, 0, At, B0); PG8_MMA(1, 1, At, B1); PG8_BAR; PG8_SCHED;
;     ...
;         if constexpr (ALIGN_EPI) { if (wr == 0) PG8_BAR; }
	v_mfma_f32_16x16x32_bf16 v[32:35], v[174:177], v[214:217], v[32:35]
	s_setprio 0
	s_add_i32 s56, s78, s60
	v_lshl_add_u64 v[218:219], v[218:219], 0, s[12:13]
	s_mov_b32 m0, s56
	ds_read_b128 v[178:181], v207 offset:49152
	ds_read_b128 v[182:185], v207 offset:50176
	ds_read_b128 v[186:189], v207 offset:51200
	ds_read_b128 v[190:193], v207 offset:52224
	ds_read_b128 v[194:197], v207 offset:53248
	ds_read_b128 v[198:201], v207 offset:54272
	ds_read_b128 v[210:213], v207 offset:55296
	ds_read_b128 v[214:217], v207 offset:56320
	global_load_lds_dwordx4 v[218:219], off
	s_add_i32 m0, s56, 0x2000
	s_add_u32 s54, s54, 0x80080
	v_lshl_add_u64 v[218:219], v[220:221], 0, s[12:13]
	s_addc_u32 s55, s55, 0
	s_add_i32 s56, s79, s60
	global_load_lds_dwordx4 v[218:219], off
	v_lshl_add_u64 v[218:219], s[54:55], 0, v[138:139]
	s_mov_b32 m0, s56
	s_nop 0
	global_load_lds_dwordx4 v[218:219], off
	v_lshl_add_u64 v[218:219], s[54:55], 0, v[142:143]
	s_add_i32 m0, s56, 0x2000
	s_nop 0
	global_load_lds_dwordx4 v[218:219], off
	v_lshl_add_u64 v[218:219], v[222:223], 0, s[12:13]
	s_mov_b32 m0, s70
	s_nop 0
	global_load_lds_dwordx4 v[218:219], off
	v_lshl_add_u64 v[218:219], v[224:225], 0, s[12:13]
	s_mov_b32 m0, s71
	s_nop 0
	global_load_lds_dwordx4 v[218:219], off
	s_waitcnt vmcnt(8)
	s_waitcnt lgkmcnt(0)
	s_barrier
	s_setprio 1
	v_mfma_f32_16x16x32_bf16 v[92:95], v[128:131], v[178:181], v[92:95]
	v_mfma_f32_16x16x32_bf16 v[88:91], v[154:157], v[178:181], v[88:91]
	v_mfma_f32_16x16x32_bf16 v[84:87], v[128:131], v[186:189], v[84:87]
	v_mfma_f32_16x16x32_bf16 v[80:83], v[154:157], v[186:189], v[80:83]
	v_mfma_f32_16x16x32_bf16 v[76:79], v[128:131], v[194:197], v[76:79]
	v_mfma_f32_16x16x32_bf16 v[72:75], v[154:157], v[194:197], v[72:75]
	v_mfma_f32_16x16x32_bf16 v[68:71], v[128:131], v[210:213], v[68:71]
	v_mfma_f32_16x16x32_bf16 v[64:67], v[154:157], v[210:213], v[64:67]
	v_mfma_f32_16x16x32_bf16 v[92:95], v[132:135], v[182:185], v[92:95]
	v_mfma_f32_16x16x32_bf16 v[88:91], v[158:161], v[182:185], v[88:91]
	v_mfma_f32_16x16x32_bf16 v[84:87], v[132:135], v[190:193], v[84:87]
	v_mfma_f32_16x16x32_bf16 v[80:83], v[158:161], v[190:193], v[80:83]
	v_mfma_f32_16x16x32_bf16 v[76:79], v[132:135], v[198:201], v[76:79]
	v_mfma_f32_16x16x32_bf16 v[72:75], v[158:161], v[198:201], v[72:75]
	v_mfma_f32_16x16x32_bf16 v[68:71], v[132:135], v[214:217], v[68:71]
	v_mfma_f32_16x16x32_bf16 v[64:67], v[158:161], v[214:217], v[64:67]
	s_setprio 0
	s_setprio 1
	v_mfma_f32_16x16x32_bf16 v[28:31], v[162:165], v[178:181], v[28:31]
	v_mfma_f32_16x16x32_bf16 v[24:27], v[170:173], v[178:181], v[24:27]
	v_mfma_f32_16x16x32_bf16 v[20:23], v[162:165], v[186:189], v[20:23]
	v_mfma_f32_16x16x32_bf16 v[16:19], v[170:173], v[186:189], v[16:19]
	v_mfma_f32_16x16x32_bf16 v[12:15], v[162:165], v[194:197], v[12:15]
	v_mfma_f32_16x16x32_bf16 v[8:11], v[170:173], v[194:197], v[8:11]
	v_mfma_f32_16x16x32_bf16 v[4:7], v[162:165], v[210:213], v[4:7]
	v_mfma_f32_16x16x32_bf16 v[0:3], v[170:173], v[210:213], v[0:3]
	v_mfma_f32_16x16x32_bf16 v[28:31], v[166:169], v[182:185], v[28:31]
	v_mfma_f32_16x16x32_bf16 v[24:27], v[174:177], v[182:185], v[24:27]
	v_mfma_f32_16x16x32_bf16 v[20:23], v[166:169], v[190:193], v[20:23]
	v_mfma_f32_16x16x32_bf16 v[16:19], v[174:177], v[190:193], v[16:19]
	v_mfma_f32_16x16x32_bf16 v[12:15], v[166:169], v[198:201], v[12:15]
	v_mfma_f32_16x16x32_bf16 v[8:11], v[174:177], v[198:201], v[8:11]
	v_mfma_f32_16x16x32_bf16 v[4:7], v[166:169], v[214:217], v[4:7]
	s_barrier
	v_mfma_f32_16x16x32_bf16 v[0:3], v[174:177], v[214:217], v[0:3]
	s_setprio 0
	s_add_i32 s77, s77, 2
	s_add_u32 s52, s52, 0x100
	s_addc_u32 s53, s53, 0
	s_add_u32 s75, s75, 0x100
	s_addc_u32 s76, s76, 0
	s_cmp_gt_u32 s77, 29
	s_cbranch_scc0 .LBB0_1051
	s_and_b64 vcc, exec, s[14:15]
	s_cbranch_vccz .LBB0_1054
	s_barrier

; #define PG8_STAGE(bufoff, gbase, voff) do { _Pragma("unroll") for (int _i = 0; _i < 2; ++_i) \
;         __builtin_amdgcn_global_load_lds((const unsigned*)((const char*)(gbase) + (voff)[_i]), (PG8_LAS unsigned*)(lds + (bufoff) + ldsw + _i * 8192), 16, 0, 0); } while (0)
; #define PG8_LDA(dst, b, h) do { _Pragma("unroll") for (int m = 0; m < 4; ++m) _Pragma("unroll") for (int k = 0; k < 2; ++k) dst[m][k] = *(const PG8_LAS bf16x8*)(lds + PG8_SA(b, h) + aoff + m * 2048 + k * 1024); } while (0)
; #define PG8_LDB(dst, b, h) do { _Pragma("unroll") for (int n = 0; n < 2; ++n) _Pragma("unroll") for (int k = 0; k < 2; ++k) dst[n][k] = *(const PG8_LAS bf16x8*)(lds + PG8_SB(b, h) + boff + n * 2048 + k * 1024); } while (0)
; #define PG8_MMA(ai, bj, At, Bt) do { __builtin_amdgcn_s_setprio(1); _Pragma("unroll") for (int m = 0; m < 4; ++m) _Pragma("unroll") for (int n = 0; n < 2; ++n) _Pragma("unroll") for (int k = 0; k < 2; ++k) \
;         acc[ai][bj][m][n] = __builtin_amdgcn_mfma_f32_16x16x32_bf16(Bt[n][k], At[m][k], acc[ai][bj][m][n], 0, 0, 0); __builtin_amdgcn_s_setprio(0); } while (0)
; #define PG8_WAIT_V(n) asm volatile("s_waitcnt vmcnt(" #n ")" ::: "memory")
; #define PG8_WAIT_L(n) asm volatile("s_waitcnt lgkmcnt(" #n ")" ::: "memory")
; #define PG8_BAR __builtin_amdgcn_s_barrier()
; #define PG8_SCHED __builtin_amdgcn_sched_barrier(0)
; template <class Epi, class Sched, bool ALIGN_EPI = false, bool SP2 = false>
; __device__ __forceinline__ void gemm_phase(PG8_LAS unsigned char* lds, const Gemm g, const Sched& S, const Epi& E) {
;     ...
;             const char* a1 = cA + (size_t)(t + 1) * kstep;
;             const char* a2 = last ? nA : cA + (size_t)(t + 2) * kstep; const char* b2 = last ? nB : cB + (size_t)(t + 2) * kstep;
;             const char* a3 = a2 + kstep; const char* b3 = b2 + kstep;
;             if constexpr (SP2) {
;             PG8_LDB(B0, 0, 0); PG8_LDB(B1, 0, 1); PG8_SCHED; PG8_LDA(At, 0, 0); PG8_STAGE(PG8_SA(1, 1), a1 + hstep, voffA);
;             PG8_WAIT_V(8); PG8_WAIT_L(0); PG8_BAR; PG8_MMA(0, 0, At, B0); PG8_MMA(0, 1, At, B1); PG8_BAR; PG8_SCHED;
;             PG8_LDA(At, 0, 1); PG8_STAGE(PG8_SB(0, 0), b2, voffB); PG8_STAGE(PG8_SB(0, 1), b2 + hstep, voffB); PG8_STAGE(PG8_SA(0, 0), a2, voffA);
;             PG8_WAIT_V(8); PG8_WAIT_L(0); PG8_BAR; PG8_MMA(1, 0, At, B0); PG8_MMA(1, 1, At, B1); PG8_BAR; PG8_SCHED;
.LBB0_1142:
	ds_read_b128 v[80:83], v171
	ds_read_b128 v[84:87], v171 offset:1024
	ds_read_b128 v[88:91], v171 offset:2048
	ds_read_b128 v[92:95], v171 offset:3072
	ds_read_b128 v[164:167], v172
	ds_read_b128 v[176:179], v172 offset:1024
	ds_read_b128 v[180:183], v172 offset:2048
	ds_read_b128 v[184:187], v172 offset:3072
	s_add_u32 s44, s42, 0xfff80080
	s_addc_u32 s45, s43, -1
	s_cmp_eq_u32 s64, 28
	s_cselect_b32 s47, s15, s45
	s_cselect_b32 s46, s60, s44
	s_cselect_b32 s45, s13, s63
	s_cselect_b32 s44, s61, s62
	v_lshl_add_u64 v[220:221], s[42:43], 0, v[156:157]
	s_add_i32 m0, s41, 0xc000
	ds_read_b128 v[188:191], v173
	ds_read_b128 v[192:195], v173 offset:1024
	ds_read_b128 v[196:199], v173 offset:2048
	ds_read_b128 v[200:203], v173 offset:3072
	ds_read_b128 v[204:207], v173 offset:4096
	ds_read_b128 v[208:211], v173 offset:5120
	ds_read_b128 v[212:215], v173 offset:6144
	ds_read_b128 v[216:219], v173 offset:7168
	global_load_lds_dwordx4 v[220:221], off
	v_lshl_add_u64 v[220:221], s[42:43], 0, v[158:159]
	s_add_i32 m0, s41, 0xe000
	s_nop 0
	global_load_lds_dwordx4 v[220:221], off
	s_waitcnt vmcnt(8)
	s_waitcnt lgkmcnt(0)
	s_barrier
	s_setprio 1
	v_mfma_f32_16x16x32_bf16 v[140:143], v[80:83], v[188:191], v[140:143]
	v_mfma_f32_16x16x32_bf16 v[136:139], v[88:91], v[188:191], v[136:139]
	v_mfma_f32_16x16x32_bf16 v[124:127], v[80:83], v[196:199], v[124:127]
	v_mfma_f32_16x16x32_bf16 v[120:123], v[88:91], v[196:199], v[120:123]
	v_mfma_f32_16x16x32_bf16 v[108:111], v[80:83], v[204:207], v[108:111]
	v_mfma_f32_16x16x32_bf16 v[104:107], v[88:91], v[204:207], v[104:107]
	v_mfma_f32_16x16x32_bf16 v[76:79], v[80:83], v[212:215], v[76:79]
	v_mfma_f32_16x16x32_bf16 v[72:75], v[88:91], v[212:215], v[72:75]
	v_mfma_f32_16x16x32_bf16 v[140:143], v[84:87], v[192:195], v[140:143]
	v_mfma_f32_16x16x32_bf16 v[136:139], v[92:95], v[192:195], v[136:139]
	v_mfma_f32_16x16x32_bf16 v[124:127], v[84:87], v[200:203], v[124:127]
	v_mfma_f32_16x16x32_bf16 v[120:123], v[92:95], v[200:203], v[120:123]
	v_mfma_f32_16x16x32_bf16 v[108:111], v[84:87], v[208:211], v[108:111]
	v_mfma_f32_16x16x32_bf16 v[104:107], v[92:95], v[208:211], v[104:107]
	v_mfma_f32_16x16x32_bf16 v[76:79], v[84:87], v[216:219], v[76:79]
	v_mfma_f32_16x16x32_bf16 v[72:75], v[92:95], v[216:219], v[72:75]
	s_setprio 0
	s_setprio 1
	v_mfma_f32_16x16x32_bf16 v[132:135], v[164:167], v[188:191], v[132:135]
	v_mfma_f32_16x16x32_bf16 v[128:131], v[180:183], v[188:191], v[128:131]
	v_mfma_f32_16x16x32_bf16 v[116:119], v[164:167], v[196:199], v[116:119]
	v_mfma_f32_16x16x32_bf16 v[112:115], v[180:183], v[196:199], v[112:115]
	v_mfma_f32_16x16x32_bf16 v[100:103], v[164:167], v[204:207], v[100:103]
	v_mfma_f32_16x16x32_bf16 v[96:99], v[180:183], v[204:207], v[96:99]
	v_mfma_f32_16x16x32_bf16 v[68:71], v[164:167], v[212:215], v[68:71]
	v_mfma_f32_16x16x32_bf16 v[64:67], v[180:183], v[212:215], v[64:67]
	v_mfma_f32_16x16x32_bf16 v[132:135], v[176:179], v[192:195], v[132:135]
	v_mfma_f32_16x16x32_bf16 v[128:131], v[184:187], v[192:195], v[128:131]
	v_mfma_f32_16x16x32_bf16 v[116:119], v[176:179], v[200:203], v[116:119]
	v_mfma_f32_16x16x32_bf16 v[112:115], v[184:187], v[200:203], v[112:115]
	v_mfma_f32_16x16x32_bf16 v[100:103], v[176:179], v[208:211], v[100:103]
	v_mfma_f32_16x16x32_bf16 v[96:99], v[184:187], v[208:211], v[96:99]
	v_mfma_f32_16x16x32_bf16 v[68:71], v[176:179], v[216:219], v[68:71]
	s_barrier
	v_mfma_f32_16x16x32_bf16 v[64:67], v[184:187], v[216:219], v[64:67]
	s_setprio 0
	s_add_i32 s65, s56, s33
	v_lshl_add_u64 v[220:221], s[44:45], 0, v[148:149]
	s_mov_b32 m0, s65
	ds_read_b128 v[188:191], v173 offset:16384
	ds_read_b128 v[192:195], v173 offset:17408
	ds_read_b128 v[196:199], v173 offset:18432
	ds_read_b128 v[200:203], v173 offset:19456
	ds_read_b128 v[204:207], v173 offset:20480
	ds_read_b128 v[208:211], v173 offset:21504
	ds_read_b128 v[212:215], v173 offset:22528
	ds_read_b128 v[216:219], v173 offset:23552
	global_load_lds_dwordx4 v[220:221], off
	s_add_i32 m0, s65, 0x2000
	s_add_u32 s66, s44, 0x80000
	v_lshl_add_u64 v[222:223], s[44:45], 0, v[152:153]
	s_addc_u32 s67, s45, 0
	s_add_i32 s65, s57, s33
	global_load_lds_dwordx4 v[222:223], off
	v_lshl_add_u64 v[224:225], s[66:67], 0, v[148:149]
	s_mov_b32 m0, s65
	v_lshl_add_u64 v[226:227], s[46:47], 0, v[150:151]
	global_load_lds_dwordx4 v[224:225], off
	v_lshl_add_u64 v[224:225], s[66:67], 0, v[152:153]
	s_add_i32 m0, s65, 0x2000
	s_nop 0
	global_load_lds_dwordx4 v[224:225], off
	v_lshl_add_u64 v[224:225], s[46:47], 0, v[144:145]
	s_mov_b32 m0, s41
	s_nop 0
	global_load_lds_dwordx4 v[224:225], off
	s_mov_b32 m0, s48
	s_nop 0
	global_load_lds_dwordx4 v[226:227], off
	s_waitcnt vmcnt(8)
	s_waitcnt lgkmcnt(0)
	s_barrier
; #define PG8_STAGE(bufoff, gbase, voff) do { _Pragma("unroll") for (int _i = 0; _i < 2; ++_i) \
;         __builtin_amdgcn_global_load_lds((const unsigned*)((const char*)(gbase) + (voff)[_i]), (PG8_LAS unsigned*)(lds + (bufoff) + ldsw + _i * 8192), 16, 0, 0); } while (0)
; #define PG8_LDA(dst, b, h) do { _Pragma("unroll") for (int m = 0; m < 4; ++m) _Pragma("unroll") for (int k = 0; k < 2; ++k) dst[m][k] = *(const PG8_LAS bf16x8*)(lds + PG8_SA(b, h) + aoff + m * 2048 + k * 1024); } while (0)
; #define PG8_LDB(dst, b, h) do { _Pragma("unroll") for (int n = 0; n < 2; ++n) _Pragma("unroll") for (int k = 0; k < 2; ++k) dst[n][k] = *(const PG8_LAS bf16x8*)(lds + PG8_SB(b, h) + boff + n * 2048 + k * 1024); } while (0)
; #define PG8_MMA(ai, bj, At, Bt) do { __builtin_amdgcn_s_setprio(1); _Pragma("unroll") for (int m = 0; m < 4; ++m) _Pragma("unroll") for (int n = 0; n < 2; ++n) _Pragma("unroll") for (int k = 0; k < 2; ++k) \
;         acc[ai][bj][m][n] = __builtin_amdgcn_mfma_f32_16x16x32_bf16(Bt[n][k], At[m][k], acc[ai][bj][m][n], 0, 0, 0); __builtin_amdgcn_s_setprio(0); } while (0)
; #define PG8_WAIT_V(n) asm volatile("s_waitcnt vmcnt(" #n ")" ::: "memory")
; #define PG8_WAIT_L(n) asm volatile("s_waitcnt lgkmcnt(" #n ")" ::: "memory")
; #define PG8_BAR __builtin_amdgcn_s_barrier()
; #define PG8_SCHED __builtin_amdgcn_sched_barrier(0)
; template <class Epi, class Sched, bool ALIGN_EPI = false, bool SP2 = false>
; __device__ __forceinline__ void gemm_phase(PG8_LAS unsigned char* lds, const Gemm g, const Sched& S, const Epi& E) {
;     ...
;             PG8_WAIT_V(8); PG8_WAIT_L(0); PG8_BAR; PG8_MMA(1, 0, At, B0); PG8_MMA(1, 1, At, B1); PG8_BAR; PG8_SCHED;
;             PG8_LDB(B0, 1, 0); PG8_LDB(B1, 1, 1); PG8_SCHED; PG8_LDA(At, 1, 0); PG8_STAGE(PG8_SA(0, 1), a2 + hstep, voffA);
;             PG8_WAIT_V(8); PG8_WAIT_L(0); PG8_BAR; PG8_MMA(0, 0, At, B0); PG8_MMA(0, 1, At, B1); PG8_BAR; PG8_SCHED;
	s_setprio 1
	v_mfma_f32_16x16x32_bf16 v[60:63], v[80:83], v[188:191], v[60:63]
	v_mfma_f32_16x16x32_bf16 v[56:59], v[88:91], v[188:191], v[56:59]
	v_mfma_f32_16x16x32_bf16 v[44:47], v[80:83], v[196:199], v[44:47]
	v_mfma_f32_16x16x32_bf16 v[40:43], v[88:91], v[196:199], v[40:43]
	v_mfma_f32_16x16x32_bf16 v[28:31], v[80:83], v[204:207], v[28:31]
	v_mfma_f32_16x16x32_bf16 v[24:27], v[88:91], v[204:207], v[24:27]
	v_mfma_f32_16x16x32_bf16 v[12:15], v[80:83], v[212:215], v[12:15]
	v_mfma_f32_16x16x32_bf16 v[8:11], v[88:91], v[212:215], v[8:11]
	v_mfma_f32_16x16x32_bf16 v[60:63], v[84:87], v[192:195], v[60:63]
	v_mfma_f32_16x16x32_bf16 v[56:59], v[92:95], v[192:195], v[56:59]
	v_mfma_f32_16x16x32_bf16 v[44:47], v[84:87], v[200:203], v[44:47]
	v_mfma_f32_16x16x32_bf16 v[40:43], v[92:95], v[200:203], v[40:43]
	v_mfma_f32_16x16x32_bf16 v[28:31], v[84:87], v[208:211], v[28:31]
	v_mfma_f32_16x16x32_bf16 v[24:27], v[92:95], v[208:211], v[24:27]
	v_mfma_f32_16x16x32_bf16 v[12:15], v[84:87], v[216:219], v[12:15]
	v_mfma_f32_16x16x32_bf16 v[8:11], v[92:95], v[216:219], v[8:11]
	s_setprio 0
	s_setprio 1
	v_mfma_f32_16x16x32_bf16 v[52:55], v[164:167], v[188:191], v[52:55]
	v_mfma_f32_16x16x32_bf16 v[48:51], v[180:183], v[188:191], v[48:51]
	v_mfma_f32_16x16x32_bf16 v[36:39], v[164:167], v[196:199], v[36:39]
	v_mfma_f32_16x16x32_bf16 v[32:35], v[180:183], v[196:199], v[32:35]
	v_mfma_f32_16x16x32_bf16 v[20:23], v[164:167], v[204:207], v[20:23]
	v_mfma_f32_16x16x32_bf16 v[16:19], v[180:183], v[204:207], v[16:19]
	v_mfma_f32_16x16x32_bf16 v[4:7], v[164:167], v[212:215], v[4:7]
	v_mfma_f32_16x16x32_bf16 v[0:3], v[180:183], v[212:215], v[0:3]
	v_mfma_f32_16x16x32_bf16 v[52:55], v[176:179], v[192:195], v[52:55]
	v_mfma_f32_16x16x32_bf16 v[48:51], v[184:187], v[192:195], v[48:51]
	v_mfma_f32_16x16x32_bf16 v[36:39], v[176:179], v[200:203], v[36:39]
	v_mfma_f32_16x16x32_bf16 v[32:35], v[184:187], v[200:203], v[32:35]
	v_mfma_f32_16x16x32_bf16 v[20:23], v[176:179], v[208:211], v[20:23]
	v_mfma_f32_16x16x32_bf16 v[16:19], v[184:187], v[208:211], v[16:19]
	v_mfma_f32_16x16x32_bf16 v[4:7], v[176:179], v[216:219], v[4:7]
	s_barrier
	v_mfma_f32_16x16x32_bf16 v[0:3], v[184:187], v[216:219], v[0:3]
	s_setprio 0
	s_add_i32 s65, 0, 0x18000
	s_add_i32 s66, 0, 0x1c000
	v_add_u32_e32 v92, s65, v169
	v_add_u32_e32 v184, s66, v169
	ds_read_b128 v[80:83], v92
	ds_read_b128 v[84:87], v92 offset:1024
	ds_read_b128 v[88:91], v92 offset:2048
	ds_read_b128 v[92:95], v92 offset:3072
	ds_read_b128 v[164:167], v184
	ds_read_b128 v[176:179], v184 offset:1024
	ds_read_b128 v[180:183], v184 offset:2048
	ds_read_b128 v[184:187], v184 offset:3072
	s_add_u32 s46, s46, 0x80000
	s_addc_u32 s47, s47, 0
	s_mov_b32 m0, s49
	v_lshl_add_u64 v[228:229], s[46:47], 0, v[144:145]
	ds_read_b128 v[188:191], v173 offset:32768
	ds_read_b128 v[192:195], v173 offset:33792
	ds_read_b128 v[196:199], v173 offset:34816
	ds_read_b128 v[200:203], v173 offset:35840
	ds_read_b128 v[204:207], v173 offset:36864
	ds_read_b128 v[208:211], v173 offset:37888
	ds_read_b128 v[212:215], v173 offset:38912
	ds_read_b128 v[216:219], v173 offset:39936
	global_load_lds_dwordx4 v[228:229], off
	v_lshl_add_u64 v[228:229], s[46:47], 0, v[150:151]
	s_mov_b32 m0, s50
	s_nop 0
	global_load_lds_dwordx4 v[228:229], off
	s_waitcnt vmcnt(8)
	s_waitcnt lgkmcnt(0)
	s_barrier
	s_setprio 1
	v_mfma_f32_16x16x32_bf16 v[140:143], v[80:83], v[188:191], v[140:143]
	v_mfma_f32_16x16x32_bf16 v[136:139], v[88:91], v[188:191], v[136:139]
	v_mfma_f32_16x16x32_bf16 v[124:127], v[80:83], v[196:199], v[124:127]
	v_mfma_f32_16x16x32_bf16 v[120:123], v[88:91], v[196:199], v[120:123]
	v_mfma_f32_16x16x32_bf16 v[108:111], v[80:83], v[204:207], v[108:111]
	v_mfma_f32_16x16x32_bf16 v[104:107], v[88:91], v[204:207], v[104:107]
	v_mfma_f32_16x16x32_bf16 v[76:79], v[80:83], v[212:215], v[76:79]
	v_mfma_f32_16x16x32_bf16 v[72:75], v[88:91], v[212:215], v[72:75]
	v_mfma_f32_16x16x32_bf16 v[140:143], v[84:87], v[192:195], v[140:143]
	v_mfma_f32_16x16x32_bf16 v[136:139], v[92:95], v[192:195], v[136:139]
	v_mfma_f32_16x16x32_bf16 v[124:127], v[84:87], v[200:203], v[124:127]
	v_mfma_f32_16x16x32_bf16 v[120:123], v[92:95], v[200:203], v[120:123]
	v_mfma_f32_16x16x32_bf16 v[108:111], v[84:87], v[208:211], v[108:111]
	v_mfma_f32_16x16x32_bf16 v[104:107], v[92:95], v[208:211], v[104:107]
	v_mfma_f32_16x16x32_bf16 v[76:79], v[84:87], v[216:219], v[76:79]
	v_mfma_f32_16x16x32_bf16 v[72:75], v[92:95], v[216:219], v[72:75]
	s_setprio 0
	s_setprio 1
	v_mfma_f32_16x16x32_bf16 v[132:135], v[164:167], v[188:191], v[132:135]
	v_mfma_f32_16x16x32_bf16 v[128:131], v[180:183], v[188:191], v[128:131]
	v_mfma_f32_16x16x32_bf16 v[116:119], v[164:167], v[196:199], v[116:119]
	v_mfma_f32_16x16x32_bf16 v[112:115], v[180:183], v[196:199], v[112:115]
	v_mfma_f32_16x16x32_bf16 v[100:103], v[164:167], v[204:207], v[100:103]
	v_mfma_f32_16x16x32_bf16 v[96:99], v[180:183], v[204:207], v[96:99]
	v_mfma_f32_16x16x32_bf16 v[68:71], v[164:167], v[212:215], v[68:71]
	v_mfma_f32_16x16x32_bf16 v[64:67], v[180:183], v[212:215], v[64:67]
	v_mfma_f32_16x16x32_bf16 v[132:135], v[176:179], v[192:195], v[132:135]
	v_mfma_f32_16x16x32_bf16 v[128:131], v[184:187], v[192:195], v[128:131]
	v_mfma_f32_16x16x32_bf16 v[116:119], v[176:179], v[200:203], v[116:119]
	v_mfma_f32_16x16x32_bf16 v[112:115], v[184:187], v[200:203], v[112:115]
	v_mfma_f32_16x16x32_bf16 v[100:103], v[176:179], v[208:211], v[100:103]
	v_mfma_f32_16x16x32_bf16 v[96:99], v[184:187], v[208:211], v[96:99]
	v_mfma_f32_16x16x32_bf16 v[68:71], v[176:179], v[216:219], v[68:71]
	s_barrier
; #define PG8_STAGE(bufoff, gbase, voff) do { _Pragma("unroll") for (int _i = 0; _i < 2; ++_i) \
;         __builtin_amdgcn_global_load_lds((const unsigned*)((const char*)(gbase) + (voff)[_i]), (PG8_LAS unsigned*)(lds + (bufoff) + ldsw + _i * 8192), 16, 0, 0); } while (0)
; #define PG8_LDA(dst, b, h) do { _Pragma("unroll") for (int m = 0; m < 4; ++m) _Pragma("unroll") for (int k = 0; k < 2; ++k) dst[m][k] = *(const PG8_LAS bf16x8*)(lds + PG8_SA(b, h) + aoff + m * 2048 + k * 1024); } while (0)
; #define PG8_MMA(ai, bj, At, Bt) do { __builtin_amdgcn_s_setprio(1); _Pragma("unroll") for (int m = 0; m < 4; ++m) _Pragma("unroll") for (int n = 0; n < 2; ++n) _Pragma("unroll") for (int k = 0; k < 2; ++k) \
;         acc[ai][bj][m][n] = __builtin_amdgcn_mfma_f32_16x16x32_bf16(Bt[n][k], At[m][k], acc[ai][bj][m][n], 0, 0, 0); __builtin_amdgcn_s_setprio(0); } while (0)
; #define PG8_WAIT_V(n) asm volatile("s_waitcnt vmcnt(" #n ")" ::: "memory")
; #define PG8_WAIT_L(n) asm volatile("s_waitcnt lgkmcnt(" #n ")" ::: "memory")
; #define PG8_BAR __builtin_amdgcn_s_barrier()
; #define PG8_SCHED __builtin_amdgcn_sched_barrier(0)
; template <class Epi, class Sched, bool ALIGN_EPI = false, bool SP2 = false>
; __device__ __forceinline__ void gemm_phase(PG8_LAS unsigned char* lds, const Gemm g, const Sched& S, const Epi& E) {
;     ...
;             PG8_WAIT_V(8); PG8_WAIT_L(0); PG8_BAR; PG8_MMA(0, 0, At, B0); PG8_MMA(0, 1, At, B1); PG8_BAR; PG8_SCHED;
;             PG8_LDA(At, 1, 1); PG8_STAGE(PG8_SB(1, 0), b3, voffB); PG8_STAGE(PG8_SB(1, 1), b3 + hstep, voffB); PG8_STAGE(PG8_SA(1, 0), a3, voffA);
;             PG8_WAIT_V(8); PG8_WAIT_L(0); PG8_BAR; PG8_MMA(1, 0, At, B0); PG8_MMA(1, 1, At, B1); PG8_BAR; PG8_SCHED;
	v_mfma_f32_16x16x32_bf16 v[64:67], v[184:187], v[216:219], v[64:67]
	s_setprio 0
	s_add_i32 s46, s65, s33
	v_lshl_add_u64 v[220:221], v[220:221], 0, s[8:9]
	s_mov_b32 m0, s46
	ds_read_b128 v[188:191], v173 offset:49152
	ds_read_b128 v[192:195], v173 offset:50176
	ds_read_b128 v[196:199], v173 offset:51200
	ds_read_b128 v[200:203], v173 offset:52224
	ds_read_b128 v[204:207], v173 offset:53248
	ds_read_b128 v[208:211], v173 offset:54272
	ds_read_b128 v[212:215], v173 offset:55296
	ds_read_b128 v[216:219], v173 offset:56320
	global_load_lds_dwordx4 v[220:221], off
	s_add_i32 m0, s46, 0x2000
	s_add_u32 s44, s44, 0x80080
	v_lshl_add_u64 v[220:221], v[222:223], 0, s[8:9]
	s_addc_u32 s45, s45, 0
	s_add_i32 s46, s66, s33
	global_load_lds_dwordx4 v[220:221], off
	v_lshl_add_u64 v[220:221], s[44:45], 0, v[148:149]
	s_mov_b32 m0, s46
	s_nop 0
	global_load_lds_dwordx4 v[220:221], off
	v_lshl_add_u64 v[220:221], s[44:45], 0, v[152:153]
	s_add_i32 m0, s46, 0x2000
	s_nop 0
	global_load_lds_dwordx4 v[220:221], off
	v_lshl_add_u64 v[220:221], v[224:225], 0, s[8:9]
	s_mov_b32 m0, s52
	s_nop 0
	global_load_lds_dwordx4 v[220:221], off
	v_lshl_add_u64 v[220:221], v[226:227], 0, s[8:9]
	s_mov_b32 m0, s53
	s_nop 0
	global_load_lds_dwordx4 v[220:221], off
	s_waitcnt vmcnt(8)
	s_waitcnt lgkmcnt(0)
	s_barrier
	s_setprio 1
	v_mfma_f32_16x16x32_bf16 v[60:63], v[80:83], v[188:191], v[60:63]
	v_mfma_f32_16x16x32_bf16 v[56:59], v[88:91], v[188:191], v[56:59]
	v_mfma_f32_16x16x32_bf16 v[44:47], v[80:83], v[196:199], v[44:47]
	v_mfma_f32_16x16x32_bf16 v[40:43], v[88:91], v[196:199], v[40:43]
	v_mfma_f32_16x16x32_bf16 v[28:31], v[80:83], v[204:207], v[28:31]
	v_mfma_f32_16x16x32_bf16 v[24:27], v[88:91], v[204:207], v[24:27]
	v_mfma_f32_16x16x32_bf16 v[12:15], v[80:83], v[212:215], v[12:15]
	v_mfma_f32_16x16x32_bf16 v[8:11], v[88:91], v[212:215], v[8:11]
	v_mfma_f32_16x16x32_bf16 v[60:63], v[84:87], v[192:195], v[60:63]
	v_mfma_f32_16x16x32_bf16 v[56:59], v[92:95], v[192:195], v[56:59]
	v_mfma_f32_16x16x32_bf16 v[44:47], v[84:87], v[200:203], v[44:47]
	v_mfma_f32_16x16x32_bf16 v[40:43], v[92:95], v[200:203], v[40:43]
	v_mfma_f32_16x16x32_bf16 v[28:31], v[84:87], v[208:211], v[28:31]
	v_mfma_f32_16x16x32_bf16 v[24:27], v[92:95], v[208:211], v[24:27]
	v_mfma_f32_16x16x32_bf16 v[12:15], v[84:87], v[216:219], v[12:15]
	v_mfma_f32_16x16x32_bf16 v[8:11], v[92:95], v[216:219], v[8:11]
	s_setprio 0
	s_setprio 1
	v_mfma_f32_16x16x32_bf16 v[52:55], v[164:167], v[188:191], v[52:55]
	v_mfma_f32_16x16x32_bf16 v[48:51], v[180:183], v[188:191], v[48:51]
	v_mfma_f32_16x16x32_bf16 v[36:39], v[164:167], v[196:199], v[36:39]
	v_mfma_f32_16x16x32_bf16 v[32:35], v[180:183], v[196:199], v[32:35]
	v_mfma_f32_16x16x32_bf16 v[20:23], v[164:167], v[204:207], v[20:23]
	v_mfma_f32_16x16x32_bf16 v[16:19], v[180:183], v[204:207], v[16:19]
	v_mfma_f32_16x16x32_bf16 v[4:7], v[164:167], v[212:215], v[4:7]
	v_mfma_f32_16x16x32_bf16 v[0:3], v[180:183], v[212:215], v[0:3]
	v_mfma_f32_16x16x32_bf16 v[52:55], v[176:179], v[192:195], v[52:55]
	v_mfma_f32_16x16x32_bf16 v[48:51], v[184:187], v[192:195], v[48:51]
	v_mfma_f32_16x16x32_bf16 v[36:39], v[176:179], v[200:203], v[36:39]
	v_mfma_f32_16x16x32_bf16 v[32:35], v[184:187], v[200:203], v[32:35]
	v_mfma_f32_16x16x32_bf16 v[20:23], v[176:179], v[208:211], v[20:23]
	v_mfma_f32_16x16x32_bf16 v[16:19], v[184:187], v[208:211], v[16:19]
	v_mfma_f32_16x16x32_bf16 v[4:7], v[176:179], v[216:219], v[4:7]
	s_barrier
	v_mfma_f32_16x16x32_bf16 v[0:3], v[184:187], v[216:219], v[0:3]
	s_setprio 0
	s_add_i32 s64, s64, 2
	s_add_u32 s42, s42, 0x100
	s_addc_u32 s43, s43, 0
	s_add_u32 s62, s62, 0x100
	s_addc_u32 s63, s63, 0
	s_cmp_gt_u32 s64, 29
	s_cbranch_scc0 .LBB0_1142
	s_and_b64 vcc, exec, s[10:11]
	s_cbranch_vccz .LBB0_1145
	s_barrier

; #define PG8_STAGE(bufoff, gbase, voff) do { _Pragma("unroll") for (int _i = 0; _i < 2; ++_i) \
;         __builtin_amdgcn_global_load_lds((const unsigned*)((const char*)(gbase) + (voff)[_i]), (PG8_LAS unsigned*)(lds + (bufoff) + ldsw + _i * 8192), 16, 0, 0); } while (0)
; #define PG8_LDA(dst, b, h) do { _Pragma("unroll") for (int m = 0; m < 4; ++m) _Pragma("unroll") for (int k = 0; k < 2; ++k) dst[m][k] = *(const PG8_LAS bf16x8*)(lds + PG8_SA(b, h) + aoff + m * 2048 + k * 1024); } while (0)
; #define PG8_LDB(dst, b, h) do { _Pragma("unroll") for (int n = 0; n < 2; ++n) _Pragma("unroll") for (int k = 0; k < 2; ++k) dst[n][k] = *(const PG8_LAS bf16x8*)(lds + PG8_SB(b, h) + boff + n * 2048 + k * 1024); } while (0)
; #define PG8_MMA(ai, bj, At, Bt) do { __builtin_amdgcn_s_setprio(1); _Pragma("unroll") for (int m = 0; m < 4; ++m) _Pragma("unroll") for (int n = 0; n < 2; ++n) _Pragma("unroll") for (int k = 0; k < 2; ++k) \
;         acc[ai][bj][m][n] = __builtin_amdgcn_mfma_f32_16x16x32_bf16(Bt[n][k], At[m][k], acc[ai][bj][m][n], 0, 0, 0); __builtin_amdgcn_s_setprio(0); } while (0)
; #define PG8_WAIT_V(n) asm volatile("s_waitcnt vmcnt(" #n ")" ::: "memory")
; #define PG8_WAIT_L(n) asm volatile("s_waitcnt lgkmcnt(" #n ")" ::: "memory")
; #define PG8_BAR __builtin_amdgcn_s_barrier()
; template <class Epi, class Sched, bool ALIGN_EPI = false, bool SP2 = false>
; __device__ __forceinline__ void gemm_phase(PG8_LAS unsigned char* lds, const Gemm g, const Sched& S, const Epi& E) {
;     ...
;         for (int t = 0; t < nt; t += 2) {
;             const bool last = (t == nt - 2);
;             const char* a1 = cA + (size_t)(t + 1) * kstep;
;             const char* a2 = last ? nA : cA + (size_t)(t + 2) * kstep; const char* b2 = last ? nB : cB + (size_t)(t + 2) * kstep;
;             const char* a3 = a2 + kstep; const char* b3 = b2 + kstep;
;             if constexpr (SP2) {
;             PG8_LDB(B0, 0, 0); PG8_LDB(B1, 0, 1); PG8_SCHED; PG8_LDA(At, 0, 0); PG8_STAGE(PG8_SA(1, 1), a1 + hstep, voffA);
;             PG8_WAIT_V(8); PG8_WAIT_L(0); PG8_BAR; PG8_MMA(0, 0, At, B0); PG8_MMA(0, 1, At, B1); PG8_BAR; PG8_SCHED;
;             PG8_LDA(At, 0, 1); PG8_STAGE(PG8_SB(0, 0), b2, voffB); PG8_STAGE(PG8_SB(0, 1), b2 + hstep, voffB); PG8_STAGE(PG8_SA(0, 0), a2, voffA);
;             PG8_WAIT_V(8); PG8_WAIT_L(0); PG8_BAR; PG8_MMA(1, 0, At, B0); PG8_MMA(1, 1, At, B1); PG8_BAR; PG8_SCHED;
.LBB0_1219:
	ds_read_b128 v[128:131], v167
	ds_read_b128 v[132:135], v167 offset:1024
	ds_read_b128 v[154:157], v167 offset:2048
	ds_read_b128 v[158:161], v167 offset:3072
	ds_read_b128 v[170:173], v168
	ds_read_b128 v[174:177], v168 offset:1024
	ds_read_b128 v[178:181], v168 offset:2048
	ds_read_b128 v[182:185], v168 offset:3072
	s_add_u32 s42, s40, 0xffe00080
	s_addc_u32 s43, s41, -1
	s_cmpk_eq_i32 s63, 0x7c
	s_cselect_b32 s45, s15, s43
	s_cselect_b32 s44, s59, s42
	s_cselect_b32 s43, s13, s62
	s_cselect_b32 s42, s60, s61
	v_lshl_add_u64 v[162:163], s[40:41], 0, v[144:145]
	s_add_i32 m0, s39, 0xc000
	ds_read_b128 v[186:189], v169
	ds_read_b128 v[190:193], v169 offset:1024
	ds_read_b128 v[194:197], v169 offset:2048
	ds_read_b128 v[198:201], v169 offset:3072
	ds_read_b128 v[202:205], v169 offset:4096
	ds_read_b128 v[206:209], v169 offset:5120
	ds_read_b128 v[210:213], v169 offset:6144
	ds_read_b128 v[214:217], v169 offset:7168
	global_load_lds_dwordx4 v[162:163], off
	v_lshl_add_u64 v[162:163], s[40:41], 0, v[148:149]
	s_add_i32 m0, s39, 0xe000
	s_nop 0
	global_load_lds_dwordx4 v[162:163], off
	s_waitcnt vmcnt(8)
	s_waitcnt lgkmcnt(0)
	s_barrier
	s_setprio 1
	v_mfma_f32_16x16x32_bf16 v[124:127], v[128:131], v[186:189], v[124:127]
	v_mfma_f32_16x16x32_bf16 v[120:123], v[154:157], v[186:189], v[120:123]
	v_mfma_f32_16x16x32_bf16 v[116:119], v[128:131], v[194:197], v[116:119]
	v_mfma_f32_16x16x32_bf16 v[112:115], v[154:157], v[194:197], v[112:115]
	v_mfma_f32_16x16x32_bf16 v[108:111], v[128:131], v[202:205], v[108:111]
	v_mfma_f32_16x16x32_bf16 v[104:107], v[154:157], v[202:205], v[104:107]
	v_mfma_f32_16x16x32_bf16 v[100:103], v[128:131], v[210:213], v[100:103]
	v_mfma_f32_16x16x32_bf16 v[96:99], v[154:157], v[210:213], v[96:99]
	v_mfma_f32_16x16x32_bf16 v[124:127], v[132:135], v[190:193], v[124:127]
	v_mfma_f32_16x16x32_bf16 v[120:123], v[158:161], v[190:193], v[120:123]
	v_mfma_f32_16x16x32_bf16 v[116:119], v[132:135], v[198:201], v[116:119]
	v_mfma_f32_16x16x32_bf16 v[112:115], v[158:161], v[198:201], v[112:115]
	v_mfma_f32_16x16x32_bf16 v[108:111], v[132:135], v[206:209], v[108:111]
	v_mfma_f32_16x16x32_bf16 v[104:107], v[158:161], v[206:209], v[104:107]
	v_mfma_f32_16x16x32_bf16 v[100:103], v[132:135], v[214:217], v[100:103]
	v_mfma_f32_16x16x32_bf16 v[96:99], v[158:161], v[214:217], v[96:99]
	s_setprio 0
	s_setprio 1
	v_mfma_f32_16x16x32_bf16 v[68:71], v[170:173], v[186:189], v[68:71]
	v_mfma_f32_16x16x32_bf16 v[60:63], v[178:181], v[186:189], v[60:63]
	v_mfma_f32_16x16x32_bf16 v[52:55], v[170:173], v[194:197], v[52:55]
	v_mfma_f32_16x16x32_bf16 v[48:51], v[178:181], v[194:197], v[48:51]
	v_mfma_f32_16x16x32_bf16 v[44:47], v[170:173], v[202:205], v[44:47]
	v_mfma_f32_16x16x32_bf16 v[40:43], v[178:181], v[202:205], v[40:43]
	v_mfma_f32_16x16x32_bf16 v[36:39], v[170:173], v[210:213], v[36:39]
	v_mfma_f32_16x16x32_bf16 v[32:35], v[178:181], v[210:213], v[32:35]
	v_mfma_f32_16x16x32_bf16 v[68:71], v[174:177], v[190:193], v[68:71]
	v_mfma_f32_16x16x32_bf16 v[60:63], v[182:185], v[190:193], v[60:63]
	v_mfma_f32_16x16x32_bf16 v[52:55], v[174:177], v[198:201], v[52:55]
	v_mfma_f32_16x16x32_bf16 v[48:51], v[182:185], v[198:201], v[48:51]
	v_mfma_f32_16x16x32_bf16 v[44:47], v[174:177], v[206:209], v[44:47]
	v_mfma_f32_16x16x32_bf16 v[40:43], v[182:185], v[206:209], v[40:43]
	v_mfma_f32_16x16x32_bf16 v[36:39], v[174:177], v[214:217], v[36:39]
	s_barrier
	v_mfma_f32_16x16x32_bf16 v[32:35], v[182:185], v[214:217], v[32:35]
	s_setprio 0
	s_add_i32 s64, s56, s33
	v_lshl_add_u64 v[162:163], s[42:43], 0, v[138:139]
	s_mov_b32 m0, s64
	ds_read_b128 v[186:189], v169 offset:16384
	ds_read_b128 v[190:193], v169 offset:17408
	ds_read_b128 v[194:197], v169 offset:18432
	ds_read_b128 v[198:201], v169 offset:19456
	ds_read_b128 v[202:205], v169 offset:20480
	ds_read_b128 v[206:209], v169 offset:21504
	ds_read_b128 v[210:213], v169 offset:22528
	ds_read_b128 v[214:217], v169 offset:23552
	global_load_lds_dwordx4 v[162:163], off
	s_add_i32 m0, s64, 0x2000
	s_add_u32 s64, s42, 0x200000
	v_lshl_add_u64 v[218:219], s[42:43], 0, v[142:143]
	s_addc_u32 s65, s43, 0
	s_add_i32 s66, s57, s33
	global_load_lds_dwordx4 v[218:219], off
	v_lshl_add_u64 v[220:221], s[64:65], 0, v[138:139]
	s_mov_b32 m0, s66
	v_lshl_add_u64 v[222:223], s[44:45], 0, v[140:141]
	global_load_lds_dwordx4 v[220:221], off
	v_lshl_add_u64 v[220:221], s[64:65], 0, v[142:143]
	s_add_i32 m0, s66, 0x2000
	s_nop 0
	global_load_lds_dwordx4 v[220:221], off
	v_lshl_add_u64 v[220:221], s[44:45], 0, v[136:137]
	s_mov_b32 m0, s39
	s_nop 0
	global_load_lds_dwordx4 v[220:221], off
	s_mov_b32 m0, s46
	s_nop 0
	global_load_lds_dwordx4 v[222:223], off
	s_waitcnt vmcnt(8)
	s_waitcnt lgkmcnt(0)
	s_barrier
; #define PG8_STAGE(bufoff, gbase, voff) do { _Pragma("unroll") for (int _i = 0; _i < 2; ++_i) \
;         __builtin_amdgcn_global_load_lds((const unsigned*)((const char*)(gbase) + (voff)[_i]), (PG8_LAS unsigned*)(lds + (bufoff) + ldsw + _i * 8192), 16, 0, 0); } while (0)
; #define PG8_LDA(dst, b, h) do { _Pragma("unroll") for (int m = 0; m < 4; ++m) _Pragma("unroll") for (int k = 0; k < 2; ++k) dst[m][k] = *(const PG8_LAS bf16x8*)(lds + PG8_SA(b, h) + aoff + m * 2048 + k * 1024); } while (0)
; #define PG8_LDB(dst, b, h) do { _Pragma("unroll") for (int n = 0; n < 2; ++n) _Pragma("unroll") for (int k = 0; k < 2; ++k) dst[n][k] = *(const PG8_LAS bf16x8*)(lds + PG8_SB(b, h) + boff + n * 2048 + k * 1024); } while (0)
; #define PG8_MMA(ai, bj, At, Bt) do { __builtin_amdgcn_s_setprio(1); _Pragma("unroll") for (int m = 0; m < 4; ++m) _Pragma("unroll") for (int n = 0; n < 2; ++n) _Pragma("unroll") for (int k = 0; k < 2; ++k) \
;         acc[ai][bj][m][n] = __builtin_amdgcn_mfma_f32_16x16x32_bf16(Bt[n][k], At[m][k], acc[ai][bj][m][n], 0, 0, 0); __builtin_amdgcn_s_setprio(0); } while (0)
; #define PG8_WAIT_V(n) asm volatile("s_waitcnt vmcnt(" #n ")" ::: "memory")
; #define PG8_WAIT_L(n) asm volatile("s_waitcnt lgkmcnt(" #n ")" ::: "memory")
; #define PG8_BAR __builtin_amdgcn_s_barrier()
; #define PG8_SCHED __builtin_amdgcn_sched_barrier(0)
; template <class Epi, class Sched, bool ALIGN_EPI = false, bool SP2 = false>
; __device__ __forceinline__ void gemm_phase(PG8_LAS unsigned char* lds, const Gemm g, const Sched& S, const Epi& E) {
;     ...
;             PG8_WAIT_V(8); PG8_WAIT_L(0); PG8_BAR; PG8_MMA(1, 0, At, B0); PG8_MMA(1, 1, At, B1); PG8_BAR; PG8_SCHED;
;             PG8_LDB(B0, 1, 0); PG8_LDB(B1, 1, 1); PG8_SCHED; PG8_LDA(At, 1, 0); PG8_STAGE(PG8_SA(0, 1), a2 + hstep, voffA);
;             PG8_WAIT_V(8); PG8_WAIT_L(0); PG8_BAR; PG8_MMA(0, 0, At, B0); PG8_MMA(0, 1, At, B1); PG8_BAR; PG8_SCHED;
	s_setprio 1
	v_mfma_f32_16x16x32_bf16 v[92:95], v[128:131], v[186:189], v[92:95]
	v_mfma_f32_16x16x32_bf16 v[88:91], v[154:157], v[186:189], v[88:91]
	v_mfma_f32_16x16x32_bf16 v[84:87], v[128:131], v[194:197], v[84:87]
	v_mfma_f32_16x16x32_bf16 v[80:83], v[154:157], v[194:197], v[80:83]
	v_mfma_f32_16x16x32_bf16 v[76:79], v[128:131], v[202:205], v[76:79]
	v_mfma_f32_16x16x32_bf16 v[72:75], v[154:157], v[202:205], v[72:75]
	v_mfma_f32_16x16x32_bf16 v[64:67], v[128:131], v[210:213], v[64:67]
	v_mfma_f32_16x16x32_bf16 v[56:59], v[154:157], v[210:213], v[56:59]
	v_mfma_f32_16x16x32_bf16 v[92:95], v[132:135], v[190:193], v[92:95]
	v_mfma_f32_16x16x32_bf16 v[88:91], v[158:161], v[190:193], v[88:91]
	v_mfma_f32_16x16x32_bf16 v[84:87], v[132:135], v[198:201], v[84:87]
	v_mfma_f32_16x16x32_bf16 v[80:83], v[158:161], v[198:201], v[80:83]
	v_mfma_f32_16x16x32_bf16 v[76:79], v[132:135], v[206:209], v[76:79]
	v_mfma_f32_16x16x32_bf16 v[72:75], v[158:161], v[206:209], v[72:75]
	v_mfma_f32_16x16x32_bf16 v[64:67], v[132:135], v[214:217], v[64:67]
	v_mfma_f32_16x16x32_bf16 v[56:59], v[158:161], v[214:217], v[56:59]
	s_setprio 0
	s_setprio 1
	v_mfma_f32_16x16x32_bf16 v[28:31], v[170:173], v[186:189], v[28:31]
	v_mfma_f32_16x16x32_bf16 v[24:27], v[178:181], v[186:189], v[24:27]
	v_mfma_f32_16x16x32_bf16 v[20:23], v[170:173], v[194:197], v[20:23]
	v_mfma_f32_16x16x32_bf16 v[16:19], v[178:181], v[194:197], v[16:19]
	v_mfma_f32_16x16x32_bf16 v[12:15], v[170:173], v[202:205], v[12:15]
	v_mfma_f32_16x16x32_bf16 v[8:11], v[178:181], v[202:205], v[8:11]
	v_mfma_f32_16x16x32_bf16 v[4:7], v[170:173], v[210:213], v[4:7]
	v_mfma_f32_16x16x32_bf16 v[0:3], v[178:181], v[210:213], v[0:3]
	v_mfma_f32_16x16x32_bf16 v[28:31], v[174:177], v[190:193], v[28:31]
	v_mfma_f32_16x16x32_bf16 v[24:27], v[182:185], v[190:193], v[24:27]
	v_mfma_f32_16x16x32_bf16 v[20:23], v[174:177], v[198:201], v[20:23]
	v_mfma_f32_16x16x32_bf16 v[16:19], v[182:185], v[198:201], v[16:19]
	v_mfma_f32_16x16x32_bf16 v[12:15], v[174:177], v[206:209], v[12:15]
	v_mfma_f32_16x16x32_bf16 v[8:11], v[182:185], v[206:209], v[8:11]
	v_mfma_f32_16x16x32_bf16 v[4:7], v[174:177], v[214:217], v[4:7]
	s_barrier
	v_mfma_f32_16x16x32_bf16 v[0:3], v[182:185], v[214:217], v[0:3]
	s_setprio 0
	s_add_i32 s64, 0, 0x18000
	s_add_i32 s65, 0, 0x1c000
	v_add_u32_e32 v158, s64, v165
	v_add_u32_e32 v182, s65, v165
	ds_read_b128 v[128:131], v158
	ds_read_b128 v[132:135], v158 offset:1024
	ds_read_b128 v[154:157], v158 offset:2048
	ds_read_b128 v[158:161], v158 offset:3072
	ds_read_b128 v[170:173], v182
	ds_read_b128 v[174:177], v182 offset:1024
	ds_read_b128 v[178:181], v182 offset:2048
	ds_read_b128 v[182:185], v182 offset:3072
	s_add_u32 s44, s44, 0x200000
	s_addc_u32 s45, s45, 0
	s_mov_b32 m0, s47
	v_lshl_add_u64 v[224:225], s[44:45], 0, v[136:137]
	ds_read_b128 v[186:189], v169 offset:32768
	ds_read_b128 v[190:193], v169 offset:33792
	ds_read_b128 v[194:197], v169 offset:34816
	ds_read_b128 v[198:201], v169 offset:35840
	ds_read_b128 v[202:205], v169 offset:36864
	ds_read_b128 v[206:209], v169 offset:37888
	ds_read_b128 v[210:213], v169 offset:38912
	ds_read_b128 v[214:217], v169 offset:39936
	global_load_lds_dwordx4 v[224:225], off
	v_lshl_add_u64 v[224:225], s[44:45], 0, v[140:141]
	s_mov_b32 m0, s48
	s_nop 0
	global_load_lds_dwordx4 v[224:225], off
	s_waitcnt vmcnt(8)
	s_waitcnt lgkmcnt(0)
	s_barrier
	s_setprio 1
	v_mfma_f32_16x16x32_bf16 v[124:127], v[128:131], v[186:189], v[124:127]
	v_mfma_f32_16x16x32_bf16 v[120:123], v[154:157], v[186:189], v[120:123]
	v_mfma_f32_16x16x32_bf16 v[116:119], v[128:131], v[194:197], v[116:119]
	v_mfma_f32_16x16x32_bf16 v[112:115], v[154:157], v[194:197], v[112:115]
	v_mfma_f32_16x16x32_bf16 v[108:111], v[128:131], v[202:205], v[108:111]
	v_mfma_f32_16x16x32_bf16 v[104:107], v[154:157], v[202:205], v[104:107]
	v_mfma_f32_16x16x32_bf16 v[100:103], v[128:131], v[210:213], v[100:103]
	v_mfma_f32_16x16x32_bf16 v[96:99], v[154:157], v[210:213], v[96:99]
	v_mfma_f32_16x16x32_bf16 v[124:127], v[132:135], v[190:193], v[124:127]
	v_mfma_f32_16x16x32_bf16 v[120:123], v[158:161], v[190:193], v[120:123]
	v_mfma_f32_16x16x32_bf16 v[116:119], v[132:135], v[198:201], v[116:119]
	v_mfma_f32_16x16x32_bf16 v[112:115], v[158:161], v[198:201], v[112:115]
	v_mfma_f32_16x16x32_bf16 v[108:111], v[132:135], v[206:209], v[108:111]
	v_mfma_f32_16x16x32_bf16 v[104:107], v[158:161], v[206:209], v[104:107]
	v_mfma_f32_16x16x32_bf16 v[100:103], v[132:135], v[214:217], v[100:103]
	v_mfma_f32_16x16x32_bf16 v[96:99], v[158:161], v[214:217], v[96:99]
	s_setprio 0
	s_setprio 1
	v_mfma_f32_16x16x32_bf16 v[68:71], v[170:173], v[186:189], v[68:71]
	v_mfma_f32_16x16x32_bf16 v[60:63], v[178:181], v[186:189], v[60:63]
	v_mfma_f32_16x16x32_bf16 v[52:55], v[170:173], v[194:197], v[52:55]
	v_mfma_f32_16x16x32_bf16 v[48:51], v[178:181], v[194:197], v[48:51]
	v_mfma_f32_16x16x32_bf16 v[44:47], v[170:173], v[202:205], v[44:47]
	v_mfma_f32_16x16x32_bf16 v[40:43], v[178:181], v[202:205], v[40:43]
	v_mfma_f32_16x16x32_bf16 v[36:39], v[170:173], v[210:213], v[36:39]
	v_mfma_f32_16x16x32_bf16 v[32:35], v[178:181], v[210:213], v[32:35]
	v_mfma_f32_16x16x32_bf16 v[68:71], v[174:177], v[190:193], v[68:71]
	v_mfma_f32_16x16x32_bf16 v[60:63], v[182:185], v[190:193], v[60:63]
	v_mfma_f32_16x16x32_bf16 v[52:55], v[174:177], v[198:201], v[52:55]
	v_mfma_f32_16x16x32_bf16 v[48:51], v[182:185], v[198:201], v[48:51]
	v_mfma_f32_16x16x32_bf16 v[44:47], v[174:177], v[206:209], v[44:47]
	v_mfma_f32_16x16x32_bf16 v[40:43], v[182:185], v[206:209], v[40:43]
	v_mfma_f32_16x16x32_bf16 v[36:39], v[174:177], v[214:217], v[36:39]
	s_barrier
; #define PG8_STAGE(bufoff, gbase, voff) do { _Pragma("unroll") for (int _i = 0; _i < 2; ++_i) \
;         __builtin_amdgcn_global_load_lds((const unsigned*)((const char*)(gbase) + (voff)[_i]), (PG8_LAS unsigned*)(lds + (bufoff) + ldsw + _i * 8192), 16, 0, 0); } while (0)
; #define PG8_LDA(dst, b, h) do { _Pragma("unroll") for (int m = 0; m < 4; ++m) _Pragma("unroll") for (int k = 0; k < 2; ++k) dst[m][k] = *(const PG8_LAS bf16x8*)(lds + PG8_SA(b, h) + aoff + m * 2048 + k * 1024); } while (0)
; #define PG8_MMA(ai, bj, At, Bt) do { __builtin_amdgcn_s_setprio(1); _Pragma("unroll") for (int m = 0; m < 4; ++m) _Pragma("unroll") for (int n = 0; n < 2; ++n) _Pragma("unroll") for (int k = 0; k < 2; ++k) \
;         acc[ai][bj][m][n] = __builtin_amdgcn_mfma_f32_16x16x32_bf16(Bt[n][k], At[m][k], acc[ai][bj][m][n], 0, 0, 0); __builtin_amdgcn_s_setprio(0); } while (0)
; #define PG8_WAIT_V(n) asm volatile("s_waitcnt vmcnt(" #n ")" ::: "memory")
; #define PG8_WAIT_L(n) asm volatile("s_waitcnt lgkmcnt(" #n ")" ::: "memory")
; #define PG8_BAR __builtin_amdgcn_s_barrier()
; #define PG8_SCHED __builtin_amdgcn_sched_barrier(0)
; template <class Epi, class Sched, bool ALIGN_EPI = false, bool SP2 = false>
; __device__ __forceinline__ void gemm_phase(PG8_LAS unsigned char* lds, const Gemm g, const Sched& S, const Epi& E) {
;     ...
;             PG8_WAIT_V(8); PG8_WAIT_L(0); PG8_BAR; PG8_MMA(0, 0, At, B0); PG8_MMA(0, 1, At, B1); PG8_BAR; PG8_SCHED;
;             PG8_LDA(At, 1, 1); PG8_STAGE(PG8_SB(1, 0), b3, voffB); PG8_STAGE(PG8_SB(1, 1), b3 + hstep, voffB); PG8_STAGE(PG8_SA(1, 0), a3, voffA);
;             PG8_WAIT_V(8); PG8_WAIT_L(0); PG8_BAR; PG8_MMA(1, 0, At, B0); PG8_MMA(1, 1, At, B1); PG8_BAR; PG8_SCHED;
	v_mfma_f32_16x16x32_bf16 v[32:35], v[182:185], v[214:217], v[32:35]
	s_setprio 0
	s_add_i32 s44, s64, s33
	v_lshl_add_u64 v[162:163], v[162:163], 0, s[8:9]
	s_mov_b32 m0, s44
	ds_read_b128 v[186:189], v169 offset:49152
	ds_read_b128 v[190:193], v169 offset:50176
	ds_read_b128 v[194:197], v169 offset:51200
	ds_read_b128 v[198:201], v169 offset:52224
	ds_read_b128 v[202:205], v169 offset:53248
	ds_read_b128 v[206:209], v169 offset:54272
	ds_read_b128 v[210:213], v169 offset:55296
	ds_read_b128 v[214:217], v169 offset:56320
	global_load_lds_dwordx4 v[162:163], off
	s_add_i32 m0, s44, 0x2000
	s_add_u32 s42, s42, 0x200080
	v_lshl_add_u64 v[162:163], v[218:219], 0, s[8:9]
	s_addc_u32 s43, s43, 0
	s_add_i32 s44, s65, s33
	global_load_lds_dwordx4 v[162:163], off
	v_lshl_add_u64 v[162:163], s[42:43], 0, v[138:139]
	s_mov_b32 m0, s44
	s_nop 0
	global_load_lds_dwordx4 v[162:163], off
	v_lshl_add_u64 v[162:163], s[42:43], 0, v[142:143]
	s_add_i32 m0, s44, 0x2000
	s_nop 0
	global_load_lds_dwordx4 v[162:163], off
	v_lshl_add_u64 v[162:163], v[220:221], 0, s[8:9]
	s_mov_b32 m0, s52
	s_nop 0
	global_load_lds_dwordx4 v[162:163], off
	v_lshl_add_u64 v[162:163], v[222:223], 0, s[8:9]
	s_mov_b32 m0, s53
	s_nop 0
	global_load_lds_dwordx4 v[162:163], off
	s_waitcnt vmcnt(8)
	s_waitcnt lgkmcnt(0)
	s_barrier
	s_setprio 1
	v_mfma_f32_16x16x32_bf16 v[92:95], v[128:131], v[186:189], v[92:95]
	v_mfma_f32_16x16x32_bf16 v[88:91], v[154:157], v[186:189], v[88:91]
	v_mfma_f32_16x16x32_bf16 v[84:87], v[128:131], v[194:197], v[84:87]
	v_mfma_f32_16x16x32_bf16 v[80:83], v[154:157], v[194:197], v[80:83]
	v_mfma_f32_16x16x32_bf16 v[76:79], v[128:131], v[202:205], v[76:79]
	v_mfma_f32_16x16x32_bf16 v[72:75], v[154:157], v[202:205], v[72:75]
	v_mfma_f32_16x16x32_bf16 v[64:67], v[128:131], v[210:213], v[64:67]
	v_mfma_f32_16x16x32_bf16 v[56:59], v[154:157], v[210:213], v[56:59]
	v_mfma_f32_16x16x32_bf16 v[92:95], v[132:135], v[190:193], v[92:95]
	v_mfma_f32_16x16x32_bf16 v[88:91], v[158:161], v[190:193], v[88:91]
	v_mfma_f32_16x16x32_bf16 v[84:87], v[132:135], v[198:201], v[84:87]
	v_mfma_f32_16x16x32_bf16 v[80:83], v[158:161], v[198:201], v[80:83]
	v_mfma_f32_16x16x32_bf16 v[76:79], v[132:135], v[206:209], v[76:79]
	v_mfma_f32_16x16x32_bf16 v[72:75], v[158:161], v[206:209], v[72:75]
	v_mfma_f32_16x16x32_bf16 v[64:67], v[132:135], v[214:217], v[64:67]
	v_mfma_f32_16x16x32_bf16 v[56:59], v[158:161], v[214:217], v[56:59]
	s_setprio 0
	s_setprio 1
	v_mfma_f32_16x16x32_bf16 v[28:31], v[170:173], v[186:189], v[28:31]
	v_mfma_f32_16x16x32_bf16 v[24:27], v[178:181], v[186:189], v[24:27]
	v_mfma_f32_16x16x32_bf16 v[20:23], v[170:173], v[194:197], v[20:23]
	v_mfma_f32_16x16x32_bf16 v[16:19], v[178:181], v[194:197], v[16:19]
	v_mfma_f32_16x16x32_bf16 v[12:15], v[170:173], v[202:205], v[12:15]
	v_mfma_f32_16x16x32_bf16 v[8:11], v[178:181], v[202:205], v[8:11]
	v_mfma_f32_16x16x32_bf16 v[4:7], v[170:173], v[210:213], v[4:7]
	v_mfma_f32_16x16x32_bf16 v[0:3], v[178:181], v[210:213], v[0:3]
	v_mfma_f32_16x16x32_bf16 v[28:31], v[174:177], v[190:193], v[28:31]
	v_mfma_f32_16x16x32_bf16 v[24:27], v[182:185], v[190:193], v[24:27]
	v_mfma_f32_16x16x32_bf16 v[20:23], v[174:177], v[198:201], v[20:23]
	v_mfma_f32_16x16x32_bf16 v[16:19], v[182:185], v[198:201], v[16:19]
	v_mfma_f32_16x16x32_bf16 v[12:15], v[174:177], v[206:209], v[12:15]
	v_mfma_f32_16x16x32_bf16 v[8:11], v[182:185], v[206:209], v[8:11]
	v_mfma_f32_16x16x32_bf16 v[4:7], v[174:177], v[214:217], v[4:7]
	s_barrier
	v_mfma_f32_16x16x32_bf16 v[0:3], v[182:185], v[214:217], v[0:3]
	s_setprio 0
	s_add_i32 s63, s63, 2
	s_add_u32 s40, s40, 0x100
	s_addc_u32 s41, s41, 0
	s_add_u32 s61, s61, 0x100
	s_addc_u32 s62, s62, 0
	s_cmpk_gt_u32 s63, 0x7d
	s_cbranch_scc0 .LBB0_1219
	s_and_b64 vcc, exec, s[10:11]
	s_cbranch_vccz .LBB0_1222
	s_barrier
